# phase-2/4 load segments: the eight A-fragment ds_reads issued first (ahead of setprio 0 and the DMA address setup)
# baseline (speedup 1.0000x reference)
.LBB0_141:
	s_lshl_b32 s34, s11, 8
	s_ashr_i32 s35, s34, 31
	s_lshl_b64 s[34:35], s[34:35], 11
	s_add_u32 s82, s49, s34
	s_addc_u32 s83, s53, s35
	s_and_b64 s[34:35], s[0:1], exec
	s_cselect_b32 s5, s83, s7
	s_cselect_b32 s22, s82, s6
	s_ashr_i32 s81, s80, 31
	s_lshl_b64 s[34:35], s[80:81], 19
	s_add_u32 s84, s55, s34
	s_addc_u32 s85, s57, s35
	s_and_b64 s[34:35], s[0:1], exec
	s_cselect_b32 s34, s85, s9
	s_cselect_b32 s35, s84, s8
	s_add_u32 s40, s8, 0x100
	s_addc_u32 s41, s9, 0
	s_mov_b32 s50, -2
	s_waitcnt vmcnt(0)
	s_waitcnt lgkmcnt(0)
	ds_read_b128 v[128:131], v175
	ds_read_b128 v[132:135], v175 offset:1024
	ds_read_b128 v[136:139], v175 offset:2048
	ds_read_b128 v[140:143], v175 offset:3072
	ds_read_b128 v[166:169], v176
	ds_read_b128 v[170:173], v176 offset:1024
	ds_read_b128 v[182:185], v176 offset:2048
	ds_read_b128 v[186:189], v176 offset:3072
	s_add_u32 s8, s6, 0x100
	s_addc_u32 s9, s7, 0
	s_cmp_eq_u32 s50, 12
	s_cselect_b32 s89, s5, s9
	s_cselect_b32 s88, s22, s8
	s_cselect_b32 s87, s34, s41
	s_cselect_b32 s86, s35, s40
	v_lshl_add_u64 v[220:221], s[6:7], 0, v[158:159]
	s_add_i32 m0, s61, 0xc000
	ds_read_b128 v[190:193], v177
	ds_read_b128 v[194:197], v177 offset:1024
	ds_read_b128 v[198:201], v177 offset:2048
	ds_read_b128 v[202:205], v177 offset:3072
	ds_read_b128 v[206:209], v177 offset:4096
	ds_read_b128 v[210:213], v177 offset:5120
	ds_read_b128 v[214:217], v177 offset:6144
	ds_read_b128 v[224:227], v177 offset:7168
	global_load_lds_dwordx4 v[220:221], off
	s_add_i32 m0, s61, 0xe000
	v_lshl_add_u64 v[220:221], s[6:7], 0, v[160:161]
	global_load_lds_dwordx4 v[220:221], off
	s_setprio 1
	s_waitcnt vmcnt(8) lgkmcnt(0)
	s_barrier
	v_mfma_f32_16x16x32_bf16 v[124:127], v[128:131], v[190:193], 0
	v_mfma_f32_16x16x32_bf16 v[120:123], v[136:139], v[190:193], 0
	v_mfma_f32_16x16x32_bf16 v[108:111], v[128:131], v[198:201], 0
	v_mfma_f32_16x16x32_bf16 v[104:107], v[136:139], v[198:201], 0
	v_mfma_f32_16x16x32_bf16 v[92:95], v[128:131], v[206:209], 0
	v_mfma_f32_16x16x32_bf16 v[88:91], v[136:139], v[206:209], 0
	v_mfma_f32_16x16x32_bf16 v[76:79], v[128:131], v[214:217], 0
	v_mfma_f32_16x16x32_bf16 v[72:75], v[136:139], v[214:217], 0
	v_mfma_f32_16x16x32_bf16 v[124:127], v[132:135], v[194:197], v[124:127]
	v_mfma_f32_16x16x32_bf16 v[120:123], v[140:143], v[194:197], v[120:123]
	v_mfma_f32_16x16x32_bf16 v[108:111], v[132:135], v[202:205], v[108:111]
	v_mfma_f32_16x16x32_bf16 v[104:107], v[140:143], v[202:205], v[104:107]
	v_mfma_f32_16x16x32_bf16 v[92:95], v[132:135], v[210:213], v[92:95]
	v_mfma_f32_16x16x32_bf16 v[88:91], v[140:143], v[210:213], v[88:91]
	v_mfma_f32_16x16x32_bf16 v[76:79], v[132:135], v[224:227], v[76:79]
	v_mfma_f32_16x16x32_bf16 v[72:75], v[140:143], v[224:227], v[72:75]
	v_mfma_f32_16x16x32_bf16 v[116:119], v[166:169], v[190:193], 0
	v_mfma_f32_16x16x32_bf16 v[112:115], v[182:185], v[190:193], 0
	v_mfma_f32_16x16x32_bf16 v[100:103], v[166:169], v[198:201], 0
	v_mfma_f32_16x16x32_bf16 v[96:99], v[182:185], v[198:201], 0
	v_mfma_f32_16x16x32_bf16 v[84:87], v[166:169], v[206:209], 0
	v_mfma_f32_16x16x32_bf16 v[80:83], v[182:185], v[206:209], 0
	v_mfma_f32_16x16x32_bf16 v[68:71], v[166:169], v[214:217], 0
	v_mfma_f32_16x16x32_bf16 v[64:67], v[182:185], v[214:217], 0
	v_mfma_f32_16x16x32_bf16 v[116:119], v[170:173], v[194:197], v[116:119]
	v_mfma_f32_16x16x32_bf16 v[112:115], v[186:189], v[194:197], v[112:115]
	v_mfma_f32_16x16x32_bf16 v[100:103], v[170:173], v[202:205], v[100:103]
	v_mfma_f32_16x16x32_bf16 v[96:99], v[186:189], v[202:205], v[96:99]
	v_mfma_f32_16x16x32_bf16 v[84:87], v[170:173], v[210:213], v[84:87]
	v_mfma_f32_16x16x32_bf16 v[80:83], v[186:189], v[210:213], v[80:83]
	v_mfma_f32_16x16x32_bf16 v[68:71], v[170:173], v[224:227], v[68:71]
	v_mfma_f32_16x16x32_bf16 v[64:67], v[186:189], v[224:227], v[64:67]
	s_barrier
	ds_read_b128 v[190:193], v177 offset:16384
	ds_read_b128 v[194:197], v177 offset:17408
	ds_read_b128 v[198:201], v177 offset:18432
	ds_read_b128 v[202:205], v177 offset:19456
	ds_read_b128 v[206:209], v177 offset:20480
	ds_read_b128 v[210:213], v177 offset:21504
	ds_read_b128 v[214:217], v177 offset:22528
	ds_read_b128 v[224:227], v177 offset:23552
	s_setprio 0
	s_add_i32 s6, s37, s59
	s_mov_b32 m0, s6
	v_lshl_add_u64 v[220:221], s[86:87], 0, v[148:149]
	global_load_lds_dwordx4 v[220:221], off
	s_add_i32 m0, s6, 0x2000
	s_add_u32 s6, s86, 0x40000
	v_lshl_add_u64 v[228:229], s[86:87], 0, v[152:153]
	s_addc_u32 s7, s87, 0
	s_add_i32 s51, s97, s59
	global_load_lds_dwordx4 v[228:229], off
	v_lshl_add_u64 v[230:231], s[6:7], 0, v[148:149]
	s_mov_b32 m0, s51
	v_lshl_add_u64 v[232:233], s[88:89], 0, v[150:151]
	global_load_lds_dwordx4 v[230:231], off
	v_lshl_add_u64 v[230:231], s[6:7], 0, v[152:153]
	s_add_i32 m0, s51, 0x2000
	v_lshl_add_u64 v[234:235], v[232:233], 0, s[68:69]
	global_load_lds_dwordx4 v[230:231], off
	s_mov_b32 m0, s61
	v_lshl_add_u64 v[230:231], s[88:89], 0, v[146:147]
	global_load_lds_dwordx4 v[230:231], off
	s_mov_b32 m0, s63
	s_nop 0
	global_load_lds_dwordx4 v[234:235], off
	s_setprio 1
	s_waitcnt vmcnt(8) lgkmcnt(0)
	s_barrier
	v_mfma_f32_16x16x32_bf16 v[60:63], v[128:131], v[190:193], 0
	v_mfma_f32_16x16x32_bf16 v[56:59], v[136:139], v[190:193], 0
	v_mfma_f32_16x16x32_bf16 v[44:47], v[128:131], v[198:201], 0
	v_mfma_f32_16x16x32_bf16 v[40:43], v[136:139], v[198:201], 0
	v_mfma_f32_16x16x32_bf16 v[28:31], v[128:131], v[206:209], 0
	v_mfma_f32_16x16x32_bf16 v[24:27], v[136:139], v[206:209], 0
	v_mfma_f32_16x16x32_bf16 v[12:15], v[128:131], v[214:217], 0
	v_mfma_f32_16x16x32_bf16 v[8:11], v[136:139], v[214:217], 0
	v_mfma_f32_16x16x32_bf16 v[60:63], v[132:135], v[194:197], v[60:63]
	v_mfma_f32_16x16x32_bf16 v[56:59], v[140:143], v[194:197], v[56:59]
	v_mfma_f32_16x16x32_bf16 v[44:47], v[132:135], v[202:205], v[44:47]
	v_mfma_f32_16x16x32_bf16 v[40:43], v[140:143], v[202:205], v[40:43]
	v_mfma_f32_16x16x32_bf16 v[28:31], v[132:135], v[210:213], v[28:31]
	v_mfma_f32_16x16x32_bf16 v[24:27], v[140:143], v[210:213], v[24:27]
	v_mfma_f32_16x16x32_bf16 v[12:15], v[132:135], v[224:227], v[12:15]
	v_mfma_f32_16x16x32_bf16 v[8:11], v[140:143], v[224:227], v[8:11]
	v_mfma_f32_16x16x32_bf16 v[52:55], v[166:169], v[190:193], 0
	v_mfma_f32_16x16x32_bf16 v[48:51], v[182:185], v[190:193], 0
	v_mfma_f32_16x16x32_bf16 v[36:39], v[166:169], v[198:201], 0
	v_mfma_f32_16x16x32_bf16 v[32:35], v[182:185], v[198:201], 0
	v_mfma_f32_16x16x32_bf16 v[20:23], v[166:169], v[206:209], 0
	v_mfma_f32_16x16x32_bf16 v[16:19], v[182:185], v[206:209], 0
	v_mfma_f32_16x16x32_bf16 v[4:7], v[166:169], v[214:217], 0
	v_mfma_f32_16x16x32_bf16 v[0:3], v[182:185], v[214:217], 0
	v_mfma_f32_16x16x32_bf16 v[52:55], v[170:173], v[194:197], v[52:55]
	v_mfma_f32_16x16x32_bf16 v[48:51], v[186:189], v[194:197], v[48:51]
	v_mfma_f32_16x16x32_bf16 v[36:39], v[170:173], v[202:205], v[36:39]
	v_mfma_f32_16x16x32_bf16 v[32:35], v[186:189], v[202:205], v[32:35]
	v_mfma_f32_16x16x32_bf16 v[20:23], v[170:173], v[210:213], v[20:23]
	v_mfma_f32_16x16x32_bf16 v[16:19], v[186:189], v[210:213], v[16:19]
	v_mfma_f32_16x16x32_bf16 v[4:7], v[170:173], v[224:227], v[4:7]
	v_mfma_f32_16x16x32_bf16 v[0:3], v[186:189], v[224:227], v[0:3]
	s_barrier
	s_setprio 0
	s_add_i32 s6, 0, 0x18000
	s_add_i32 s51, 0, 0x1c000
	v_add_u32_e32 v140, s6, v174
	v_add_u32_e32 v154, s51, v174
	ds_read_b128 v[128:131], v140
	ds_read_b128 v[132:135], v140 offset:1024
	ds_read_b128 v[136:139], v140 offset:2048
	ds_read_b128 v[140:143], v140 offset:3072
	ds_read_b128 v[166:169], v154
	ds_read_b128 v[170:173], v154 offset:1024
	ds_read_b128 v[182:185], v154 offset:2048
	ds_read_b128 v[186:189], v154 offset:3072
	s_mov_b32 m0, s65
	v_lshl_add_u64 v[234:235], v[230:231], 0, s[66:67]
	ds_read_b128 v[190:193], v177 offset:32768
	ds_read_b128 v[194:197], v177 offset:33792
	ds_read_b128 v[198:201], v177 offset:34816
	ds_read_b128 v[202:205], v177 offset:35840
	ds_read_b128 v[206:209], v177 offset:36864
	ds_read_b128 v[210:213], v177 offset:37888
	ds_read_b128 v[214:217], v177 offset:38912
	ds_read_b128 v[224:227], v177 offset:39936
	global_load_lds_dwordx4 v[234:235], off
	s_mov_b32 m0, s77
	v_lshl_add_u64 v[234:235], v[232:233], 0, s[46:47]
	global_load_lds_dwordx4 v[234:235], off
	s_setprio 1
	s_waitcnt vmcnt(8) lgkmcnt(0)
	s_barrier
	v_mfma_f32_16x16x32_bf16 v[124:127], v[128:131], v[190:193], v[124:127]
	v_mfma_f32_16x16x32_bf16 v[120:123], v[136:139], v[190:193], v[120:123]
	v_mfma_f32_16x16x32_bf16 v[108:111], v[128:131], v[198:201], v[108:111]
	v_mfma_f32_16x16x32_bf16 v[104:107], v[136:139], v[198:201], v[104:107]
	v_mfma_f32_16x16x32_bf16 v[92:95], v[128:131], v[206:209], v[92:95]
	v_mfma_f32_16x16x32_bf16 v[88:91], v[136:139], v[206:209], v[88:91]
	v_mfma_f32_16x16x32_bf16 v[76:79], v[128:131], v[214:217], v[76:79]
	v_mfma_f32_16x16x32_bf16 v[72:75], v[136:139], v[214:217], v[72:75]
	v_mfma_f32_16x16x32_bf16 v[124:127], v[132:135], v[194:197], v[124:127]
	v_mfma_f32_16x16x32_bf16 v[120:123], v[140:143], v[194:197], v[120:123]
	v_mfma_f32_16x16x32_bf16 v[108:111], v[132:135], v[202:205], v[108:111]
	v_mfma_f32_16x16x32_bf16 v[104:107], v[140:143], v[202:205], v[104:107]
	v_mfma_f32_16x16x32_bf16 v[92:95], v[132:135], v[210:213], v[92:95]
	v_mfma_f32_16x16x32_bf16 v[88:91], v[140:143], v[210:213], v[88:91]
	v_mfma_f32_16x16x32_bf16 v[76:79], v[132:135], v[224:227], v[76:79]
	v_mfma_f32_16x16x32_bf16 v[72:75], v[140:143], v[224:227], v[72:75]
	v_mfma_f32_16x16x32_bf16 v[116:119], v[166:169], v[190:193], v[116:119]
	v_mfma_f32_16x16x32_bf16 v[112:115], v[182:185], v[190:193], v[112:115]
	v_mfma_f32_16x16x32_bf16 v[100:103], v[166:169], v[198:201], v[100:103]
	v_mfma_f32_16x16x32_bf16 v[96:99], v[182:185], v[198:201], v[96:99]
	v_mfma_f32_16x16x32_bf16 v[84:87], v[166:169], v[206:209], v[84:87]
	v_mfma_f32_16x16x32_bf16 v[80:83], v[182:185], v[206:209], v[80:83]
	v_mfma_f32_16x16x32_bf16 v[68:71], v[166:169], v[214:217], v[68:71]
	v_mfma_f32_16x16x32_bf16 v[64:67], v[182:185], v[214:217], v[64:67]
	v_mfma_f32_16x16x32_bf16 v[116:119], v[170:173], v[194:197], v[116:119]
	v_mfma_f32_16x16x32_bf16 v[112:115], v[186:189], v[194:197], v[112:115]
	v_mfma_f32_16x16x32_bf16 v[100:103], v[170:173], v[202:205], v[100:103]
	v_mfma_f32_16x16x32_bf16 v[96:99], v[186:189], v[202:205], v[96:99]
	v_mfma_f32_16x16x32_bf16 v[84:87], v[170:173], v[210:213], v[84:87]
	v_mfma_f32_16x16x32_bf16 v[80:83], v[186:189], v[210:213], v[80:83]
	v_mfma_f32_16x16x32_bf16 v[68:71], v[170:173], v[224:227], v[68:71]
	v_mfma_f32_16x16x32_bf16 v[64:67], v[186:189], v[224:227], v[64:67]
	s_barrier
	ds_read_b128 v[190:193], v177 offset:49152
	ds_read_b128 v[194:197], v177 offset:50176
	ds_read_b128 v[198:201], v177 offset:51200
	ds_read_b128 v[202:205], v177 offset:52224
	ds_read_b128 v[206:209], v177 offset:53248
	ds_read_b128 v[210:213], v177 offset:54272
	ds_read_b128 v[214:217], v177 offset:55296
	ds_read_b128 v[224:227], v177 offset:56320
	s_setprio 0
	s_add_i32 s6, s6, s59
	s_mov_b32 m0, s6
	v_lshl_add_u64 v[220:221], v[220:221], 0, s[42:43]
	global_load_lds_dwordx4 v[220:221], off
	s_add_i32 m0, s6, 0x2000
	s_add_u32 s6, s86, 0x40080
	v_lshl_add_u64 v[220:221], v[228:229], 0, s[42:43]
	s_addc_u32 s7, s87, 0
	s_add_i32 s51, s51, s59
	global_load_lds_dwordx4 v[220:221], off
	s_mov_b32 m0, s51
	v_lshl_add_u64 v[220:221], s[6:7], 0, v[148:149]
	global_load_lds_dwordx4 v[220:221], off
	s_add_i32 m0, s51, 0x2000
	v_lshl_add_u64 v[220:221], s[6:7], 0, v[152:153]
	global_load_lds_dwordx4 v[220:221], off
	s_mov_b32 m0, s91
	v_lshl_add_u64 v[220:221], v[230:231], 0, s[42:43]
	global_load_lds_dwordx4 v[220:221], off
	s_mov_b32 m0, s92
	v_lshl_add_u64 v[220:221], v[232:233], 0, s[44:45]
	global_load_lds_dwordx4 v[220:221], off
	s_setprio 1
	s_waitcnt vmcnt(8) lgkmcnt(0)
	s_barrier
	v_mfma_f32_16x16x32_bf16 v[60:63], v[128:131], v[190:193], v[60:63]
	v_mfma_f32_16x16x32_bf16 v[56:59], v[136:139], v[190:193], v[56:59]
	v_mfma_f32_16x16x32_bf16 v[44:47], v[128:131], v[198:201], v[44:47]
	v_mfma_f32_16x16x32_bf16 v[40:43], v[136:139], v[198:201], v[40:43]
	v_mfma_f32_16x16x32_bf16 v[28:31], v[128:131], v[206:209], v[28:31]
	v_mfma_f32_16x16x32_bf16 v[24:27], v[136:139], v[206:209], v[24:27]
	v_mfma_f32_16x16x32_bf16 v[12:15], v[128:131], v[214:217], v[12:15]
	v_mfma_f32_16x16x32_bf16 v[8:11], v[136:139], v[214:217], v[8:11]
	v_mfma_f32_16x16x32_bf16 v[60:63], v[132:135], v[194:197], v[60:63]
	v_mfma_f32_16x16x32_bf16 v[56:59], v[140:143], v[194:197], v[56:59]
	v_mfma_f32_16x16x32_bf16 v[44:47], v[132:135], v[202:205], v[44:47]
	v_mfma_f32_16x16x32_bf16 v[40:43], v[140:143], v[202:205], v[40:43]
	v_mfma_f32_16x16x32_bf16 v[28:31], v[132:135], v[210:213], v[28:31]
	v_mfma_f32_16x16x32_bf16 v[24:27], v[140:143], v[210:213], v[24:27]
	v_mfma_f32_16x16x32_bf16 v[12:15], v[132:135], v[224:227], v[12:15]
	v_mfma_f32_16x16x32_bf16 v[8:11], v[140:143], v[224:227], v[8:11]
	v_mfma_f32_16x16x32_bf16 v[52:55], v[166:169], v[190:193], v[52:55]
	v_mfma_f32_16x16x32_bf16 v[48:51], v[182:185], v[190:193], v[48:51]
	v_mfma_f32_16x16x32_bf16 v[36:39], v[166:169], v[198:201], v[36:39]
	v_mfma_f32_16x16x32_bf16 v[32:35], v[182:185], v[198:201], v[32:35]
	v_mfma_f32_16x16x32_bf16 v[20:23], v[166:169], v[206:209], v[20:23]
	v_mfma_f32_16x16x32_bf16 v[16:19], v[182:185], v[206:209], v[16:19]
	v_mfma_f32_16x16x32_bf16 v[4:7], v[166:169], v[214:217], v[4:7]
	v_mfma_f32_16x16x32_bf16 v[0:3], v[182:185], v[214:217], v[0:3]
	v_mfma_f32_16x16x32_bf16 v[52:55], v[170:173], v[194:197], v[52:55]
	v_mfma_f32_16x16x32_bf16 v[48:51], v[186:189], v[194:197], v[48:51]
	v_mfma_f32_16x16x32_bf16 v[36:39], v[170:173], v[202:205], v[36:39]
	v_mfma_f32_16x16x32_bf16 v[32:35], v[186:189], v[202:205], v[32:35]
	v_mfma_f32_16x16x32_bf16 v[20:23], v[170:173], v[210:213], v[20:23]
	v_mfma_f32_16x16x32_bf16 v[16:19], v[186:189], v[210:213], v[16:19]
	v_mfma_f32_16x16x32_bf16 v[4:7], v[170:173], v[224:227], v[4:7]
	v_mfma_f32_16x16x32_bf16 v[0:3], v[186:189], v[224:227], v[0:3]
	s_barrier
	s_setprio 0
	s_add_i32 s50, s50, 2
	s_add_u32 s40, s40, 0x100
	s_addc_u32 s41, s41, 0
	s_cmp_gt_u32 s50, 13
	s_mov_b64 s[6:7], s[8:9]
.LBB0_142:
	ds_read_b128 v[128:131], v175
	ds_read_b128 v[132:135], v175 offset:1024
	ds_read_b128 v[136:139], v175 offset:2048
	ds_read_b128 v[140:143], v175 offset:3072
	ds_read_b128 v[166:169], v176
	ds_read_b128 v[170:173], v176 offset:1024
	ds_read_b128 v[182:185], v176 offset:2048
	ds_read_b128 v[186:189], v176 offset:3072
	s_add_u32 s8, s6, 0x100
	s_addc_u32 s9, s7, 0
	s_cmp_eq_u32 s50, 12
	s_cselect_b32 s89, s5, s9
	s_cselect_b32 s88, s22, s8
	s_cselect_b32 s87, s34, s41
	s_cselect_b32 s86, s35, s40
	v_lshl_add_u64 v[220:221], s[6:7], 0, v[158:159]
	s_add_i32 m0, s61, 0xc000
	ds_read_b128 v[190:193], v177
	ds_read_b128 v[194:197], v177 offset:1024
	ds_read_b128 v[198:201], v177 offset:2048
	ds_read_b128 v[202:205], v177 offset:3072
	ds_read_b128 v[206:209], v177 offset:4096
	ds_read_b128 v[210:213], v177 offset:5120
	ds_read_b128 v[214:217], v177 offset:6144
	ds_read_b128 v[224:227], v177 offset:7168
	global_load_lds_dwordx4 v[220:221], off
	s_add_i32 m0, s61, 0xe000
	v_lshl_add_u64 v[220:221], s[6:7], 0, v[160:161]
	global_load_lds_dwordx4 v[220:221], off
	s_setprio 1
	s_waitcnt vmcnt(8) lgkmcnt(0)
	s_barrier
	v_mfma_f32_16x16x32_bf16 v[124:127], v[128:131], v[190:193], v[124:127]
	v_mfma_f32_16x16x32_bf16 v[120:123], v[136:139], v[190:193], v[120:123]
	v_mfma_f32_16x16x32_bf16 v[108:111], v[128:131], v[198:201], v[108:111]
	v_mfma_f32_16x16x32_bf16 v[104:107], v[136:139], v[198:201], v[104:107]
	v_mfma_f32_16x16x32_bf16 v[92:95], v[128:131], v[206:209], v[92:95]
	v_mfma_f32_16x16x32_bf16 v[88:91], v[136:139], v[206:209], v[88:91]
	v_mfma_f32_16x16x32_bf16 v[76:79], v[128:131], v[214:217], v[76:79]
	v_mfma_f32_16x16x32_bf16 v[72:75], v[136:139], v[214:217], v[72:75]
	v_mfma_f32_16x16x32_bf16 v[124:127], v[132:135], v[194:197], v[124:127]
	v_mfma_f32_16x16x32_bf16 v[120:123], v[140:143], v[194:197], v[120:123]
	v_mfma_f32_16x16x32_bf16 v[108:111], v[132:135], v[202:205], v[108:111]
	v_mfma_f32_16x16x32_bf16 v[104:107], v[140:143], v[202:205], v[104:107]
	v_mfma_f32_16x16x32_bf16 v[92:95], v[132:135], v[210:213], v[92:95]
	v_mfma_f32_16x16x32_bf16 v[88:91], v[140:143], v[210:213], v[88:91]
	v_mfma_f32_16x16x32_bf16 v[76:79], v[132:135], v[224:227], v[76:79]
	v_mfma_f32_16x16x32_bf16 v[72:75], v[140:143], v[224:227], v[72:75]
	v_mfma_f32_16x16x32_bf16 v[116:119], v[166:169], v[190:193], v[116:119]
	v_mfma_f32_16x16x32_bf16 v[112:115], v[182:185], v[190:193], v[112:115]
	v_mfma_f32_16x16x32_bf16 v[100:103], v[166:169], v[198:201], v[100:103]
	v_mfma_f32_16x16x32_bf16 v[96:99], v[182:185], v[198:201], v[96:99]
	v_mfma_f32_16x16x32_bf16 v[84:87], v[166:169], v[206:209], v[84:87]
	v_mfma_f32_16x16x32_bf16 v[80:83], v[182:185], v[206:209], v[80:83]
	v_mfma_f32_16x16x32_bf16 v[68:71], v[166:169], v[214:217], v[68:71]
	v_mfma_f32_16x16x32_bf16 v[64:67], v[182:185], v[214:217], v[64:67]
	v_mfma_f32_16x16x32_bf16 v[116:119], v[170:173], v[194:197], v[116:119]
	v_mfma_f32_16x16x32_bf16 v[112:115], v[186:189], v[194:197], v[112:115]
	v_mfma_f32_16x16x32_bf16 v[100:103], v[170:173], v[202:205], v[100:103]
	v_mfma_f32_16x16x32_bf16 v[96:99], v[186:189], v[202:205], v[96:99]
	v_mfma_f32_16x16x32_bf16 v[84:87], v[170:173], v[210:213], v[84:87]
	v_mfma_f32_16x16x32_bf16 v[80:83], v[186:189], v[210:213], v[80:83]
	v_mfma_f32_16x16x32_bf16 v[68:71], v[170:173], v[224:227], v[68:71]
	v_mfma_f32_16x16x32_bf16 v[64:67], v[186:189], v[224:227], v[64:67]
	s_barrier
	ds_read_b128 v[190:193], v177 offset:16384
	ds_read_b128 v[194:197], v177 offset:17408
	ds_read_b128 v[198:201], v177 offset:18432
	ds_read_b128 v[202:205], v177 offset:19456
	ds_read_b128 v[206:209], v177 offset:20480
	ds_read_b128 v[210:213], v177 offset:21504
	ds_read_b128 v[214:217], v177 offset:22528
	ds_read_b128 v[224:227], v177 offset:23552
	s_setprio 0
	s_add_i32 s6, s37, s59
	s_mov_b32 m0, s6
	v_lshl_add_u64 v[220:221], s[86:87], 0, v[148:149]
	global_load_lds_dwordx4 v[220:221], off
	s_add_i32 m0, s6, 0x2000
	s_add_u32 s6, s86, 0x40000
	v_lshl_add_u64 v[228:229], s[86:87], 0, v[152:153]
	s_addc_u32 s7, s87, 0
	s_add_i32 s51, s97, s59
	global_load_lds_dwordx4 v[228:229], off
	v_lshl_add_u64 v[230:231], s[6:7], 0, v[148:149]
	s_mov_b32 m0, s51
	v_lshl_add_u64 v[232:233], s[88:89], 0, v[150:151]
	global_load_lds_dwordx4 v[230:231], off
	v_lshl_add_u64 v[230:231], s[6:7], 0, v[152:153]
	s_add_i32 m0, s51, 0x2000
	v_lshl_add_u64 v[234:235], v[232:233], 0, s[68:69]
	global_load_lds_dwordx4 v[230:231], off
	s_mov_b32 m0, s61
	v_lshl_add_u64 v[230:231], s[88:89], 0, v[146:147]
	global_load_lds_dwordx4 v[230:231], off
	s_mov_b32 m0, s63
	s_nop 0
	global_load_lds_dwordx4 v[234:235], off
	s_setprio 1
	s_waitcnt vmcnt(8) lgkmcnt(0)
	s_barrier
	v_mfma_f32_16x16x32_bf16 v[60:63], v[128:131], v[190:193], v[60:63]
	v_mfma_f32_16x16x32_bf16 v[56:59], v[136:139], v[190:193], v[56:59]
	v_mfma_f32_16x16x32_bf16 v[44:47], v[128:131], v[198:201], v[44:47]
	v_mfma_f32_16x16x32_bf16 v[40:43], v[136:139], v[198:201], v[40:43]
	v_mfma_f32_16x16x32_bf16 v[28:31], v[128:131], v[206:209], v[28:31]
	v_mfma_f32_16x16x32_bf16 v[24:27], v[136:139], v[206:209], v[24:27]
	v_mfma_f32_16x16x32_bf16 v[12:15], v[128:131], v[214:217], v[12:15]
	v_mfma_f32_16x16x32_bf16 v[8:11], v[136:139], v[214:217], v[8:11]
	v_mfma_f32_16x16x32_bf16 v[60:63], v[132:135], v[194:197], v[60:63]
	v_mfma_f32_16x16x32_bf16 v[56:59], v[140:143], v[194:197], v[56:59]
	v_mfma_f32_16x16x32_bf16 v[44:47], v[132:135], v[202:205], v[44:47]
	v_mfma_f32_16x16x32_bf16 v[40:43], v[140:143], v[202:205], v[40:43]
	v_mfma_f32_16x16x32_bf16 v[28:31], v[132:135], v[210:213], v[28:31]
	v_mfma_f32_16x16x32_bf16 v[24:27], v[140:143], v[210:213], v[24:27]
	v_mfma_f32_16x16x32_bf16 v[12:15], v[132:135], v[224:227], v[12:15]
	v_mfma_f32_16x16x32_bf16 v[8:11], v[140:143], v[224:227], v[8:11]
	v_mfma_f32_16x16x32_bf16 v[52:55], v[166:169], v[190:193], v[52:55]
	v_mfma_f32_16x16x32_bf16 v[48:51], v[182:185], v[190:193], v[48:51]
	v_mfma_f32_16x16x32_bf16 v[36:39], v[166:169], v[198:201], v[36:39]
	v_mfma_f32_16x16x32_bf16 v[32:35], v[182:185], v[198:201], v[32:35]
	v_mfma_f32_16x16x32_bf16 v[20:23], v[166:169], v[206:209], v[20:23]
	v_mfma_f32_16x16x32_bf16 v[16:19], v[182:185], v[206:209], v[16:19]
	v_mfma_f32_16x16x32_bf16 v[4:7], v[166:169], v[214:217], v[4:7]
	v_mfma_f32_16x16x32_bf16 v[0:3], v[182:185], v[214:217], v[0:3]
	v_mfma_f32_16x16x32_bf16 v[52:55], v[170:173], v[194:197], v[52:55]
	v_mfma_f32_16x16x32_bf16 v[48:51], v[186:189], v[194:197], v[48:51]
	v_mfma_f32_16x16x32_bf16 v[36:39], v[170:173], v[202:205], v[36:39]
	v_mfma_f32_16x16x32_bf16 v[32:35], v[186:189], v[202:205], v[32:35]
	v_mfma_f32_16x16x32_bf16 v[20:23], v[170:173], v[210:213], v[20:23]
	v_mfma_f32_16x16x32_bf16 v[16:19], v[186:189], v[210:213], v[16:19]
	v_mfma_f32_16x16x32_bf16 v[4:7], v[170:173], v[224:227], v[4:7]
	v_mfma_f32_16x16x32_bf16 v[0:3], v[186:189], v[224:227], v[0:3]
	s_barrier
	s_setprio 0
	s_add_i32 s6, 0, 0x18000
	s_add_i32 s51, 0, 0x1c000
	v_add_u32_e32 v140, s6, v174
	v_add_u32_e32 v154, s51, v174
	ds_read_b128 v[128:131], v140
	ds_read_b128 v[132:135], v140 offset:1024
	ds_read_b128 v[136:139], v140 offset:2048
	ds_read_b128 v[140:143], v140 offset:3072
	ds_read_b128 v[166:169], v154
	ds_read_b128 v[170:173], v154 offset:1024
	ds_read_b128 v[182:185], v154 offset:2048
	ds_read_b128 v[186:189], v154 offset:3072
	s_mov_b32 m0, s65
	v_lshl_add_u64 v[234:235], v[230:231], 0, s[66:67]
	ds_read_b128 v[190:193], v177 offset:32768
	ds_read_b128 v[194:197], v177 offset:33792
	ds_read_b128 v[198:201], v177 offset:34816
	ds_read_b128 v[202:205], v177 offset:35840
	ds_read_b128 v[206:209], v177 offset:36864
	ds_read_b128 v[210:213], v177 offset:37888
	ds_read_b128 v[214:217], v177 offset:38912
	ds_read_b128 v[224:227], v177 offset:39936
	global_load_lds_dwordx4 v[234:235], off
	s_mov_b32 m0, s77
	v_lshl_add_u64 v[234:235], v[232:233], 0, s[46:47]
	global_load_lds_dwordx4 v[234:235], off
	s_setprio 1
	s_waitcnt vmcnt(8) lgkmcnt(0)
	s_barrier
	v_mfma_f32_16x16x32_bf16 v[124:127], v[128:131], v[190:193], v[124:127]
	v_mfma_f32_16x16x32_bf16 v[120:123], v[136:139], v[190:193], v[120:123]
	v_mfma_f32_16x16x32_bf16 v[108:111], v[128:131], v[198:201], v[108:111]
	v_mfma_f32_16x16x32_bf16 v[104:107], v[136:139], v[198:201], v[104:107]
	v_mfma_f32_16x16x32_bf16 v[92:95], v[128:131], v[206:209], v[92:95]
	v_mfma_f32_16x16x32_bf16 v[88:91], v[136:139], v[206:209], v[88:91]
	v_mfma_f32_16x16x32_bf16 v[76:79], v[128:131], v[214:217], v[76:79]
	v_mfma_f32_16x16x32_bf16 v[72:75], v[136:139], v[214:217], v[72:75]
	v_mfma_f32_16x16x32_bf16 v[124:127], v[132:135], v[194:197], v[124:127]
	v_mfma_f32_16x16x32_bf16 v[120:123], v[140:143], v[194:197], v[120:123]
	v_mfma_f32_16x16x32_bf16 v[108:111], v[132:135], v[202:205], v[108:111]
	v_mfma_f32_16x16x32_bf16 v[104:107], v[140:143], v[202:205], v[104:107]
	v_mfma_f32_16x16x32_bf16 v[92:95], v[132:135], v[210:213], v[92:95]
	v_mfma_f32_16x16x32_bf16 v[88:91], v[140:143], v[210:213], v[88:91]
	v_mfma_f32_16x16x32_bf16 v[76:79], v[132:135], v[224:227], v[76:79]
	v_mfma_f32_16x16x32_bf16 v[72:75], v[140:143], v[224:227], v[72:75]
	v_mfma_f32_16x16x32_bf16 v[116:119], v[166:169], v[190:193], v[116:119]
	v_mfma_f32_16x16x32_bf16 v[112:115], v[182:185], v[190:193], v[112:115]
	v_mfma_f32_16x16x32_bf16 v[100:103], v[166:169], v[198:201], v[100:103]
	v_mfma_f32_16x16x32_bf16 v[96:99], v[182:185], v[198:201], v[96:99]
	v_mfma_f32_16x16x32_bf16 v[84:87], v[166:169], v[206:209], v[84:87]
	v_mfma_f32_16x16x32_bf16 v[80:83], v[182:185], v[206:209], v[80:83]
	v_mfma_f32_16x16x32_bf16 v[68:71], v[166:169], v[214:217], v[68:71]
	v_mfma_f32_16x16x32_bf16 v[64:67], v[182:185], v[214:217], v[64:67]
	v_mfma_f32_16x16x32_bf16 v[116:119], v[170:173], v[194:197], v[116:119]
	v_mfma_f32_16x16x32_bf16 v[112:115], v[186:189], v[194:197], v[112:115]
	v_mfma_f32_16x16x32_bf16 v[100:103], v[170:173], v[202:205], v[100:103]
	v_mfma_f32_16x16x32_bf16 v[96:99], v[186:189], v[202:205], v[96:99]
	v_mfma_f32_16x16x32_bf16 v[84:87], v[170:173], v[210:213], v[84:87]
	v_mfma_f32_16x16x32_bf16 v[80:83], v[186:189], v[210:213], v[80:83]
	v_mfma_f32_16x16x32_bf16 v[68:71], v[170:173], v[224:227], v[68:71]
	v_mfma_f32_16x16x32_bf16 v[64:67], v[186:189], v[224:227], v[64:67]
	s_barrier
	ds_read_b128 v[190:193], v177 offset:49152
	ds_read_b128 v[194:197], v177 offset:50176
	ds_read_b128 v[198:201], v177 offset:51200
	ds_read_b128 v[202:205], v177 offset:52224
	ds_read_b128 v[206:209], v177 offset:53248
	ds_read_b128 v[210:213], v177 offset:54272
	ds_read_b128 v[214:217], v177 offset:55296
	ds_read_b128 v[224:227], v177 offset:56320
	s_setprio 0
	s_add_i32 s6, s6, s59
	s_mov_b32 m0, s6
	v_lshl_add_u64 v[220:221], v[220:221], 0, s[42:43]
	global_load_lds_dwordx4 v[220:221], off
	s_add_i32 m0, s6, 0x2000
	s_add_u32 s6, s86, 0x40080
	v_lshl_add_u64 v[220:221], v[228:229], 0, s[42:43]
	s_addc_u32 s7, s87, 0
	s_add_i32 s51, s51, s59
	global_load_lds_dwordx4 v[220:221], off
	s_mov_b32 m0, s51
	v_lshl_add_u64 v[220:221], s[6:7], 0, v[148:149]
	global_load_lds_dwordx4 v[220:221], off
	s_add_i32 m0, s51, 0x2000
	v_lshl_add_u64 v[220:221], s[6:7], 0, v[152:153]
	global_load_lds_dwordx4 v[220:221], off
	s_mov_b32 m0, s91
	v_lshl_add_u64 v[220:221], v[230:231], 0, s[42:43]
	global_load_lds_dwordx4 v[220:221], off
	s_mov_b32 m0, s92
	v_lshl_add_u64 v[220:221], v[232:233], 0, s[44:45]
	global_load_lds_dwordx4 v[220:221], off
	s_setprio 1
	s_waitcnt vmcnt(8) lgkmcnt(0)
	s_barrier
	v_mfma_f32_16x16x32_bf16 v[60:63], v[128:131], v[190:193], v[60:63]
	v_mfma_f32_16x16x32_bf16 v[56:59], v[136:139], v[190:193], v[56:59]
	v_mfma_f32_16x16x32_bf16 v[44:47], v[128:131], v[198:201], v[44:47]
	v_mfma_f32_16x16x32_bf16 v[40:43], v[136:139], v[198:201], v[40:43]
	v_mfma_f32_16x16x32_bf16 v[28:31], v[128:131], v[206:209], v[28:31]
	v_mfma_f32_16x16x32_bf16 v[24:27], v[136:139], v[206:209], v[24:27]
	v_mfma_f32_16x16x32_bf16 v[12:15], v[128:131], v[214:217], v[12:15]
	v_mfma_f32_16x16x32_bf16 v[8:11], v[136:139], v[214:217], v[8:11]
	v_mfma_f32_16x16x32_bf16 v[60:63], v[132:135], v[194:197], v[60:63]
	v_mfma_f32_16x16x32_bf16 v[56:59], v[140:143], v[194:197], v[56:59]
	v_mfma_f32_16x16x32_bf16 v[44:47], v[132:135], v[202:205], v[44:47]
	v_mfma_f32_16x16x32_bf16 v[40:43], v[140:143], v[202:205], v[40:43]
	v_mfma_f32_16x16x32_bf16 v[28:31], v[132:135], v[210:213], v[28:31]
	v_mfma_f32_16x16x32_bf16 v[24:27], v[140:143], v[210:213], v[24:27]
	v_mfma_f32_16x16x32_bf16 v[12:15], v[132:135], v[224:227], v[12:15]
	v_mfma_f32_16x16x32_bf16 v[8:11], v[140:143], v[224:227], v[8:11]
	v_mfma_f32_16x16x32_bf16 v[52:55], v[166:169], v[190:193], v[52:55]
	v_mfma_f32_16x16x32_bf16 v[48:51], v[182:185], v[190:193], v[48:51]
	v_mfma_f32_16x16x32_bf16 v[36:39], v[166:169], v[198:201], v[36:39]
	v_mfma_f32_16x16x32_bf16 v[32:35], v[182:185], v[198:201], v[32:35]
	v_mfma_f32_16x16x32_bf16 v[20:23], v[166:169], v[206:209], v[20:23]
	v_mfma_f32_16x16x32_bf16 v[16:19], v[182:185], v[206:209], v[16:19]
	v_mfma_f32_16x16x32_bf16 v[4:7], v[166:169], v[214:217], v[4:7]
	v_mfma_f32_16x16x32_bf16 v[0:3], v[182:185], v[214:217], v[0:3]
	v_mfma_f32_16x16x32_bf16 v[52:55], v[170:173], v[194:197], v[52:55]
	v_mfma_f32_16x16x32_bf16 v[48:51], v[186:189], v[194:197], v[48:51]
	v_mfma_f32_16x16x32_bf16 v[36:39], v[170:173], v[202:205], v[36:39]
	v_mfma_f32_16x16x32_bf16 v[32:35], v[186:189], v[202:205], v[32:35]
	v_mfma_f32_16x16x32_bf16 v[20:23], v[170:173], v[210:213], v[20:23]
	v_mfma_f32_16x16x32_bf16 v[16:19], v[186:189], v[210:213], v[16:19]
	v_mfma_f32_16x16x32_bf16 v[4:7], v[170:173], v[224:227], v[4:7]
	v_mfma_f32_16x16x32_bf16 v[0:3], v[186:189], v[224:227], v[0:3]
	s_barrier
	s_setprio 0
	s_add_i32 s50, s50, 2
	s_add_u32 s40, s40, 0x100
	s_addc_u32 s41, s41, 0
	s_cmp_gt_u32 s50, 13
	s_mov_b64 s[6:7], s[8:9]
	s_cbranch_scc0 .LBB0_142
	v_readlane_b32 s6, v249, 60
	v_readlane_b32 s7, v249, 61
	s_and_b64 vcc, exec, s[6:7]
	s_cbranch_vccz .LBB0_145
	s_barrier

.LBB0_392:
	s_lshl_b32 s40, s65, 8
	v_readlane_b32 s72, v249, 0
	s_ashr_i32 s41, s40, 31
	v_readlane_b32 s84, v249, 12
	v_readlane_b32 s85, v249, 13
	s_lshl_b64 s[40:41], s[40:41], 10
	v_readlane_b32 s86, v249, 14
	v_readlane_b32 s87, v249, 15
	s_mov_b64 s[28:29], s[84:85]
	s_add_u32 s40, s28, s40
	s_addc_u32 s41, s29, s41
	s_and_b64 s[42:43], s[0:1], exec
	s_cselect_b32 s67, s41, s45
	s_cselect_b32 s72, s40, s44
	s_ashr_i32 s39, s38, 31
	s_lshl_b64 s[42:43], s[38:39], 18
	s_add_u32 s42, s10, s42
	s_addc_u32 s43, s11, s43
	s_and_b64 s[48:49], s[0:1], exec
	v_readlane_b32 s73, v249, 1
	v_readlane_b32 s74, v249, 2
	s_cselect_b32 s39, s43, s47
	s_cselect_b32 s50, s42, s46
	s_add_u32 s51, s46, 0x100
	s_addc_u32 s73, s47, 0
	s_mov_b32 s74, -2
	s_waitcnt vmcnt(0)
	s_waitcnt lgkmcnt(0)
	v_readlane_b32 s75, v249, 3
	v_readlane_b32 s76, v249, 4
	v_readlane_b32 s77, v249, 5
	v_readlane_b32 s78, v249, 6
	v_readlane_b32 s79, v249, 7
	v_readlane_b32 s80, v249, 8
	v_readlane_b32 s81, v249, 9
	v_readlane_b32 s82, v249, 10
	v_readlane_b32 s83, v249, 11
	s_mov_b64 s[30:31], s[86:87]
	ds_read_b128 v[144:147], v153
	ds_read_b128 v[156:159], v153 offset:1024
	ds_read_b128 v[160:163], v153 offset:2048
	ds_read_b128 v[164:167], v153 offset:3072
	ds_read_b128 v[168:171], v154
	ds_read_b128 v[172:175], v154 offset:1024
	ds_read_b128 v[176:179], v154 offset:2048
	ds_read_b128 v[180:183], v154 offset:3072
	s_add_u32 s46, s44, 0x100
	s_addc_u32 s47, s45, 0
	s_cmp_eq_u32 s74, 4
	s_cselect_b32 s77, s67, s47
	s_cselect_b32 s76, s72, s46
	s_cselect_b32 s49, s39, s73
	s_cselect_b32 s48, s50, s51
	v_lshl_add_u64 v[148:149], s[44:45], 0, v[136:137]
	s_add_i32 m0, s52, 0xc000
	ds_read_b128 v[184:187], v155
	ds_read_b128 v[188:191], v155 offset:1024
	ds_read_b128 v[192:195], v155 offset:2048
	ds_read_b128 v[196:199], v155 offset:3072
	ds_read_b128 v[200:203], v155 offset:4096
	ds_read_b128 v[204:207], v155 offset:5120
	ds_read_b128 v[208:211], v155 offset:6144
	ds_read_b128 v[212:215], v155 offset:7168
	global_load_lds_dwordx4 v[148:149], off
	s_add_i32 m0, s52, 0xe000
	v_lshl_add_u64 v[148:149], s[44:45], 0, v[138:139]
	global_load_lds_dwordx4 v[148:149], off
	s_setprio 1
	s_waitcnt vmcnt(8) lgkmcnt(0)
	s_barrier
	v_mfma_f32_16x16x32_bf16 v[124:127], v[144:147], v[184:187], 0
	v_mfma_f32_16x16x32_bf16 v[120:123], v[160:163], v[184:187], 0
	v_mfma_f32_16x16x32_bf16 v[108:111], v[144:147], v[192:195], 0
	v_mfma_f32_16x16x32_bf16 v[104:107], v[160:163], v[192:195], 0
	v_mfma_f32_16x16x32_bf16 v[92:95], v[144:147], v[200:203], 0
	v_mfma_f32_16x16x32_bf16 v[88:91], v[160:163], v[200:203], 0
	v_mfma_f32_16x16x32_bf16 v[76:79], v[144:147], v[208:211], 0
	v_mfma_f32_16x16x32_bf16 v[72:75], v[160:163], v[208:211], 0
	v_mfma_f32_16x16x32_bf16 v[124:127], v[156:159], v[188:191], v[124:127]
	v_mfma_f32_16x16x32_bf16 v[120:123], v[164:167], v[188:191], v[120:123]
	v_mfma_f32_16x16x32_bf16 v[108:111], v[156:159], v[196:199], v[108:111]
	v_mfma_f32_16x16x32_bf16 v[104:107], v[164:167], v[196:199], v[104:107]
	v_mfma_f32_16x16x32_bf16 v[92:95], v[156:159], v[204:207], v[92:95]
	v_mfma_f32_16x16x32_bf16 v[88:91], v[164:167], v[204:207], v[88:91]
	v_mfma_f32_16x16x32_bf16 v[76:79], v[156:159], v[212:215], v[76:79]
	v_mfma_f32_16x16x32_bf16 v[72:75], v[164:167], v[212:215], v[72:75]
	v_mfma_f32_16x16x32_bf16 v[116:119], v[168:171], v[184:187], 0
	v_mfma_f32_16x16x32_bf16 v[112:115], v[176:179], v[184:187], 0
	v_mfma_f32_16x16x32_bf16 v[100:103], v[168:171], v[192:195], 0
	v_mfma_f32_16x16x32_bf16 v[96:99], v[176:179], v[192:195], 0
	v_mfma_f32_16x16x32_bf16 v[84:87], v[168:171], v[200:203], 0
	v_mfma_f32_16x16x32_bf16 v[80:83], v[176:179], v[200:203], 0
	v_mfma_f32_16x16x32_bf16 v[68:71], v[168:171], v[208:211], 0
	v_mfma_f32_16x16x32_bf16 v[64:67], v[176:179], v[208:211], 0
	v_mfma_f32_16x16x32_bf16 v[116:119], v[172:175], v[188:191], v[116:119]
	v_mfma_f32_16x16x32_bf16 v[112:115], v[180:183], v[188:191], v[112:115]
	v_mfma_f32_16x16x32_bf16 v[100:103], v[172:175], v[196:199], v[100:103]
	v_mfma_f32_16x16x32_bf16 v[96:99], v[180:183], v[196:199], v[96:99]
	v_mfma_f32_16x16x32_bf16 v[84:87], v[172:175], v[204:207], v[84:87]
	v_mfma_f32_16x16x32_bf16 v[80:83], v[180:183], v[204:207], v[80:83]
	v_mfma_f32_16x16x32_bf16 v[68:71], v[172:175], v[212:215], v[68:71]
	v_mfma_f32_16x16x32_bf16 v[64:67], v[180:183], v[212:215], v[64:67]
	s_barrier
	ds_read_b128 v[184:187], v155 offset:16384
	ds_read_b128 v[188:191], v155 offset:17408
	ds_read_b128 v[192:195], v155 offset:18432
	ds_read_b128 v[196:199], v155 offset:19456
	ds_read_b128 v[200:203], v155 offset:20480
	ds_read_b128 v[204:207], v155 offset:21504
	ds_read_b128 v[208:211], v155 offset:22528
	ds_read_b128 v[212:215], v155 offset:23552
	s_setprio 0
	s_add_i32 s44, s61, s33
	s_mov_b32 m0, s44
	v_lshl_add_u64 v[148:149], s[48:49], 0, v[132:133]
	global_load_lds_dwordx4 v[148:149], off
	s_add_i32 m0, s44, 0x2000
	s_add_u32 s44, s48, 0x20000
	v_lshl_add_u64 v[216:217], s[48:49], 0, v[128:129]
	s_addc_u32 s45, s49, 0
	s_add_i32 s68, s62, s33
	global_load_lds_dwordx4 v[216:217], off
	v_lshl_add_u64 v[220:221], s[44:45], 0, v[132:133]
	s_mov_b32 m0, s68
	v_lshl_add_u64 v[224:225], s[76:77], 0, v[130:131]
	global_load_lds_dwordx4 v[220:221], off
	v_lshl_add_u64 v[220:221], s[44:45], 0, v[128:129]
	s_add_i32 m0, s68, 0x2000
	v_lshl_add_u64 v[226:227], v[224:225], 0, s[8:9]
	global_load_lds_dwordx4 v[220:221], off
	s_mov_b32 m0, s52
	v_lshl_add_u64 v[220:221], s[76:77], 0, v[134:135]
	global_load_lds_dwordx4 v[220:221], off
	s_mov_b32 m0, s53
	s_nop 0
	global_load_lds_dwordx4 v[226:227], off
	s_setprio 1
	s_waitcnt vmcnt(8) lgkmcnt(0)
	s_barrier
	v_mfma_f32_16x16x32_bf16 v[60:63], v[144:147], v[184:187], 0
	v_mfma_f32_16x16x32_bf16 v[56:59], v[160:163], v[184:187], 0
	v_mfma_f32_16x16x32_bf16 v[44:47], v[144:147], v[192:195], 0
	v_mfma_f32_16x16x32_bf16 v[40:43], v[160:163], v[192:195], 0
	v_mfma_f32_16x16x32_bf16 v[28:31], v[144:147], v[200:203], 0
	v_mfma_f32_16x16x32_bf16 v[24:27], v[160:163], v[200:203], 0
	v_mfma_f32_16x16x32_bf16 v[12:15], v[144:147], v[208:211], 0
	v_mfma_f32_16x16x32_bf16 v[8:11], v[160:163], v[208:211], 0
	v_mfma_f32_16x16x32_bf16 v[60:63], v[156:159], v[188:191], v[60:63]
	v_mfma_f32_16x16x32_bf16 v[56:59], v[164:167], v[188:191], v[56:59]
	v_mfma_f32_16x16x32_bf16 v[44:47], v[156:159], v[196:199], v[44:47]
	v_mfma_f32_16x16x32_bf16 v[40:43], v[164:167], v[196:199], v[40:43]
	v_mfma_f32_16x16x32_bf16 v[28:31], v[156:159], v[204:207], v[28:31]
	v_mfma_f32_16x16x32_bf16 v[24:27], v[164:167], v[204:207], v[24:27]
	v_mfma_f32_16x16x32_bf16 v[12:15], v[156:159], v[212:215], v[12:15]
	v_mfma_f32_16x16x32_bf16 v[8:11], v[164:167], v[212:215], v[8:11]
	v_mfma_f32_16x16x32_bf16 v[52:55], v[168:171], v[184:187], 0
	v_mfma_f32_16x16x32_bf16 v[48:51], v[176:179], v[184:187], 0
	v_mfma_f32_16x16x32_bf16 v[36:39], v[168:171], v[192:195], 0
	v_mfma_f32_16x16x32_bf16 v[32:35], v[176:179], v[192:195], 0
	v_mfma_f32_16x16x32_bf16 v[20:23], v[168:171], v[200:203], 0
	v_mfma_f32_16x16x32_bf16 v[16:19], v[176:179], v[200:203], 0
	v_mfma_f32_16x16x32_bf16 v[4:7], v[168:171], v[208:211], 0
	v_mfma_f32_16x16x32_bf16 v[0:3], v[176:179], v[208:211], 0
	v_mfma_f32_16x16x32_bf16 v[52:55], v[172:175], v[188:191], v[52:55]
	v_mfma_f32_16x16x32_bf16 v[48:51], v[180:183], v[188:191], v[48:51]
	v_mfma_f32_16x16x32_bf16 v[36:39], v[172:175], v[196:199], v[36:39]
	v_mfma_f32_16x16x32_bf16 v[32:35], v[180:183], v[196:199], v[32:35]
	v_mfma_f32_16x16x32_bf16 v[20:23], v[172:175], v[204:207], v[20:23]
	v_mfma_f32_16x16x32_bf16 v[16:19], v[180:183], v[204:207], v[16:19]
	v_mfma_f32_16x16x32_bf16 v[4:7], v[172:175], v[212:215], v[4:7]
	v_mfma_f32_16x16x32_bf16 v[0:3], v[180:183], v[212:215], v[0:3]
	s_barrier
	s_setprio 0
	s_add_i32 s44, 0, 0x18000
	s_add_i32 s68, 0, 0x1c000
	v_add_u32_e32 v164, s44, v151
	v_add_u32_e32 v180, s68, v151
	ds_read_b128 v[144:147], v164
	ds_read_b128 v[156:159], v164 offset:1024
	ds_read_b128 v[160:163], v164 offset:2048
	ds_read_b128 v[164:167], v164 offset:3072
	ds_read_b128 v[168:171], v180
	ds_read_b128 v[172:175], v180 offset:1024
	ds_read_b128 v[176:179], v180 offset:2048
	ds_read_b128 v[180:183], v180 offset:3072
	s_mov_b32 m0, s54
	v_lshl_add_u64 v[226:227], v[220:221], 0, s[6:7]
	ds_read_b128 v[184:187], v155 offset:32768
	ds_read_b128 v[188:191], v155 offset:33792
	ds_read_b128 v[192:195], v155 offset:34816
	ds_read_b128 v[196:199], v155 offset:35840
	ds_read_b128 v[200:203], v155 offset:36864
	ds_read_b128 v[204:207], v155 offset:37888
	ds_read_b128 v[208:211], v155 offset:38912
	ds_read_b128 v[212:215], v155 offset:39936
	global_load_lds_dwordx4 v[226:227], off
	s_mov_b32 m0, s55
	v_lshl_add_u64 v[226:227], v[224:225], 0, s[12:13]
	global_load_lds_dwordx4 v[226:227], off
	s_setprio 1
	s_waitcnt vmcnt(8) lgkmcnt(0)
	s_barrier
	v_mfma_f32_16x16x32_bf16 v[124:127], v[144:147], v[184:187], v[124:127]
	v_mfma_f32_16x16x32_bf16 v[120:123], v[160:163], v[184:187], v[120:123]
	v_mfma_f32_16x16x32_bf16 v[108:111], v[144:147], v[192:195], v[108:111]
	v_mfma_f32_16x16x32_bf16 v[104:107], v[160:163], v[192:195], v[104:107]
	v_mfma_f32_16x16x32_bf16 v[92:95], v[144:147], v[200:203], v[92:95]
	v_mfma_f32_16x16x32_bf16 v[88:91], v[160:163], v[200:203], v[88:91]
	v_mfma_f32_16x16x32_bf16 v[76:79], v[144:147], v[208:211], v[76:79]
	v_mfma_f32_16x16x32_bf16 v[72:75], v[160:163], v[208:211], v[72:75]
	v_mfma_f32_16x16x32_bf16 v[124:127], v[156:159], v[188:191], v[124:127]
	v_mfma_f32_16x16x32_bf16 v[120:123], v[164:167], v[188:191], v[120:123]
	v_mfma_f32_16x16x32_bf16 v[108:111], v[156:159], v[196:199], v[108:111]
	v_mfma_f32_16x16x32_bf16 v[104:107], v[164:167], v[196:199], v[104:107]
	v_mfma_f32_16x16x32_bf16 v[92:95], v[156:159], v[204:207], v[92:95]
	v_mfma_f32_16x16x32_bf16 v[88:91], v[164:167], v[204:207], v[88:91]
	v_mfma_f32_16x16x32_bf16 v[76:79], v[156:159], v[212:215], v[76:79]
	v_mfma_f32_16x16x32_bf16 v[72:75], v[164:167], v[212:215], v[72:75]
	v_mfma_f32_16x16x32_bf16 v[116:119], v[168:171], v[184:187], v[116:119]
	v_mfma_f32_16x16x32_bf16 v[112:115], v[176:179], v[184:187], v[112:115]
	v_mfma_f32_16x16x32_bf16 v[100:103], v[168:171], v[192:195], v[100:103]
	v_mfma_f32_16x16x32_bf16 v[96:99], v[176:179], v[192:195], v[96:99]
	v_mfma_f32_16x16x32_bf16 v[84:87], v[168:171], v[200:203], v[84:87]
	v_mfma_f32_16x16x32_bf16 v[80:83], v[176:179], v[200:203], v[80:83]
	v_mfma_f32_16x16x32_bf16 v[68:71], v[168:171], v[208:211], v[68:71]
	v_mfma_f32_16x16x32_bf16 v[64:67], v[176:179], v[208:211], v[64:67]
	v_mfma_f32_16x16x32_bf16 v[116:119], v[172:175], v[188:191], v[116:119]
	v_mfma_f32_16x16x32_bf16 v[112:115], v[180:183], v[188:191], v[112:115]
	v_mfma_f32_16x16x32_bf16 v[100:103], v[172:175], v[196:199], v[100:103]
	v_mfma_f32_16x16x32_bf16 v[96:99], v[180:183], v[196:199], v[96:99]
	v_mfma_f32_16x16x32_bf16 v[84:87], v[172:175], v[204:207], v[84:87]
	v_mfma_f32_16x16x32_bf16 v[80:83], v[180:183], v[204:207], v[80:83]
	v_mfma_f32_16x16x32_bf16 v[68:71], v[172:175], v[212:215], v[68:71]
	v_mfma_f32_16x16x32_bf16 v[64:67], v[180:183], v[212:215], v[64:67]
	s_barrier
	ds_read_b128 v[184:187], v155 offset:49152
	ds_read_b128 v[188:191], v155 offset:50176
	ds_read_b128 v[192:195], v155 offset:51200
	ds_read_b128 v[196:199], v155 offset:52224
	ds_read_b128 v[200:203], v155 offset:53248
	ds_read_b128 v[204:207], v155 offset:54272
	ds_read_b128 v[208:211], v155 offset:55296
	ds_read_b128 v[212:215], v155 offset:56320
	s_setprio 0
	s_add_i32 s44, s44, s33
	s_mov_b32 m0, s44
	v_lshl_add_u64 v[148:149], v[148:149], 0, s[22:23]
	global_load_lds_dwordx4 v[148:149], off
	s_add_i32 m0, s44, 0x2000
	s_add_u32 s44, s48, 0x20080
	v_lshl_add_u64 v[148:149], v[216:217], 0, s[22:23]
	s_addc_u32 s45, s49, 0
	s_add_i32 s48, s68, s33
	global_load_lds_dwordx4 v[148:149], off
	s_mov_b32 m0, s48
	v_lshl_add_u64 v[148:149], s[44:45], 0, v[132:133]
	global_load_lds_dwordx4 v[148:149], off
	s_add_i32 m0, s48, 0x2000
	v_lshl_add_u64 v[148:149], s[44:45], 0, v[128:129]
	global_load_lds_dwordx4 v[148:149], off
	s_mov_b32 m0, s57
	v_lshl_add_u64 v[148:149], v[220:221], 0, s[22:23]
	global_load_lds_dwordx4 v[148:149], off
	s_mov_b32 m0, s58
	v_lshl_add_u64 v[148:149], v[224:225], 0, s[24:25]
	global_load_lds_dwordx4 v[148:149], off
	s_setprio 1
	s_waitcnt vmcnt(8) lgkmcnt(0)
	s_barrier
	v_mfma_f32_16x16x32_bf16 v[60:63], v[144:147], v[184:187], v[60:63]
	v_mfma_f32_16x16x32_bf16 v[56:59], v[160:163], v[184:187], v[56:59]
	v_mfma_f32_16x16x32_bf16 v[44:47], v[144:147], v[192:195], v[44:47]
	v_mfma_f32_16x16x32_bf16 v[40:43], v[160:163], v[192:195], v[40:43]
	v_mfma_f32_16x16x32_bf16 v[28:31], v[144:147], v[200:203], v[28:31]
	v_mfma_f32_16x16x32_bf16 v[24:27], v[160:163], v[200:203], v[24:27]
	v_mfma_f32_16x16x32_bf16 v[12:15], v[144:147], v[208:211], v[12:15]
	v_mfma_f32_16x16x32_bf16 v[8:11], v[160:163], v[208:211], v[8:11]
	v_mfma_f32_16x16x32_bf16 v[60:63], v[156:159], v[188:191], v[60:63]
	v_mfma_f32_16x16x32_bf16 v[56:59], v[164:167], v[188:191], v[56:59]
	v_mfma_f32_16x16x32_bf16 v[44:47], v[156:159], v[196:199], v[44:47]
	v_mfma_f32_16x16x32_bf16 v[40:43], v[164:167], v[196:199], v[40:43]
	v_mfma_f32_16x16x32_bf16 v[28:31], v[156:159], v[204:207], v[28:31]
	v_mfma_f32_16x16x32_bf16 v[24:27], v[164:167], v[204:207], v[24:27]
	v_mfma_f32_16x16x32_bf16 v[12:15], v[156:159], v[212:215], v[12:15]
	v_mfma_f32_16x16x32_bf16 v[8:11], v[164:167], v[212:215], v[8:11]
	v_mfma_f32_16x16x32_bf16 v[52:55], v[168:171], v[184:187], v[52:55]
	v_mfma_f32_16x16x32_bf16 v[48:51], v[176:179], v[184:187], v[48:51]
	v_mfma_f32_16x16x32_bf16 v[36:39], v[168:171], v[192:195], v[36:39]
	v_mfma_f32_16x16x32_bf16 v[32:35], v[176:179], v[192:195], v[32:35]
	v_mfma_f32_16x16x32_bf16 v[20:23], v[168:171], v[200:203], v[20:23]
	v_mfma_f32_16x16x32_bf16 v[16:19], v[176:179], v[200:203], v[16:19]
	v_mfma_f32_16x16x32_bf16 v[4:7], v[168:171], v[208:211], v[4:7]
	v_mfma_f32_16x16x32_bf16 v[0:3], v[176:179], v[208:211], v[0:3]
	v_mfma_f32_16x16x32_bf16 v[52:55], v[172:175], v[188:191], v[52:55]
	v_mfma_f32_16x16x32_bf16 v[48:51], v[180:183], v[188:191], v[48:51]
	v_mfma_f32_16x16x32_bf16 v[36:39], v[172:175], v[196:199], v[36:39]
	v_mfma_f32_16x16x32_bf16 v[32:35], v[180:183], v[196:199], v[32:35]
	v_mfma_f32_16x16x32_bf16 v[20:23], v[172:175], v[204:207], v[20:23]
	v_mfma_f32_16x16x32_bf16 v[16:19], v[180:183], v[204:207], v[16:19]
	v_mfma_f32_16x16x32_bf16 v[4:7], v[172:175], v[212:215], v[4:7]
	v_mfma_f32_16x16x32_bf16 v[0:3], v[180:183], v[212:215], v[0:3]
	s_barrier
	s_setprio 0
	s_add_i32 s74, s74, 2
	s_add_u32 s51, s51, 0x100
	s_addc_u32 s73, s73, 0
	s_cmp_gt_u32 s74, 5
	s_mov_b64 s[44:45], s[46:47]
.LBB0_393:
	ds_read_b128 v[144:147], v153
	ds_read_b128 v[156:159], v153 offset:1024
	ds_read_b128 v[160:163], v153 offset:2048
	ds_read_b128 v[164:167], v153 offset:3072
	ds_read_b128 v[168:171], v154
	ds_read_b128 v[172:175], v154 offset:1024
	ds_read_b128 v[176:179], v154 offset:2048
	ds_read_b128 v[180:183], v154 offset:3072
	s_add_u32 s46, s44, 0x100
	s_addc_u32 s47, s45, 0
	s_cmp_eq_u32 s74, 4
	s_cselect_b32 s77, s67, s47
	s_cselect_b32 s76, s72, s46
	s_cselect_b32 s49, s39, s73
	s_cselect_b32 s48, s50, s51
	v_lshl_add_u64 v[148:149], s[44:45], 0, v[136:137]
	s_add_i32 m0, s52, 0xc000
	ds_read_b128 v[184:187], v155
	ds_read_b128 v[188:191], v155 offset:1024
	ds_read_b128 v[192:195], v155 offset:2048
	ds_read_b128 v[196:199], v155 offset:3072
	ds_read_b128 v[200:203], v155 offset:4096
	ds_read_b128 v[204:207], v155 offset:5120
	ds_read_b128 v[208:211], v155 offset:6144
	ds_read_b128 v[212:215], v155 offset:7168
	global_load_lds_dwordx4 v[148:149], off
	s_add_i32 m0, s52, 0xe000
	v_lshl_add_u64 v[148:149], s[44:45], 0, v[138:139]
	global_load_lds_dwordx4 v[148:149], off
	s_setprio 1
	s_waitcnt vmcnt(8) lgkmcnt(0)
	s_barrier
	v_mfma_f32_16x16x32_bf16 v[124:127], v[144:147], v[184:187], v[124:127]
	v_mfma_f32_16x16x32_bf16 v[120:123], v[160:163], v[184:187], v[120:123]
	v_mfma_f32_16x16x32_bf16 v[108:111], v[144:147], v[192:195], v[108:111]
	v_mfma_f32_16x16x32_bf16 v[104:107], v[160:163], v[192:195], v[104:107]
	v_mfma_f32_16x16x32_bf16 v[92:95], v[144:147], v[200:203], v[92:95]
	v_mfma_f32_16x16x32_bf16 v[88:91], v[160:163], v[200:203], v[88:91]
	v_mfma_f32_16x16x32_bf16 v[76:79], v[144:147], v[208:211], v[76:79]
	v_mfma_f32_16x16x32_bf16 v[72:75], v[160:163], v[208:211], v[72:75]
	v_mfma_f32_16x16x32_bf16 v[124:127], v[156:159], v[188:191], v[124:127]
	v_mfma_f32_16x16x32_bf16 v[120:123], v[164:167], v[188:191], v[120:123]
	v_mfma_f32_16x16x32_bf16 v[108:111], v[156:159], v[196:199], v[108:111]
	v_mfma_f32_16x16x32_bf16 v[104:107], v[164:167], v[196:199], v[104:107]
	v_mfma_f32_16x16x32_bf16 v[92:95], v[156:159], v[204:207], v[92:95]
	v_mfma_f32_16x16x32_bf16 v[88:91], v[164:167], v[204:207], v[88:91]
	v_mfma_f32_16x16x32_bf16 v[76:79], v[156:159], v[212:215], v[76:79]
	v_mfma_f32_16x16x32_bf16 v[72:75], v[164:167], v[212:215], v[72:75]
	v_mfma_f32_16x16x32_bf16 v[116:119], v[168:171], v[184:187], v[116:119]
	v_mfma_f32_16x16x32_bf16 v[112:115], v[176:179], v[184:187], v[112:115]
	v_mfma_f32_16x16x32_bf16 v[100:103], v[168:171], v[192:195], v[100:103]
	v_mfma_f32_16x16x32_bf16 v[96:99], v[176:179], v[192:195], v[96:99]
	v_mfma_f32_16x16x32_bf16 v[84:87], v[168:171], v[200:203], v[84:87]
	v_mfma_f32_16x16x32_bf16 v[80:83], v[176:179], v[200:203], v[80:83]
	v_mfma_f32_16x16x32_bf16 v[68:71], v[168:171], v[208:211], v[68:71]
	v_mfma_f32_16x16x32_bf16 v[64:67], v[176:179], v[208:211], v[64:67]
	v_mfma_f32_16x16x32_bf16 v[116:119], v[172:175], v[188:191], v[116:119]
	v_mfma_f32_16x16x32_bf16 v[112:115], v[180:183], v[188:191], v[112:115]
	v_mfma_f32_16x16x32_bf16 v[100:103], v[172:175], v[196:199], v[100:103]
	v_mfma_f32_16x16x32_bf16 v[96:99], v[180:183], v[196:199], v[96:99]
	v_mfma_f32_16x16x32_bf16 v[84:87], v[172:175], v[204:207], v[84:87]
	v_mfma_f32_16x16x32_bf16 v[80:83], v[180:183], v[204:207], v[80:83]
	v_mfma_f32_16x16x32_bf16 v[68:71], v[172:175], v[212:215], v[68:71]
	v_mfma_f32_16x16x32_bf16 v[64:67], v[180:183], v[212:215], v[64:67]
	s_barrier
	ds_read_b128 v[184:187], v155 offset:16384
	ds_read_b128 v[188:191], v155 offset:17408
	ds_read_b128 v[192:195], v155 offset:18432
	ds_read_b128 v[196:199], v155 offset:19456
	ds_read_b128 v[200:203], v155 offset:20480
	ds_read_b128 v[204:207], v155 offset:21504
	ds_read_b128 v[208:211], v155 offset:22528
	ds_read_b128 v[212:215], v155 offset:23552
	s_setprio 0
	s_add_i32 s44, s61, s33
	s_mov_b32 m0, s44
	v_lshl_add_u64 v[148:149], s[48:49], 0, v[132:133]
	global_load_lds_dwordx4 v[148:149], off
	s_add_i32 m0, s44, 0x2000
	s_add_u32 s44, s48, 0x20000
	v_lshl_add_u64 v[216:217], s[48:49], 0, v[128:129]
	s_addc_u32 s45, s49, 0
	s_add_i32 s68, s62, s33
	global_load_lds_dwordx4 v[216:217], off
	v_lshl_add_u64 v[220:221], s[44:45], 0, v[132:133]
	s_mov_b32 m0, s68
	v_lshl_add_u64 v[224:225], s[76:77], 0, v[130:131]
	global_load_lds_dwordx4 v[220:221], off
	v_lshl_add_u64 v[220:221], s[44:45], 0, v[128:129]
	s_add_i32 m0, s68, 0x2000
	v_lshl_add_u64 v[226:227], v[224:225], 0, s[8:9]
	global_load_lds_dwordx4 v[220:221], off
	s_mov_b32 m0, s52
	v_lshl_add_u64 v[220:221], s[76:77], 0, v[134:135]
	global_load_lds_dwordx4 v[220:221], off
	s_mov_b32 m0, s53
	s_nop 0
	global_load_lds_dwordx4 v[226:227], off
	s_setprio 1
	s_waitcnt vmcnt(8) lgkmcnt(0)
	s_barrier
	v_mfma_f32_16x16x32_bf16 v[60:63], v[144:147], v[184:187], v[60:63]
	v_mfma_f32_16x16x32_bf16 v[56:59], v[160:163], v[184:187], v[56:59]
	v_mfma_f32_16x16x32_bf16 v[44:47], v[144:147], v[192:195], v[44:47]
	v_mfma_f32_16x16x32_bf16 v[40:43], v[160:163], v[192:195], v[40:43]
	v_mfma_f32_16x16x32_bf16 v[28:31], v[144:147], v[200:203], v[28:31]
	v_mfma_f32_16x16x32_bf16 v[24:27], v[160:163], v[200:203], v[24:27]
	v_mfma_f32_16x16x32_bf16 v[12:15], v[144:147], v[208:211], v[12:15]
	v_mfma_f32_16x16x32_bf16 v[8:11], v[160:163], v[208:211], v[8:11]
	v_mfma_f32_16x16x32_bf16 v[60:63], v[156:159], v[188:191], v[60:63]
	v_mfma_f32_16x16x32_bf16 v[56:59], v[164:167], v[188:191], v[56:59]
	v_mfma_f32_16x16x32_bf16 v[44:47], v[156:159], v[196:199], v[44:47]
	v_mfma_f32_16x16x32_bf16 v[40:43], v[164:167], v[196:199], v[40:43]
	v_mfma_f32_16x16x32_bf16 v[28:31], v[156:159], v[204:207], v[28:31]
	v_mfma_f32_16x16x32_bf16 v[24:27], v[164:167], v[204:207], v[24:27]
	v_mfma_f32_16x16x32_bf16 v[12:15], v[156:159], v[212:215], v[12:15]
	v_mfma_f32_16x16x32_bf16 v[8:11], v[164:167], v[212:215], v[8:11]
	v_mfma_f32_16x16x32_bf16 v[52:55], v[168:171], v[184:187], v[52:55]
	v_mfma_f32_16x16x32_bf16 v[48:51], v[176:179], v[184:187], v[48:51]
	v_mfma_f32_16x16x32_bf16 v[36:39], v[168:171], v[192:195], v[36:39]
	v_mfma_f32_16x16x32_bf16 v[32:35], v[176:179], v[192:195], v[32:35]
	v_mfma_f32_16x16x32_bf16 v[20:23], v[168:171], v[200:203], v[20:23]
	v_mfma_f32_16x16x32_bf16 v[16:19], v[176:179], v[200:203], v[16:19]
	v_mfma_f32_16x16x32_bf16 v[4:7], v[168:171], v[208:211], v[4:7]
	v_mfma_f32_16x16x32_bf16 v[0:3], v[176:179], v[208:211], v[0:3]
	v_mfma_f32_16x16x32_bf16 v[52:55], v[172:175], v[188:191], v[52:55]
	v_mfma_f32_16x16x32_bf16 v[48:51], v[180:183], v[188:191], v[48:51]
	v_mfma_f32_16x16x32_bf16 v[36:39], v[172:175], v[196:199], v[36:39]
	v_mfma_f32_16x16x32_bf16 v[32:35], v[180:183], v[196:199], v[32:35]
	v_mfma_f32_16x16x32_bf16 v[20:23], v[172:175], v[204:207], v[20:23]
	v_mfma_f32_16x16x32_bf16 v[16:19], v[180:183], v[204:207], v[16:19]
	v_mfma_f32_16x16x32_bf16 v[4:7], v[172:175], v[212:215], v[4:7]
	v_mfma_f32_16x16x32_bf16 v[0:3], v[180:183], v[212:215], v[0:3]
	s_barrier
	s_setprio 0
	s_add_i32 s44, 0, 0x18000
	s_add_i32 s68, 0, 0x1c000
	v_add_u32_e32 v164, s44, v151
	v_add_u32_e32 v180, s68, v151
	ds_read_b128 v[144:147], v164
	ds_read_b128 v[156:159], v164 offset:1024
	ds_read_b128 v[160:163], v164 offset:2048
	ds_read_b128 v[164:167], v164 offset:3072
	ds_read_b128 v[168:171], v180
	ds_read_b128 v[172:175], v180 offset:1024
	ds_read_b128 v[176:179], v180 offset:2048
	ds_read_b128 v[180:183], v180 offset:3072
	s_mov_b32 m0, s54
	v_lshl_add_u64 v[226:227], v[220:221], 0, s[6:7]
	ds_read_b128 v[184:187], v155 offset:32768
	ds_read_b128 v[188:191], v155 offset:33792
	ds_read_b128 v[192:195], v155 offset:34816
	ds_read_b128 v[196:199], v155 offset:35840
	ds_read_b128 v[200:203], v155 offset:36864
	ds_read_b128 v[204:207], v155 offset:37888
	ds_read_b128 v[208:211], v155 offset:38912
	ds_read_b128 v[212:215], v155 offset:39936
	global_load_lds_dwordx4 v[226:227], off
	s_mov_b32 m0, s55
	v_lshl_add_u64 v[226:227], v[224:225], 0, s[12:13]
	global_load_lds_dwordx4 v[226:227], off
	s_setprio 1
	s_waitcnt vmcnt(8) lgkmcnt(0)
	s_barrier
	v_mfma_f32_16x16x32_bf16 v[124:127], v[144:147], v[184:187], v[124:127]
	v_mfma_f32_16x16x32_bf16 v[120:123], v[160:163], v[184:187], v[120:123]
	v_mfma_f32_16x16x32_bf16 v[108:111], v[144:147], v[192:195], v[108:111]
	v_mfma_f32_16x16x32_bf16 v[104:107], v[160:163], v[192:195], v[104:107]
	v_mfma_f32_16x16x32_bf16 v[92:95], v[144:147], v[200:203], v[92:95]
	v_mfma_f32_16x16x32_bf16 v[88:91], v[160:163], v[200:203], v[88:91]
	v_mfma_f32_16x16x32_bf16 v[76:79], v[144:147], v[208:211], v[76:79]
	v_mfma_f32_16x16x32_bf16 v[72:75], v[160:163], v[208:211], v[72:75]
	v_mfma_f32_16x16x32_bf16 v[124:127], v[156:159], v[188:191], v[124:127]
	v_mfma_f32_16x16x32_bf16 v[120:123], v[164:167], v[188:191], v[120:123]
	v_mfma_f32_16x16x32_bf16 v[108:111], v[156:159], v[196:199], v[108:111]
	v_mfma_f32_16x16x32_bf16 v[104:107], v[164:167], v[196:199], v[104:107]
	v_mfma_f32_16x16x32_bf16 v[92:95], v[156:159], v[204:207], v[92:95]
	v_mfma_f32_16x16x32_bf16 v[88:91], v[164:167], v[204:207], v[88:91]
	v_mfma_f32_16x16x32_bf16 v[76:79], v[156:159], v[212:215], v[76:79]
	v_mfma_f32_16x16x32_bf16 v[72:75], v[164:167], v[212:215], v[72:75]
	v_mfma_f32_16x16x32_bf16 v[116:119], v[168:171], v[184:187], v[116:119]
	v_mfma_f32_16x16x32_bf16 v[112:115], v[176:179], v[184:187], v[112:115]
	v_mfma_f32_16x16x32_bf16 v[100:103], v[168:171], v[192:195], v[100:103]
	v_mfma_f32_16x16x32_bf16 v[96:99], v[176:179], v[192:195], v[96:99]
	v_mfma_f32_16x16x32_bf16 v[84:87], v[168:171], v[200:203], v[84:87]
	v_mfma_f32_16x16x32_bf16 v[80:83], v[176:179], v[200:203], v[80:83]
	v_mfma_f32_16x16x32_bf16 v[68:71], v[168:171], v[208:211], v[68:71]
	v_mfma_f32_16x16x32_bf16 v[64:67], v[176:179], v[208:211], v[64:67]
	v_mfma_f32_16x16x32_bf16 v[116:119], v[172:175], v[188:191], v[116:119]
	v_mfma_f32_16x16x32_bf16 v[112:115], v[180:183], v[188:191], v[112:115]
	v_mfma_f32_16x16x32_bf16 v[100:103], v[172:175], v[196:199], v[100:103]
	v_mfma_f32_16x16x32_bf16 v[96:99], v[180:183], v[196:199], v[96:99]
	v_mfma_f32_16x16x32_bf16 v[84:87], v[172:175], v[204:207], v[84:87]
	v_mfma_f32_16x16x32_bf16 v[80:83], v[180:183], v[204:207], v[80:83]
	v_mfma_f32_16x16x32_bf16 v[68:71], v[172:175], v[212:215], v[68:71]
	v_mfma_f32_16x16x32_bf16 v[64:67], v[180:183], v[212:215], v[64:67]
	s_barrier
	ds_read_b128 v[184:187], v155 offset:49152
	ds_read_b128 v[188:191], v155 offset:50176
	ds_read_b128 v[192:195], v155 offset:51200
	ds_read_b128 v[196:199], v155 offset:52224
	ds_read_b128 v[200:203], v155 offset:53248
	ds_read_b128 v[204:207], v155 offset:54272
	ds_read_b128 v[208:211], v155 offset:55296
	ds_read_b128 v[212:215], v155 offset:56320
	s_setprio 0
	s_add_i32 s44, s44, s33
	s_mov_b32 m0, s44
	v_lshl_add_u64 v[148:149], v[148:149], 0, s[22:23]
	global_load_lds_dwordx4 v[148:149], off
	s_add_i32 m0, s44, 0x2000
	s_add_u32 s44, s48, 0x20080
	v_lshl_add_u64 v[148:149], v[216:217], 0, s[22:23]
	s_addc_u32 s45, s49, 0
	s_add_i32 s48, s68, s33
	global_load_lds_dwordx4 v[148:149], off
	s_mov_b32 m0, s48
	v_lshl_add_u64 v[148:149], s[44:45], 0, v[132:133]
	global_load_lds_dwordx4 v[148:149], off
	s_add_i32 m0, s48, 0x2000
	v_lshl_add_u64 v[148:149], s[44:45], 0, v[128:129]
	global_load_lds_dwordx4 v[148:149], off
	s_mov_b32 m0, s57
	v_lshl_add_u64 v[148:149], v[220:221], 0, s[22:23]
	global_load_lds_dwordx4 v[148:149], off
	s_mov_b32 m0, s58
	v_lshl_add_u64 v[148:149], v[224:225], 0, s[24:25]
	global_load_lds_dwordx4 v[148:149], off
	s_setprio 1
	s_waitcnt vmcnt(8) lgkmcnt(0)
	s_barrier
	v_mfma_f32_16x16x32_bf16 v[60:63], v[144:147], v[184:187], v[60:63]
	v_mfma_f32_16x16x32_bf16 v[56:59], v[160:163], v[184:187], v[56:59]
	v_mfma_f32_16x16x32_bf16 v[44:47], v[144:147], v[192:195], v[44:47]
	v_mfma_f32_16x16x32_bf16 v[40:43], v[160:163], v[192:195], v[40:43]
	v_mfma_f32_16x16x32_bf16 v[28:31], v[144:147], v[200:203], v[28:31]
	v_mfma_f32_16x16x32_bf16 v[24:27], v[160:163], v[200:203], v[24:27]
	v_mfma_f32_16x16x32_bf16 v[12:15], v[144:147], v[208:211], v[12:15]
	v_mfma_f32_16x16x32_bf16 v[8:11], v[160:163], v[208:211], v[8:11]
	v_mfma_f32_16x16x32_bf16 v[60:63], v[156:159], v[188:191], v[60:63]
	v_mfma_f32_16x16x32_bf16 v[56:59], v[164:167], v[188:191], v[56:59]
	v_mfma_f32_16x16x32_bf16 v[44:47], v[156:159], v[196:199], v[44:47]
	v_mfma_f32_16x16x32_bf16 v[40:43], v[164:167], v[196:199], v[40:43]
	v_mfma_f32_16x16x32_bf16 v[28:31], v[156:159], v[204:207], v[28:31]
	v_mfma_f32_16x16x32_bf16 v[24:27], v[164:167], v[204:207], v[24:27]
	v_mfma_f32_16x16x32_bf16 v[12:15], v[156:159], v[212:215], v[12:15]
	v_mfma_f32_16x16x32_bf16 v[8:11], v[164:167], v[212:215], v[8:11]
	v_mfma_f32_16x16x32_bf16 v[52:55], v[168:171], v[184:187], v[52:55]
	v_mfma_f32_16x16x32_bf16 v[48:51], v[176:179], v[184:187], v[48:51]
	v_mfma_f32_16x16x32_bf16 v[36:39], v[168:171], v[192:195], v[36:39]
	v_mfma_f32_16x16x32_bf16 v[32:35], v[176:179], v[192:195], v[32:35]
	v_mfma_f32_16x16x32_bf16 v[20:23], v[168:171], v[200:203], v[20:23]
	v_mfma_f32_16x16x32_bf16 v[16:19], v[176:179], v[200:203], v[16:19]
	v_mfma_f32_16x16x32_bf16 v[4:7], v[168:171], v[208:211], v[4:7]
	v_mfma_f32_16x16x32_bf16 v[0:3], v[176:179], v[208:211], v[0:3]
	v_mfma_f32_16x16x32_bf16 v[52:55], v[172:175], v[188:191], v[52:55]
	v_mfma_f32_16x16x32_bf16 v[48:51], v[180:183], v[188:191], v[48:51]
	v_mfma_f32_16x16x32_bf16 v[36:39], v[172:175], v[196:199], v[36:39]
	v_mfma_f32_16x16x32_bf16 v[32:35], v[180:183], v[196:199], v[32:35]
	v_mfma_f32_16x16x32_bf16 v[20:23], v[172:175], v[204:207], v[20:23]
	v_mfma_f32_16x16x32_bf16 v[16:19], v[180:183], v[204:207], v[16:19]
	v_mfma_f32_16x16x32_bf16 v[4:7], v[172:175], v[212:215], v[4:7]
	v_mfma_f32_16x16x32_bf16 v[0:3], v[180:183], v[212:215], v[0:3]
	s_barrier
	s_setprio 0
	s_add_i32 s74, s74, 2
	s_add_u32 s51, s51, 0x100
	s_addc_u32 s73, s73, 0
	s_cmp_gt_u32 s74, 5
	s_mov_b64 s[44:45], s[46:47]
	s_cbranch_scc0 .LBB0_393
	s_and_b64 vcc, exec, s[36:37]
	s_cbranch_vccz .LBB0_396
	s_barrier

.LBB0_465:
	s_lshl_b32 s42, s73, 8
	s_ashr_i32 s43, s42, 31
	s_lshl_b64 s[42:43], s[42:43], 11
	s_add_u32 s42, s10, s42
	s_addc_u32 s43, s11, s43
	s_and_b64 s[44:45], s[4:5], exec
	s_cselect_b32 s47, s43, s49
	s_cselect_b32 s74, s42, s48
	s_ashr_i32 s41, s40, 31
	s_lshl_b64 s[44:45], s[40:41], 19
	s_add_u32 s44, s33, s44
	s_addc_u32 s45, s34, s45
	s_and_b64 s[50:51], s[4:5], exec
	s_cselect_b32 s41, s45, s53
	s_cselect_b32 s50, s44, s52
	s_add_u32 s51, s52, 0x100
	s_addc_u32 s75, s53, 0
	s_mov_b32 s76, -2
	s_waitcnt lgkmcnt(0)
	s_waitcnt vmcnt(0)
	s_waitcnt lgkmcnt(0)
	ds_read_b128 v[144:147], v151
	ds_read_b128 v[156:159], v151 offset:1024
	ds_read_b128 v[160:163], v151 offset:2048
	ds_read_b128 v[164:167], v151 offset:3072
	ds_read_b128 v[168:171], v152
	ds_read_b128 v[172:175], v152 offset:1024
	ds_read_b128 v[176:179], v152 offset:2048
	ds_read_b128 v[180:183], v152 offset:3072
	s_add_u32 s52, s48, 0x100
	s_addc_u32 s53, s49, 0
	s_cmp_eq_u32 s76, 12
	s_cselect_b32 s79, s47, s53
	s_cselect_b32 s78, s74, s52
	s_cselect_b32 s55, s41, s75
	s_cselect_b32 s54, s50, s51
	v_lshl_add_u64 v[216:217], s[48:49], 0, v[136:137]
	s_add_i32 m0, s56, 0xc000
	ds_read_b128 v[184:187], v153
	ds_read_b128 v[188:191], v153 offset:1024
	ds_read_b128 v[192:195], v153 offset:2048
	ds_read_b128 v[196:199], v153 offset:3072
	ds_read_b128 v[200:203], v153 offset:4096
	ds_read_b128 v[204:207], v153 offset:5120
	ds_read_b128 v[208:211], v153 offset:6144
	ds_read_b128 v[212:215], v153 offset:7168
	global_load_lds_dwordx4 v[216:217], off
	s_add_i32 m0, s56, 0xe000
	v_lshl_add_u64 v[216:217], s[48:49], 0, v[138:139]
	global_load_lds_dwordx4 v[216:217], off
	s_setprio 1
	s_waitcnt vmcnt(8) lgkmcnt(0)
	s_barrier
	v_mfma_f32_16x16x32_bf16 v[124:127], v[144:147], v[184:187], 0
	v_mfma_f32_16x16x32_bf16 v[120:123], v[160:163], v[184:187], 0
	v_mfma_f32_16x16x32_bf16 v[108:111], v[144:147], v[192:195], 0
	v_mfma_f32_16x16x32_bf16 v[104:107], v[160:163], v[192:195], 0
	v_mfma_f32_16x16x32_bf16 v[92:95], v[144:147], v[200:203], 0
	v_mfma_f32_16x16x32_bf16 v[88:91], v[160:163], v[200:203], 0
	v_mfma_f32_16x16x32_bf16 v[76:79], v[144:147], v[208:211], 0
	v_mfma_f32_16x16x32_bf16 v[72:75], v[160:163], v[208:211], 0
	v_mfma_f32_16x16x32_bf16 v[124:127], v[156:159], v[188:191], v[124:127]
	v_mfma_f32_16x16x32_bf16 v[120:123], v[164:167], v[188:191], v[120:123]
	v_mfma_f32_16x16x32_bf16 v[108:111], v[156:159], v[196:199], v[108:111]
	v_mfma_f32_16x16x32_bf16 v[104:107], v[164:167], v[196:199], v[104:107]
	v_mfma_f32_16x16x32_bf16 v[92:95], v[156:159], v[204:207], v[92:95]
	v_mfma_f32_16x16x32_bf16 v[88:91], v[164:167], v[204:207], v[88:91]
	v_mfma_f32_16x16x32_bf16 v[76:79], v[156:159], v[212:215], v[76:79]
	v_mfma_f32_16x16x32_bf16 v[72:75], v[164:167], v[212:215], v[72:75]
	v_mfma_f32_16x16x32_bf16 v[116:119], v[168:171], v[184:187], 0
	v_mfma_f32_16x16x32_bf16 v[112:115], v[176:179], v[184:187], 0
	v_mfma_f32_16x16x32_bf16 v[100:103], v[168:171], v[192:195], 0
	v_mfma_f32_16x16x32_bf16 v[96:99], v[176:179], v[192:195], 0
	v_mfma_f32_16x16x32_bf16 v[84:87], v[168:171], v[200:203], 0
	v_mfma_f32_16x16x32_bf16 v[80:83], v[176:179], v[200:203], 0
	v_mfma_f32_16x16x32_bf16 v[68:71], v[168:171], v[208:211], 0
	v_mfma_f32_16x16x32_bf16 v[64:67], v[176:179], v[208:211], 0
	v_mfma_f32_16x16x32_bf16 v[116:119], v[172:175], v[188:191], v[116:119]
	v_mfma_f32_16x16x32_bf16 v[112:115], v[180:183], v[188:191], v[112:115]
	v_mfma_f32_16x16x32_bf16 v[100:103], v[172:175], v[196:199], v[100:103]
	v_mfma_f32_16x16x32_bf16 v[96:99], v[180:183], v[196:199], v[96:99]
	v_mfma_f32_16x16x32_bf16 v[84:87], v[172:175], v[204:207], v[84:87]
	v_mfma_f32_16x16x32_bf16 v[80:83], v[180:183], v[204:207], v[80:83]
	v_mfma_f32_16x16x32_bf16 v[68:71], v[172:175], v[212:215], v[68:71]
	v_mfma_f32_16x16x32_bf16 v[64:67], v[180:183], v[212:215], v[64:67]
	s_barrier
	ds_read_b128 v[184:187], v153 offset:16384
	ds_read_b128 v[188:191], v153 offset:17408
	ds_read_b128 v[192:195], v153 offset:18432
	ds_read_b128 v[196:199], v153 offset:19456
	ds_read_b128 v[200:203], v153 offset:20480
	ds_read_b128 v[204:207], v153 offset:21504
	ds_read_b128 v[208:211], v153 offset:22528
	ds_read_b128 v[212:215], v153 offset:23552
	s_setprio 0
	s_add_i32 s48, s67, s35
	s_mov_b32 m0, s48
	v_lshl_add_u64 v[216:217], s[54:55], 0, v[130:131]
	global_load_lds_dwordx4 v[216:217], off
	s_add_i32 m0, s48, 0x2000
	s_add_u32 s48, s54, 0x40000
	v_lshl_add_u64 v[220:221], s[54:55], 0, v[134:135]
	s_addc_u32 s49, s55, 0
	s_add_i32 s68, s72, s35
	global_load_lds_dwordx4 v[220:221], off
	v_lshl_add_u64 v[224:225], s[48:49], 0, v[130:131]
	s_mov_b32 m0, s68
	v_lshl_add_u64 v[226:227], s[78:79], 0, v[132:133]
	global_load_lds_dwordx4 v[224:225], off
	v_lshl_add_u64 v[224:225], s[48:49], 0, v[134:135]
	s_add_i32 m0, s68, 0x2000
	v_lshl_add_u64 v[228:229], v[226:227], 0, s[12:13]
	global_load_lds_dwordx4 v[224:225], off
	s_mov_b32 m0, s56
	v_lshl_add_u64 v[224:225], s[78:79], 0, v[128:129]
	global_load_lds_dwordx4 v[224:225], off
	s_mov_b32 m0, s57
	s_nop 0
	global_load_lds_dwordx4 v[228:229], off
	s_setprio 1
	s_waitcnt vmcnt(8) lgkmcnt(0)
	s_barrier
	v_mfma_f32_16x16x32_bf16 v[60:63], v[144:147], v[184:187], 0
	v_mfma_f32_16x16x32_bf16 v[56:59], v[160:163], v[184:187], 0
	v_mfma_f32_16x16x32_bf16 v[44:47], v[144:147], v[192:195], 0
	v_mfma_f32_16x16x32_bf16 v[40:43], v[160:163], v[192:195], 0
	v_mfma_f32_16x16x32_bf16 v[28:31], v[144:147], v[200:203], 0
	v_mfma_f32_16x16x32_bf16 v[24:27], v[160:163], v[200:203], 0
	v_mfma_f32_16x16x32_bf16 v[12:15], v[144:147], v[208:211], 0
	v_mfma_f32_16x16x32_bf16 v[8:11], v[160:163], v[208:211], 0
	v_mfma_f32_16x16x32_bf16 v[60:63], v[156:159], v[188:191], v[60:63]
	v_mfma_f32_16x16x32_bf16 v[56:59], v[164:167], v[188:191], v[56:59]
	v_mfma_f32_16x16x32_bf16 v[44:47], v[156:159], v[196:199], v[44:47]
	v_mfma_f32_16x16x32_bf16 v[40:43], v[164:167], v[196:199], v[40:43]
	v_mfma_f32_16x16x32_bf16 v[28:31], v[156:159], v[204:207], v[28:31]
	v_mfma_f32_16x16x32_bf16 v[24:27], v[164:167], v[204:207], v[24:27]
	v_mfma_f32_16x16x32_bf16 v[12:15], v[156:159], v[212:215], v[12:15]
	v_mfma_f32_16x16x32_bf16 v[8:11], v[164:167], v[212:215], v[8:11]
	v_mfma_f32_16x16x32_bf16 v[52:55], v[168:171], v[184:187], 0
	v_mfma_f32_16x16x32_bf16 v[48:51], v[176:179], v[184:187], 0
	v_mfma_f32_16x16x32_bf16 v[36:39], v[168:171], v[192:195], 0
	v_mfma_f32_16x16x32_bf16 v[32:35], v[176:179], v[192:195], 0
	v_mfma_f32_16x16x32_bf16 v[20:23], v[168:171], v[200:203], 0
	v_mfma_f32_16x16x32_bf16 v[16:19], v[176:179], v[200:203], 0
	v_mfma_f32_16x16x32_bf16 v[4:7], v[168:171], v[208:211], 0
	v_mfma_f32_16x16x32_bf16 v[0:3], v[176:179], v[208:211], 0
	v_mfma_f32_16x16x32_bf16 v[52:55], v[172:175], v[188:191], v[52:55]
	v_mfma_f32_16x16x32_bf16 v[48:51], v[180:183], v[188:191], v[48:51]
	v_mfma_f32_16x16x32_bf16 v[36:39], v[172:175], v[196:199], v[36:39]
	v_mfma_f32_16x16x32_bf16 v[32:35], v[180:183], v[196:199], v[32:35]
	v_mfma_f32_16x16x32_bf16 v[20:23], v[172:175], v[204:207], v[20:23]
	v_mfma_f32_16x16x32_bf16 v[16:19], v[180:183], v[204:207], v[16:19]
	v_mfma_f32_16x16x32_bf16 v[4:7], v[172:175], v[212:215], v[4:7]
	v_mfma_f32_16x16x32_bf16 v[0:3], v[180:183], v[212:215], v[0:3]
	s_barrier
	s_setprio 0
	s_add_i32 s48, 0, 0x18000
	v_add_u32_e32 v155, s48, v149
	s_add_i32 s68, 0, 0x1c000
	ds_read_b128 v[144:147], v155
	ds_read_b128 v[156:159], v155 offset:1024
	ds_read_b128 v[160:163], v155 offset:2048
	ds_read_b128 v[164:167], v155 offset:3072
	v_add_u32_e32 v155, s68, v149
	ds_read_b128 v[168:171], v155
	ds_read_b128 v[172:175], v155 offset:1024
	ds_read_b128 v[176:179], v155 offset:2048
	ds_read_b128 v[180:183], v155 offset:3072
	s_mov_b32 m0, s58
	v_lshl_add_u64 v[228:229], v[224:225], 0, s[8:9]
	ds_read_b128 v[184:187], v153 offset:32768
	ds_read_b128 v[188:191], v153 offset:33792
	ds_read_b128 v[192:195], v153 offset:34816
	ds_read_b128 v[196:199], v153 offset:35840
	ds_read_b128 v[200:203], v153 offset:36864
	ds_read_b128 v[204:207], v153 offset:37888
	ds_read_b128 v[208:211], v153 offset:38912
	ds_read_b128 v[212:215], v153 offset:39936
	global_load_lds_dwordx4 v[228:229], off
	s_mov_b32 m0, s59
	v_lshl_add_u64 v[228:229], v[226:227], 0, s[14:15]
	global_load_lds_dwordx4 v[228:229], off
	s_setprio 1
	s_waitcnt vmcnt(8) lgkmcnt(0)
	s_barrier
	v_mfma_f32_16x16x32_bf16 v[124:127], v[144:147], v[184:187], v[124:127]
	v_mfma_f32_16x16x32_bf16 v[120:123], v[160:163], v[184:187], v[120:123]
	v_mfma_f32_16x16x32_bf16 v[108:111], v[144:147], v[192:195], v[108:111]
	v_mfma_f32_16x16x32_bf16 v[104:107], v[160:163], v[192:195], v[104:107]
	v_mfma_f32_16x16x32_bf16 v[92:95], v[144:147], v[200:203], v[92:95]
	v_mfma_f32_16x16x32_bf16 v[88:91], v[160:163], v[200:203], v[88:91]
	v_mfma_f32_16x16x32_bf16 v[76:79], v[144:147], v[208:211], v[76:79]
	v_mfma_f32_16x16x32_bf16 v[72:75], v[160:163], v[208:211], v[72:75]
	v_mfma_f32_16x16x32_bf16 v[124:127], v[156:159], v[188:191], v[124:127]
	v_mfma_f32_16x16x32_bf16 v[120:123], v[164:167], v[188:191], v[120:123]
	v_mfma_f32_16x16x32_bf16 v[108:111], v[156:159], v[196:199], v[108:111]
	v_mfma_f32_16x16x32_bf16 v[104:107], v[164:167], v[196:199], v[104:107]
	v_mfma_f32_16x16x32_bf16 v[92:95], v[156:159], v[204:207], v[92:95]
	v_mfma_f32_16x16x32_bf16 v[88:91], v[164:167], v[204:207], v[88:91]
	v_mfma_f32_16x16x32_bf16 v[76:79], v[156:159], v[212:215], v[76:79]
	v_mfma_f32_16x16x32_bf16 v[72:75], v[164:167], v[212:215], v[72:75]
	v_mfma_f32_16x16x32_bf16 v[116:119], v[168:171], v[184:187], v[116:119]
	v_mfma_f32_16x16x32_bf16 v[112:115], v[176:179], v[184:187], v[112:115]
	v_mfma_f32_16x16x32_bf16 v[100:103], v[168:171], v[192:195], v[100:103]
	v_mfma_f32_16x16x32_bf16 v[96:99], v[176:179], v[192:195], v[96:99]
	v_mfma_f32_16x16x32_bf16 v[84:87], v[168:171], v[200:203], v[84:87]
	v_mfma_f32_16x16x32_bf16 v[80:83], v[176:179], v[200:203], v[80:83]
	v_mfma_f32_16x16x32_bf16 v[68:71], v[168:171], v[208:211], v[68:71]
	v_mfma_f32_16x16x32_bf16 v[64:67], v[176:179], v[208:211], v[64:67]
	v_mfma_f32_16x16x32_bf16 v[116:119], v[172:175], v[188:191], v[116:119]
	v_mfma_f32_16x16x32_bf16 v[112:115], v[180:183], v[188:191], v[112:115]
	v_mfma_f32_16x16x32_bf16 v[100:103], v[172:175], v[196:199], v[100:103]
	v_mfma_f32_16x16x32_bf16 v[96:99], v[180:183], v[196:199], v[96:99]
	v_mfma_f32_16x16x32_bf16 v[84:87], v[172:175], v[204:207], v[84:87]
	v_mfma_f32_16x16x32_bf16 v[80:83], v[180:183], v[204:207], v[80:83]
	v_mfma_f32_16x16x32_bf16 v[68:71], v[172:175], v[212:215], v[68:71]
	v_mfma_f32_16x16x32_bf16 v[64:67], v[180:183], v[212:215], v[64:67]
	s_barrier
	ds_read_b128 v[184:187], v153 offset:49152
	ds_read_b128 v[188:191], v153 offset:50176
	ds_read_b128 v[192:195], v153 offset:51200
	ds_read_b128 v[196:199], v153 offset:52224
	ds_read_b128 v[200:203], v153 offset:53248
	ds_read_b128 v[204:207], v153 offset:54272
	ds_read_b128 v[208:211], v153 offset:55296
	ds_read_b128 v[212:215], v153 offset:56320
	s_setprio 0
	s_add_i32 s48, s48, s35
	s_mov_b32 m0, s48
	v_lshl_add_u64 v[216:217], v[216:217], 0, s[24:25]
	global_load_lds_dwordx4 v[216:217], off
	s_add_i32 m0, s48, 0x2000
	s_add_u32 s48, s54, 0x40080
	v_lshl_add_u64 v[216:217], v[220:221], 0, s[24:25]
	s_addc_u32 s49, s55, 0
	s_add_i32 s54, s68, s35
	global_load_lds_dwordx4 v[216:217], off
	s_mov_b32 m0, s54
	v_lshl_add_u64 v[216:217], s[48:49], 0, v[130:131]
	global_load_lds_dwordx4 v[216:217], off
	s_add_i32 m0, s54, 0x2000
	v_lshl_add_u64 v[216:217], s[48:49], 0, v[134:135]
	global_load_lds_dwordx4 v[216:217], off
	s_mov_b32 m0, s61
	v_lshl_add_u64 v[216:217], v[224:225], 0, s[24:25]
	global_load_lds_dwordx4 v[216:217], off
	s_mov_b32 m0, s62
	v_lshl_add_u64 v[216:217], v[226:227], 0, s[36:37]
	global_load_lds_dwordx4 v[216:217], off
	s_setprio 1
	s_waitcnt vmcnt(8) lgkmcnt(0)
	s_barrier
	v_mfma_f32_16x16x32_bf16 v[60:63], v[144:147], v[184:187], v[60:63]
	v_mfma_f32_16x16x32_bf16 v[56:59], v[160:163], v[184:187], v[56:59]
	v_mfma_f32_16x16x32_bf16 v[44:47], v[144:147], v[192:195], v[44:47]
	v_mfma_f32_16x16x32_bf16 v[40:43], v[160:163], v[192:195], v[40:43]
	v_mfma_f32_16x16x32_bf16 v[28:31], v[144:147], v[200:203], v[28:31]
	v_mfma_f32_16x16x32_bf16 v[24:27], v[160:163], v[200:203], v[24:27]
	v_mfma_f32_16x16x32_bf16 v[12:15], v[144:147], v[208:211], v[12:15]
	v_mfma_f32_16x16x32_bf16 v[8:11], v[160:163], v[208:211], v[8:11]
	v_mfma_f32_16x16x32_bf16 v[60:63], v[156:159], v[188:191], v[60:63]
	v_mfma_f32_16x16x32_bf16 v[56:59], v[164:167], v[188:191], v[56:59]
	v_mfma_f32_16x16x32_bf16 v[44:47], v[156:159], v[196:199], v[44:47]
	v_mfma_f32_16x16x32_bf16 v[40:43], v[164:167], v[196:199], v[40:43]
	v_mfma_f32_16x16x32_bf16 v[28:31], v[156:159], v[204:207], v[28:31]
	v_mfma_f32_16x16x32_bf16 v[24:27], v[164:167], v[204:207], v[24:27]
	v_mfma_f32_16x16x32_bf16 v[12:15], v[156:159], v[212:215], v[12:15]
	v_mfma_f32_16x16x32_bf16 v[8:11], v[164:167], v[212:215], v[8:11]
	v_mfma_f32_16x16x32_bf16 v[52:55], v[168:171], v[184:187], v[52:55]
	v_mfma_f32_16x16x32_bf16 v[48:51], v[176:179], v[184:187], v[48:51]
	v_mfma_f32_16x16x32_bf16 v[36:39], v[168:171], v[192:195], v[36:39]
	v_mfma_f32_16x16x32_bf16 v[32:35], v[176:179], v[192:195], v[32:35]
	v_mfma_f32_16x16x32_bf16 v[20:23], v[168:171], v[200:203], v[20:23]
	v_mfma_f32_16x16x32_bf16 v[16:19], v[176:179], v[200:203], v[16:19]
	v_mfma_f32_16x16x32_bf16 v[4:7], v[168:171], v[208:211], v[4:7]
	v_mfma_f32_16x16x32_bf16 v[0:3], v[176:179], v[208:211], v[0:3]
	v_mfma_f32_16x16x32_bf16 v[52:55], v[172:175], v[188:191], v[52:55]
	v_mfma_f32_16x16x32_bf16 v[48:51], v[180:183], v[188:191], v[48:51]
	v_mfma_f32_16x16x32_bf16 v[36:39], v[172:175], v[196:199], v[36:39]
	v_mfma_f32_16x16x32_bf16 v[32:35], v[180:183], v[196:199], v[32:35]
	v_mfma_f32_16x16x32_bf16 v[20:23], v[172:175], v[204:207], v[20:23]
	v_mfma_f32_16x16x32_bf16 v[16:19], v[180:183], v[204:207], v[16:19]
	v_mfma_f32_16x16x32_bf16 v[4:7], v[172:175], v[212:215], v[4:7]
	v_mfma_f32_16x16x32_bf16 v[0:3], v[180:183], v[212:215], v[0:3]
	s_barrier
	s_setprio 0
	s_add_i32 s76, s76, 2
	s_add_u32 s51, s51, 0x100
	s_addc_u32 s75, s75, 0
	s_cmp_gt_u32 s76, 13
	s_mov_b64 s[48:49], s[52:53]
.LBB0_466:
	ds_read_b128 v[144:147], v151
	ds_read_b128 v[156:159], v151 offset:1024
	ds_read_b128 v[160:163], v151 offset:2048
	ds_read_b128 v[164:167], v151 offset:3072
	ds_read_b128 v[168:171], v152
	ds_read_b128 v[172:175], v152 offset:1024
	ds_read_b128 v[176:179], v152 offset:2048
	ds_read_b128 v[180:183], v152 offset:3072
	s_add_u32 s52, s48, 0x100
	s_addc_u32 s53, s49, 0
	s_cmp_eq_u32 s76, 12
	s_cselect_b32 s79, s47, s53
	s_cselect_b32 s78, s74, s52
	s_cselect_b32 s55, s41, s75
	s_cselect_b32 s54, s50, s51
	v_lshl_add_u64 v[216:217], s[48:49], 0, v[136:137]
	s_add_i32 m0, s56, 0xc000
	ds_read_b128 v[184:187], v153
	ds_read_b128 v[188:191], v153 offset:1024
	ds_read_b128 v[192:195], v153 offset:2048
	ds_read_b128 v[196:199], v153 offset:3072
	ds_read_b128 v[200:203], v153 offset:4096
	ds_read_b128 v[204:207], v153 offset:5120
	ds_read_b128 v[208:211], v153 offset:6144
	ds_read_b128 v[212:215], v153 offset:7168
	global_load_lds_dwordx4 v[216:217], off
	s_add_i32 m0, s56, 0xe000
	v_lshl_add_u64 v[216:217], s[48:49], 0, v[138:139]
	global_load_lds_dwordx4 v[216:217], off
	s_setprio 1
	s_waitcnt vmcnt(8) lgkmcnt(0)
	s_barrier
	v_mfma_f32_16x16x32_bf16 v[124:127], v[144:147], v[184:187], v[124:127]
	v_mfma_f32_16x16x32_bf16 v[120:123], v[160:163], v[184:187], v[120:123]
	v_mfma_f32_16x16x32_bf16 v[108:111], v[144:147], v[192:195], v[108:111]
	v_mfma_f32_16x16x32_bf16 v[104:107], v[160:163], v[192:195], v[104:107]
	v_mfma_f32_16x16x32_bf16 v[92:95], v[144:147], v[200:203], v[92:95]
	v_mfma_f32_16x16x32_bf16 v[88:91], v[160:163], v[200:203], v[88:91]
	v_mfma_f32_16x16x32_bf16 v[76:79], v[144:147], v[208:211], v[76:79]
	v_mfma_f32_16x16x32_bf16 v[72:75], v[160:163], v[208:211], v[72:75]
	v_mfma_f32_16x16x32_bf16 v[124:127], v[156:159], v[188:191], v[124:127]
	v_mfma_f32_16x16x32_bf16 v[120:123], v[164:167], v[188:191], v[120:123]
	v_mfma_f32_16x16x32_bf16 v[108:111], v[156:159], v[196:199], v[108:111]
	v_mfma_f32_16x16x32_bf16 v[104:107], v[164:167], v[196:199], v[104:107]
	v_mfma_f32_16x16x32_bf16 v[92:95], v[156:159], v[204:207], v[92:95]
	v_mfma_f32_16x16x32_bf16 v[88:91], v[164:167], v[204:207], v[88:91]
	v_mfma_f32_16x16x32_bf16 v[76:79], v[156:159], v[212:215], v[76:79]
	v_mfma_f32_16x16x32_bf16 v[72:75], v[164:167], v[212:215], v[72:75]
	v_mfma_f32_16x16x32_bf16 v[116:119], v[168:171], v[184:187], v[116:119]
	v_mfma_f32_16x16x32_bf16 v[112:115], v[176:179], v[184:187], v[112:115]
	v_mfma_f32_16x16x32_bf16 v[100:103], v[168:171], v[192:195], v[100:103]
	v_mfma_f32_16x16x32_bf16 v[96:99], v[176:179], v[192:195], v[96:99]
	v_mfma_f32_16x16x32_bf16 v[84:87], v[168:171], v[200:203], v[84:87]
	v_mfma_f32_16x16x32_bf16 v[80:83], v[176:179], v[200:203], v[80:83]
	v_mfma_f32_16x16x32_bf16 v[68:71], v[168:171], v[208:211], v[68:71]
	v_mfma_f32_16x16x32_bf16 v[64:67], v[176:179], v[208:211], v[64:67]
	v_mfma_f32_16x16x32_bf16 v[116:119], v[172:175], v[188:191], v[116:119]
	v_mfma_f32_16x16x32_bf16 v[112:115], v[180:183], v[188:191], v[112:115]
	v_mfma_f32_16x16x32_bf16 v[100:103], v[172:175], v[196:199], v[100:103]
	v_mfma_f32_16x16x32_bf16 v[96:99], v[180:183], v[196:199], v[96:99]
	v_mfma_f32_16x16x32_bf16 v[84:87], v[172:175], v[204:207], v[84:87]
	v_mfma_f32_16x16x32_bf16 v[80:83], v[180:183], v[204:207], v[80:83]
	v_mfma_f32_16x16x32_bf16 v[68:71], v[172:175], v[212:215], v[68:71]
	v_mfma_f32_16x16x32_bf16 v[64:67], v[180:183], v[212:215], v[64:67]
	s_barrier
	ds_read_b128 v[184:187], v153 offset:16384
	ds_read_b128 v[188:191], v153 offset:17408
	ds_read_b128 v[192:195], v153 offset:18432
	ds_read_b128 v[196:199], v153 offset:19456
	ds_read_b128 v[200:203], v153 offset:20480
	ds_read_b128 v[204:207], v153 offset:21504
	ds_read_b128 v[208:211], v153 offset:22528
	ds_read_b128 v[212:215], v153 offset:23552
	s_setprio 0
	s_add_i32 s48, s67, s35
	s_mov_b32 m0, s48
	v_lshl_add_u64 v[216:217], s[54:55], 0, v[130:131]
	global_load_lds_dwordx4 v[216:217], off
	s_add_i32 m0, s48, 0x2000
	s_add_u32 s48, s54, 0x40000
	v_lshl_add_u64 v[220:221], s[54:55], 0, v[134:135]
	s_addc_u32 s49, s55, 0
	s_add_i32 s68, s72, s35
	global_load_lds_dwordx4 v[220:221], off
	v_lshl_add_u64 v[224:225], s[48:49], 0, v[130:131]
	s_mov_b32 m0, s68
	v_lshl_add_u64 v[226:227], s[78:79], 0, v[132:133]
	global_load_lds_dwordx4 v[224:225], off
	v_lshl_add_u64 v[224:225], s[48:49], 0, v[134:135]
	s_add_i32 m0, s68, 0x2000
	v_lshl_add_u64 v[228:229], v[226:227], 0, s[12:13]
	global_load_lds_dwordx4 v[224:225], off
	s_mov_b32 m0, s56
	v_lshl_add_u64 v[224:225], s[78:79], 0, v[128:129]
	global_load_lds_dwordx4 v[224:225], off
	s_mov_b32 m0, s57
	s_nop 0
	global_load_lds_dwordx4 v[228:229], off
	s_setprio 1
	s_waitcnt vmcnt(8) lgkmcnt(0)
	s_barrier
	v_mfma_f32_16x16x32_bf16 v[60:63], v[144:147], v[184:187], v[60:63]
	v_mfma_f32_16x16x32_bf16 v[56:59], v[160:163], v[184:187], v[56:59]
	v_mfma_f32_16x16x32_bf16 v[44:47], v[144:147], v[192:195], v[44:47]
	v_mfma_f32_16x16x32_bf16 v[40:43], v[160:163], v[192:195], v[40:43]
	v_mfma_f32_16x16x32_bf16 v[28:31], v[144:147], v[200:203], v[28:31]
	v_mfma_f32_16x16x32_bf16 v[24:27], v[160:163], v[200:203], v[24:27]
	v_mfma_f32_16x16x32_bf16 v[12:15], v[144:147], v[208:211], v[12:15]
	v_mfma_f32_16x16x32_bf16 v[8:11], v[160:163], v[208:211], v[8:11]
	v_mfma_f32_16x16x32_bf16 v[60:63], v[156:159], v[188:191], v[60:63]
	v_mfma_f32_16x16x32_bf16 v[56:59], v[164:167], v[188:191], v[56:59]
	v_mfma_f32_16x16x32_bf16 v[44:47], v[156:159], v[196:199], v[44:47]
	v_mfma_f32_16x16x32_bf16 v[40:43], v[164:167], v[196:199], v[40:43]
	v_mfma_f32_16x16x32_bf16 v[28:31], v[156:159], v[204:207], v[28:31]
	v_mfma_f32_16x16x32_bf16 v[24:27], v[164:167], v[204:207], v[24:27]
	v_mfma_f32_16x16x32_bf16 v[12:15], v[156:159], v[212:215], v[12:15]
	v_mfma_f32_16x16x32_bf16 v[8:11], v[164:167], v[212:215], v[8:11]
	v_mfma_f32_16x16x32_bf16 v[52:55], v[168:171], v[184:187], v[52:55]
	v_mfma_f32_16x16x32_bf16 v[48:51], v[176:179], v[184:187], v[48:51]
	v_mfma_f32_16x16x32_bf16 v[36:39], v[168:171], v[192:195], v[36:39]
	v_mfma_f32_16x16x32_bf16 v[32:35], v[176:179], v[192:195], v[32:35]
	v_mfma_f32_16x16x32_bf16 v[20:23], v[168:171], v[200:203], v[20:23]
	v_mfma_f32_16x16x32_bf16 v[16:19], v[176:179], v[200:203], v[16:19]
	v_mfma_f32_16x16x32_bf16 v[4:7], v[168:171], v[208:211], v[4:7]
	v_mfma_f32_16x16x32_bf16 v[0:3], v[176:179], v[208:211], v[0:3]
	v_mfma_f32_16x16x32_bf16 v[52:55], v[172:175], v[188:191], v[52:55]
	v_mfma_f32_16x16x32_bf16 v[48:51], v[180:183], v[188:191], v[48:51]
	v_mfma_f32_16x16x32_bf16 v[36:39], v[172:175], v[196:199], v[36:39]
	v_mfma_f32_16x16x32_bf16 v[32:35], v[180:183], v[196:199], v[32:35]
	v_mfma_f32_16x16x32_bf16 v[20:23], v[172:175], v[204:207], v[20:23]
	v_mfma_f32_16x16x32_bf16 v[16:19], v[180:183], v[204:207], v[16:19]
	v_mfma_f32_16x16x32_bf16 v[4:7], v[172:175], v[212:215], v[4:7]
	v_mfma_f32_16x16x32_bf16 v[0:3], v[180:183], v[212:215], v[0:3]
	s_barrier
	s_setprio 0
	s_add_i32 s48, 0, 0x18000
	v_add_u32_e32 v155, s48, v149
	s_add_i32 s68, 0, 0x1c000
	ds_read_b128 v[144:147], v155
	ds_read_b128 v[156:159], v155 offset:1024
	ds_read_b128 v[160:163], v155 offset:2048
	ds_read_b128 v[164:167], v155 offset:3072
	v_add_u32_e32 v155, s68, v149
	ds_read_b128 v[168:171], v155
	ds_read_b128 v[172:175], v155 offset:1024
	ds_read_b128 v[176:179], v155 offset:2048
	ds_read_b128 v[180:183], v155 offset:3072
	s_mov_b32 m0, s58
	v_lshl_add_u64 v[228:229], v[224:225], 0, s[8:9]
	ds_read_b128 v[184:187], v153 offset:32768
	ds_read_b128 v[188:191], v153 offset:33792
	ds_read_b128 v[192:195], v153 offset:34816
	ds_read_b128 v[196:199], v153 offset:35840
	ds_read_b128 v[200:203], v153 offset:36864
	ds_read_b128 v[204:207], v153 offset:37888
	ds_read_b128 v[208:211], v153 offset:38912
	ds_read_b128 v[212:215], v153 offset:39936
	global_load_lds_dwordx4 v[228:229], off
	s_mov_b32 m0, s59
	v_lshl_add_u64 v[228:229], v[226:227], 0, s[14:15]
	global_load_lds_dwordx4 v[228:229], off
	s_setprio 1
	s_waitcnt vmcnt(8) lgkmcnt(0)
	s_barrier
	v_mfma_f32_16x16x32_bf16 v[124:127], v[144:147], v[184:187], v[124:127]
	v_mfma_f32_16x16x32_bf16 v[120:123], v[160:163], v[184:187], v[120:123]
	v_mfma_f32_16x16x32_bf16 v[108:111], v[144:147], v[192:195], v[108:111]
	v_mfma_f32_16x16x32_bf16 v[104:107], v[160:163], v[192:195], v[104:107]
	v_mfma_f32_16x16x32_bf16 v[92:95], v[144:147], v[200:203], v[92:95]
	v_mfma_f32_16x16x32_bf16 v[88:91], v[160:163], v[200:203], v[88:91]
	v_mfma_f32_16x16x32_bf16 v[76:79], v[144:147], v[208:211], v[76:79]
	v_mfma_f32_16x16x32_bf16 v[72:75], v[160:163], v[208:211], v[72:75]
	v_mfma_f32_16x16x32_bf16 v[124:127], v[156:159], v[188:191], v[124:127]
	v_mfma_f32_16x16x32_bf16 v[120:123], v[164:167], v[188:191], v[120:123]
	v_mfma_f32_16x16x32_bf16 v[108:111], v[156:159], v[196:199], v[108:111]
	v_mfma_f32_16x16x32_bf16 v[104:107], v[164:167], v[196:199], v[104:107]
	v_mfma_f32_16x16x32_bf16 v[92:95], v[156:159], v[204:207], v[92:95]
	v_mfma_f32_16x16x32_bf16 v[88:91], v[164:167], v[204:207], v[88:91]
	v_mfma_f32_16x16x32_bf16 v[76:79], v[156:159], v[212:215], v[76:79]
	v_mfma_f32_16x16x32_bf16 v[72:75], v[164:167], v[212:215], v[72:75]
	v_mfma_f32_16x16x32_bf16 v[116:119], v[168:171], v[184:187], v[116:119]
	v_mfma_f32_16x16x32_bf16 v[112:115], v[176:179], v[184:187], v[112:115]
	v_mfma_f32_16x16x32_bf16 v[100:103], v[168:171], v[192:195], v[100:103]
	v_mfma_f32_16x16x32_bf16 v[96:99], v[176:179], v[192:195], v[96:99]
	v_mfma_f32_16x16x32_bf16 v[84:87], v[168:171], v[200:203], v[84:87]
	v_mfma_f32_16x16x32_bf16 v[80:83], v[176:179], v[200:203], v[80:83]
	v_mfma_f32_16x16x32_bf16 v[68:71], v[168:171], v[208:211], v[68:71]
	v_mfma_f32_16x16x32_bf16 v[64:67], v[176:179], v[208:211], v[64:67]
	v_mfma_f32_16x16x32_bf16 v[116:119], v[172:175], v[188:191], v[116:119]
	v_mfma_f32_16x16x32_bf16 v[112:115], v[180:183], v[188:191], v[112:115]
	v_mfma_f32_16x16x32_bf16 v[100:103], v[172:175], v[196:199], v[100:103]
	v_mfma_f32_16x16x32_bf16 v[96:99], v[180:183], v[196:199], v[96:99]
	v_mfma_f32_16x16x32_bf16 v[84:87], v[172:175], v[204:207], v[84:87]
	v_mfma_f32_16x16x32_bf16 v[80:83], v[180:183], v[204:207], v[80:83]
	v_mfma_f32_16x16x32_bf16 v[68:71], v[172:175], v[212:215], v[68:71]
	v_mfma_f32_16x16x32_bf16 v[64:67], v[180:183], v[212:215], v[64:67]
	s_barrier
	ds_read_b128 v[184:187], v153 offset:49152
	ds_read_b128 v[188:191], v153 offset:50176
	ds_read_b128 v[192:195], v153 offset:51200
	ds_read_b128 v[196:199], v153 offset:52224
	ds_read_b128 v[200:203], v153 offset:53248
	ds_read_b128 v[204:207], v153 offset:54272
	ds_read_b128 v[208:211], v153 offset:55296
	ds_read_b128 v[212:215], v153 offset:56320
	s_setprio 0
	s_add_i32 s48, s48, s35
	s_mov_b32 m0, s48
	v_lshl_add_u64 v[216:217], v[216:217], 0, s[24:25]
	global_load_lds_dwordx4 v[216:217], off
	s_add_i32 m0, s48, 0x2000
	s_add_u32 s48, s54, 0x40080
	v_lshl_add_u64 v[216:217], v[220:221], 0, s[24:25]
	s_addc_u32 s49, s55, 0
	s_add_i32 s54, s68, s35
	global_load_lds_dwordx4 v[216:217], off
	s_mov_b32 m0, s54
	v_lshl_add_u64 v[216:217], s[48:49], 0, v[130:131]
	global_load_lds_dwordx4 v[216:217], off
	s_add_i32 m0, s54, 0x2000
	v_lshl_add_u64 v[216:217], s[48:49], 0, v[134:135]
	global_load_lds_dwordx4 v[216:217], off
	s_mov_b32 m0, s61
	v_lshl_add_u64 v[216:217], v[224:225], 0, s[24:25]
	global_load_lds_dwordx4 v[216:217], off
	s_mov_b32 m0, s62
	v_lshl_add_u64 v[216:217], v[226:227], 0, s[36:37]
	global_load_lds_dwordx4 v[216:217], off
	s_setprio 1
	s_waitcnt vmcnt(8) lgkmcnt(0)
	s_barrier
	v_mfma_f32_16x16x32_bf16 v[60:63], v[144:147], v[184:187], v[60:63]
	v_mfma_f32_16x16x32_bf16 v[56:59], v[160:163], v[184:187], v[56:59]
	v_mfma_f32_16x16x32_bf16 v[44:47], v[144:147], v[192:195], v[44:47]
	v_mfma_f32_16x16x32_bf16 v[40:43], v[160:163], v[192:195], v[40:43]
	v_mfma_f32_16x16x32_bf16 v[28:31], v[144:147], v[200:203], v[28:31]
	v_mfma_f32_16x16x32_bf16 v[24:27], v[160:163], v[200:203], v[24:27]
	v_mfma_f32_16x16x32_bf16 v[12:15], v[144:147], v[208:211], v[12:15]
	v_mfma_f32_16x16x32_bf16 v[8:11], v[160:163], v[208:211], v[8:11]
	v_mfma_f32_16x16x32_bf16 v[60:63], v[156:159], v[188:191], v[60:63]
	v_mfma_f32_16x16x32_bf16 v[56:59], v[164:167], v[188:191], v[56:59]
	v_mfma_f32_16x16x32_bf16 v[44:47], v[156:159], v[196:199], v[44:47]
	v_mfma_f32_16x16x32_bf16 v[40:43], v[164:167], v[196:199], v[40:43]
	v_mfma_f32_16x16x32_bf16 v[28:31], v[156:159], v[204:207], v[28:31]
	v_mfma_f32_16x16x32_bf16 v[24:27], v[164:167], v[204:207], v[24:27]
	v_mfma_f32_16x16x32_bf16 v[12:15], v[156:159], v[212:215], v[12:15]
	v_mfma_f32_16x16x32_bf16 v[8:11], v[164:167], v[212:215], v[8:11]
	v_mfma_f32_16x16x32_bf16 v[52:55], v[168:171], v[184:187], v[52:55]
	v_mfma_f32_16x16x32_bf16 v[48:51], v[176:179], v[184:187], v[48:51]
	v_mfma_f32_16x16x32_bf16 v[36:39], v[168:171], v[192:195], v[36:39]
	v_mfma_f32_16x16x32_bf16 v[32:35], v[176:179], v[192:195], v[32:35]
	v_mfma_f32_16x16x32_bf16 v[20:23], v[168:171], v[200:203], v[20:23]
	v_mfma_f32_16x16x32_bf16 v[16:19], v[176:179], v[200:203], v[16:19]
	v_mfma_f32_16x16x32_bf16 v[4:7], v[168:171], v[208:211], v[4:7]
	v_mfma_f32_16x16x32_bf16 v[0:3], v[176:179], v[208:211], v[0:3]
	v_mfma_f32_16x16x32_bf16 v[52:55], v[172:175], v[188:191], v[52:55]
	v_mfma_f32_16x16x32_bf16 v[48:51], v[180:183], v[188:191], v[48:51]
	v_mfma_f32_16x16x32_bf16 v[36:39], v[172:175], v[196:199], v[36:39]
	v_mfma_f32_16x16x32_bf16 v[32:35], v[180:183], v[196:199], v[32:35]
	v_mfma_f32_16x16x32_bf16 v[20:23], v[172:175], v[204:207], v[20:23]
	v_mfma_f32_16x16x32_bf16 v[16:19], v[180:183], v[204:207], v[16:19]
	v_mfma_f32_16x16x32_bf16 v[4:7], v[172:175], v[212:215], v[4:7]
	v_mfma_f32_16x16x32_bf16 v[0:3], v[180:183], v[212:215], v[0:3]
	s_barrier
	s_setprio 0
	s_add_i32 s76, s76, 2
	s_add_u32 s51, s51, 0x100
	s_addc_u32 s75, s75, 0
	s_cmp_gt_u32 s76, 13
	s_mov_b64 s[48:49], s[52:53]
	s_cbranch_scc0 .LBB0_466

.LBB0_564:
	s_ashr_i32 s77, s76, 31
	s_lshl_b64 s[50:51], s[76:77], 19
	s_add_u32 s82, s49, s50
	s_addc_u32 s83, s53, s51
	s_and_b64 s[0:1], s[0:1], exec
	s_cselect_b32 s13, s83, s89
	s_cselect_b32 s77, s82, s88
	v_lshl_add_u64 v[92:93], s[84:85], 0, v[168:169]
	s_add_u32 vcc_lo, s88, 0x100
	v_lshl_add_u64 v[130:131], v[92:93], 0, s[86:87]
	s_addc_u32 vcc_hi, s89, 0
	s_mov_b32 s50, -2
	s_mov_b64 s[0:1], 0
	s_waitcnt vmcnt(0)
	ds_read_b128 v[132:135], v207
	ds_read_b128 v[136:139], v207 offset:1024
	ds_read_b128 v[140:143], v207 offset:2048
	ds_read_b128 v[144:147], v207 offset:3072
	ds_read_b128 v[148:151], v208
	ds_read_b128 v[152:155], v208 offset:1024
	ds_read_b128 v[156:159], v208 offset:2048
	ds_read_b128 v[174:177], v208 offset:3072
	s_add_u32 s51, s84, s0
	s_addc_u32 s68, s85, s1
	s_add_u32 s51, s51, 0x100
	s_addc_u32 s68, s68, 0
	s_add_u32 s69, vcc_lo, s0
	s_addc_u32 s70, vcc_hi, s1
	s_cmpk_eq_i32 s0, 0x700
	s_cselect_b32 s91, s79, s68
	s_cselect_b32 s90, s78, s51
	s_cselect_b32 s51, s81, s87
	s_cselect_b32 s71, s80, s86
	s_cselect_b32 s89, s13, s70
	s_cselect_b32 s88, s77, s69
	v_lshl_add_u64 v[160:161], v[92:93], 0, s[0:1]
	s_add_i32 m0, s59, 0xc000
	ds_read_b128 v[194:197], v209
	ds_read_b128 v[198:201], v209 offset:1024
	ds_read_b128 v[212:215], v209 offset:2048
	ds_read_b128 v[224:227], v209 offset:3072
	ds_read_b128 v[228:231], v209 offset:4096
	ds_read_b128 v[232:235], v209 offset:5120
	ds_read_b128 v[236:239], v209 offset:6144
	ds_read_b128 v[240:243], v209 offset:7168
	global_load_lds_dwordx4 v[160:161], off
	s_add_i32 m0, s59, 0xe000
	v_lshl_add_u64 v[160:161], v[130:131], 0, s[0:1]
	global_load_lds_dwordx4 v[160:161], off
	s_setprio 1
	s_waitcnt vmcnt(8) lgkmcnt(0)
	s_barrier
	v_mfma_f32_16x16x32_bf16 v[126:129], v[132:135], v[194:197], 0
	v_mfma_f32_16x16x32_bf16 v[60:63], v[140:143], v[194:197], 0
	v_mfma_f32_16x16x32_bf16 v[118:121], v[132:135], v[212:215], 0
	v_mfma_f32_16x16x32_bf16 v[52:55], v[140:143], v[212:215], 0
	v_mfma_f32_16x16x32_bf16 v[110:113], v[132:135], v[228:231], 0
	v_mfma_f32_16x16x32_bf16 v[44:47], v[140:143], v[228:231], 0
	v_mfma_f32_16x16x32_bf16 v[94:97], v[132:135], v[236:239], 0
	v_mfma_f32_16x16x32_bf16 v[28:31], v[140:143], v[236:239], 0
	v_mfma_f32_16x16x32_bf16 v[126:129], v[136:139], v[198:201], v[126:129]
	v_mfma_f32_16x16x32_bf16 v[60:63], v[144:147], v[198:201], v[60:63]
	v_mfma_f32_16x16x32_bf16 v[118:121], v[136:139], v[224:227], v[118:121]
	v_mfma_f32_16x16x32_bf16 v[52:55], v[144:147], v[224:227], v[52:55]
	v_mfma_f32_16x16x32_bf16 v[110:113], v[136:139], v[232:235], v[110:113]
	v_mfma_f32_16x16x32_bf16 v[44:47], v[144:147], v[232:235], v[44:47]
	v_mfma_f32_16x16x32_bf16 v[94:97], v[136:139], v[240:243], v[94:97]
	v_mfma_f32_16x16x32_bf16 v[28:31], v[144:147], v[240:243], v[28:31]
	v_mfma_f32_16x16x32_bf16 v[122:125], v[148:151], v[194:197], 0
	v_mfma_f32_16x16x32_bf16 v[56:59], v[156:159], v[194:197], 0
	v_mfma_f32_16x16x32_bf16 v[114:117], v[148:151], v[212:215], 0
	v_mfma_f32_16x16x32_bf16 v[48:51], v[156:159], v[212:215], 0
	v_mfma_f32_16x16x32_bf16 v[102:105], v[148:151], v[228:231], 0
	v_mfma_f32_16x16x32_bf16 v[36:39], v[156:159], v[228:231], 0
	v_mfma_f32_16x16x32_bf16 v[88:91], v[148:151], v[236:239], 0
	v_mfma_f32_16x16x32_bf16 v[24:27], v[156:159], v[236:239], 0
	v_mfma_f32_16x16x32_bf16 v[122:125], v[152:155], v[198:201], v[122:125]
	v_mfma_f32_16x16x32_bf16 v[56:59], v[174:177], v[198:201], v[56:59]
	v_mfma_f32_16x16x32_bf16 v[114:117], v[152:155], v[224:227], v[114:117]
	v_mfma_f32_16x16x32_bf16 v[48:51], v[174:177], v[224:227], v[48:51]
	v_mfma_f32_16x16x32_bf16 v[102:105], v[152:155], v[232:235], v[102:105]
	v_mfma_f32_16x16x32_bf16 v[36:39], v[174:177], v[232:235], v[36:39]
	v_mfma_f32_16x16x32_bf16 v[88:91], v[152:155], v[240:243], v[88:91]
	v_mfma_f32_16x16x32_bf16 v[24:27], v[174:177], v[240:243], v[24:27]
	s_barrier
	ds_read_b128 v[194:197], v209 offset:16384
	ds_read_b128 v[198:201], v209 offset:17408
	ds_read_b128 v[212:215], v209 offset:18432
	ds_read_b128 v[224:227], v209 offset:19456
	ds_read_b128 v[228:231], v209 offset:20480
	ds_read_b128 v[232:235], v209 offset:21504
	ds_read_b128 v[236:239], v209 offset:22528
	ds_read_b128 v[240:243], v209 offset:23552
	s_setprio 0
	s_add_i32 s68, s95, s57
	s_mov_b32 m0, s68
	v_lshl_add_u64 v[160:161], s[88:89], 0, v[164:165]
	global_load_lds_dwordx4 v[160:161], off
	s_add_i32 m0, s68, 0x2000
	s_add_u32 s68, s88, 0x40000
	v_lshl_add_u64 v[216:217], s[88:89], 0, v[166:167]
	s_addc_u32 s69, s89, 0
	s_add_i32 s70, s96, s57
	global_load_lds_dwordx4 v[216:217], off
	s_mov_b32 m0, s70
	v_lshl_add_u64 v[220:221], s[68:69], 0, v[164:165]
	global_load_lds_dwordx4 v[220:221], off
	s_add_i32 m0, s70, 0x2000
	v_lshl_add_u64 v[220:221], s[68:69], 0, v[166:167]
	s_add_u32 s68, s90, s71
	global_load_lds_dwordx4 v[220:221], off
	v_lshl_add_u64 v[220:221], s[90:91], 0, v[162:163]
	s_mov_b32 m0, s59
	s_addc_u32 s69, s91, s51
	global_load_lds_dwordx4 v[220:221], off
	s_mov_b32 m0, s61
	v_lshl_add_u64 v[244:245], s[68:69], 0, v[162:163]
	global_load_lds_dwordx4 v[244:245], off
	s_setprio 1
	s_waitcnt vmcnt(8) lgkmcnt(0)
	s_barrier
	v_mfma_f32_16x16x32_bf16 v[84:87], v[132:135], v[194:197], 0
	v_mfma_f32_16x16x32_bf16 v[20:23], v[140:143], v[194:197], 0
	v_mfma_f32_16x16x32_bf16 v[76:79], v[132:135], v[212:215], 0
	v_mfma_f32_16x16x32_bf16 v[12:15], v[140:143], v[212:215], 0
	v_mfma_f32_16x16x32_bf16 v[68:71], v[132:135], v[228:231], 0
	v_mfma_f32_16x16x32_bf16 v[4:7], v[140:143], v[228:231], 0
	v_mfma_f32_16x16x32_bf16 v[106:109], v[132:135], v[236:239], 0
	v_mfma_f32_16x16x32_bf16 v[40:43], v[140:143], v[236:239], 0
	v_mfma_f32_16x16x32_bf16 v[84:87], v[136:139], v[198:201], v[84:87]
	v_mfma_f32_16x16x32_bf16 v[20:23], v[144:147], v[198:201], v[20:23]
	v_mfma_f32_16x16x32_bf16 v[76:79], v[136:139], v[224:227], v[76:79]
	v_mfma_f32_16x16x32_bf16 v[12:15], v[144:147], v[224:227], v[12:15]
	v_mfma_f32_16x16x32_bf16 v[68:71], v[136:139], v[232:235], v[68:71]
	v_mfma_f32_16x16x32_bf16 v[4:7], v[144:147], v[232:235], v[4:7]
	v_mfma_f32_16x16x32_bf16 v[106:109], v[136:139], v[240:243], v[106:109]
	v_mfma_f32_16x16x32_bf16 v[40:43], v[144:147], v[240:243], v[40:43]
	v_mfma_f32_16x16x32_bf16 v[80:83], v[148:151], v[194:197], 0
	v_mfma_f32_16x16x32_bf16 v[16:19], v[156:159], v[194:197], 0
	v_mfma_f32_16x16x32_bf16 v[72:75], v[148:151], v[212:215], 0
	v_mfma_f32_16x16x32_bf16 v[8:11], v[156:159], v[212:215], 0
	v_mfma_f32_16x16x32_bf16 v[64:67], v[148:151], v[228:231], 0
	v_mfma_f32_16x16x32_bf16 v[0:3], v[156:159], v[228:231], 0
	v_mfma_f32_16x16x32_bf16 v[98:101], v[148:151], v[236:239], 0
	v_mfma_f32_16x16x32_bf16 v[32:35], v[156:159], v[236:239], 0
	v_mfma_f32_16x16x32_bf16 v[80:83], v[152:155], v[198:201], v[80:83]
	v_mfma_f32_16x16x32_bf16 v[16:19], v[174:177], v[198:201], v[16:19]
	v_mfma_f32_16x16x32_bf16 v[72:75], v[152:155], v[224:227], v[72:75]
	v_mfma_f32_16x16x32_bf16 v[8:11], v[174:177], v[224:227], v[8:11]
	v_mfma_f32_16x16x32_bf16 v[64:67], v[152:155], v[232:235], v[64:67]
	v_mfma_f32_16x16x32_bf16 v[0:3], v[174:177], v[232:235], v[0:3]
	v_mfma_f32_16x16x32_bf16 v[98:101], v[152:155], v[240:243], v[98:101]
	v_mfma_f32_16x16x32_bf16 v[32:35], v[174:177], v[240:243], v[32:35]
	s_barrier
	s_setprio 0
	s_add_i32 s70, 0, 0x18000
	s_add_i32 s14, 0, 0x1c000
	v_add_u32_e32 v144, s70, v203
	v_add_u32_e32 v174, s14, v203
	ds_read_b128 v[132:135], v144
	ds_read_b128 v[136:139], v144 offset:1024
	ds_read_b128 v[140:143], v144 offset:2048
	ds_read_b128 v[144:147], v144 offset:3072
	ds_read_b128 v[148:151], v174
	ds_read_b128 v[152:155], v174 offset:1024
	ds_read_b128 v[156:159], v174 offset:2048
	ds_read_b128 v[174:177], v174 offset:3072
	s_add_u32 s68, s90, 0x2000
	s_addc_u32 s69, s91, 0
	v_lshl_add_u64 v[246:247], s[68:69], 0, v[162:163]
	s_add_u32 s68, s68, s71
	s_mov_b32 m0, s63
	s_addc_u32 s69, s69, s51
	ds_read_b128 v[194:197], v209 offset:32768
	ds_read_b128 v[198:201], v209 offset:33792
	ds_read_b128 v[212:215], v209 offset:34816
	ds_read_b128 v[224:227], v209 offset:35840
	ds_read_b128 v[228:231], v209 offset:36864
	ds_read_b128 v[232:235], v209 offset:37888
	ds_read_b128 v[236:239], v209 offset:38912
	ds_read_b128 v[240:243], v209 offset:39936
	global_load_lds_dwordx4 v[246:247], off
	s_mov_b32 m0, s67
	v_lshl_add_u64 v[246:247], s[68:69], 0, v[162:163]
	global_load_lds_dwordx4 v[246:247], off
	s_setprio 1
	s_waitcnt vmcnt(8) lgkmcnt(0)
	s_barrier
	v_mfma_f32_16x16x32_bf16 v[126:129], v[132:135], v[194:197], v[126:129]
	v_mfma_f32_16x16x32_bf16 v[60:63], v[140:143], v[194:197], v[60:63]
	v_mfma_f32_16x16x32_bf16 v[118:121], v[132:135], v[212:215], v[118:121]
	v_mfma_f32_16x16x32_bf16 v[52:55], v[140:143], v[212:215], v[52:55]
	v_mfma_f32_16x16x32_bf16 v[110:113], v[132:135], v[228:231], v[110:113]
	v_mfma_f32_16x16x32_bf16 v[44:47], v[140:143], v[228:231], v[44:47]
	v_mfma_f32_16x16x32_bf16 v[94:97], v[132:135], v[236:239], v[94:97]
	v_mfma_f32_16x16x32_bf16 v[28:31], v[140:143], v[236:239], v[28:31]
	v_mfma_f32_16x16x32_bf16 v[126:129], v[136:139], v[198:201], v[126:129]
	v_mfma_f32_16x16x32_bf16 v[60:63], v[144:147], v[198:201], v[60:63]
	v_mfma_f32_16x16x32_bf16 v[118:121], v[136:139], v[224:227], v[118:121]
	v_mfma_f32_16x16x32_bf16 v[52:55], v[144:147], v[224:227], v[52:55]
	v_mfma_f32_16x16x32_bf16 v[110:113], v[136:139], v[232:235], v[110:113]
	v_mfma_f32_16x16x32_bf16 v[44:47], v[144:147], v[232:235], v[44:47]
	v_mfma_f32_16x16x32_bf16 v[94:97], v[136:139], v[240:243], v[94:97]
	v_mfma_f32_16x16x32_bf16 v[28:31], v[144:147], v[240:243], v[28:31]
	v_mfma_f32_16x16x32_bf16 v[122:125], v[148:151], v[194:197], v[122:125]
	v_mfma_f32_16x16x32_bf16 v[56:59], v[156:159], v[194:197], v[56:59]
	v_mfma_f32_16x16x32_bf16 v[114:117], v[148:151], v[212:215], v[114:117]
	v_mfma_f32_16x16x32_bf16 v[48:51], v[156:159], v[212:215], v[48:51]
	v_mfma_f32_16x16x32_bf16 v[102:105], v[148:151], v[228:231], v[102:105]
	v_mfma_f32_16x16x32_bf16 v[36:39], v[156:159], v[228:231], v[36:39]
	v_mfma_f32_16x16x32_bf16 v[88:91], v[148:151], v[236:239], v[88:91]
	v_mfma_f32_16x16x32_bf16 v[24:27], v[156:159], v[236:239], v[24:27]
	v_mfma_f32_16x16x32_bf16 v[122:125], v[152:155], v[198:201], v[122:125]
	v_mfma_f32_16x16x32_bf16 v[56:59], v[174:177], v[198:201], v[56:59]
	v_mfma_f32_16x16x32_bf16 v[114:117], v[152:155], v[224:227], v[114:117]
	v_mfma_f32_16x16x32_bf16 v[48:51], v[174:177], v[224:227], v[48:51]
	v_mfma_f32_16x16x32_bf16 v[102:105], v[152:155], v[232:235], v[102:105]
	v_mfma_f32_16x16x32_bf16 v[36:39], v[174:177], v[232:235], v[36:39]
	v_mfma_f32_16x16x32_bf16 v[88:91], v[152:155], v[240:243], v[88:91]
	v_mfma_f32_16x16x32_bf16 v[24:27], v[174:177], v[240:243], v[24:27]
	s_barrier
	ds_read_b128 v[194:197], v209 offset:49152
	ds_read_b128 v[198:201], v209 offset:50176
	ds_read_b128 v[212:215], v209 offset:51200
	ds_read_b128 v[224:227], v209 offset:52224
	ds_read_b128 v[228:231], v209 offset:53248
	ds_read_b128 v[232:235], v209 offset:54272
	ds_read_b128 v[236:239], v209 offset:55296
	ds_read_b128 v[240:243], v209 offset:56320
	s_setprio 0
	s_add_i32 s15, s70, s57
	s_mov_b32 m0, s15
	v_lshl_add_u64 v[160:161], v[160:161], 0, s[22:23]
	global_load_lds_dwordx4 v[160:161], off
	s_add_i32 m0, s15, 0x2000
	s_add_u32 s68, s88, 0x40080
	v_lshl_add_u64 v[160:161], v[216:217], 0, s[22:23]
	s_addc_u32 s69, s89, 0
	s_add_i32 s14, s14, s57
	global_load_lds_dwordx4 v[160:161], off
	s_mov_b32 m0, s14
	v_lshl_add_u64 v[160:161], s[68:69], 0, v[164:165]
	global_load_lds_dwordx4 v[160:161], off
	s_add_i32 m0, s14, 0x2000
	v_lshl_add_u64 v[160:161], s[68:69], 0, v[166:167]
	global_load_lds_dwordx4 v[160:161], off
	s_mov_b32 m0, s75
	v_lshl_add_u64 v[160:161], v[220:221], 0, s[22:23]
	global_load_lds_dwordx4 v[160:161], off
	s_mov_b32 m0, s92
	v_lshl_add_u64 v[160:161], v[244:245], 0, s[22:23]
	global_load_lds_dwordx4 v[160:161], off
	s_setprio 1
	s_waitcnt vmcnt(8) lgkmcnt(0)
	s_barrier
	v_mfma_f32_16x16x32_bf16 v[84:87], v[132:135], v[194:197], v[84:87]
	v_mfma_f32_16x16x32_bf16 v[20:23], v[140:143], v[194:197], v[20:23]
	v_mfma_f32_16x16x32_bf16 v[76:79], v[132:135], v[212:215], v[76:79]
	v_mfma_f32_16x16x32_bf16 v[12:15], v[140:143], v[212:215], v[12:15]
	v_mfma_f32_16x16x32_bf16 v[68:71], v[132:135], v[228:231], v[68:71]
	v_mfma_f32_16x16x32_bf16 v[4:7], v[140:143], v[228:231], v[4:7]
	v_mfma_f32_16x16x32_bf16 v[106:109], v[132:135], v[236:239], v[106:109]
	v_mfma_f32_16x16x32_bf16 v[40:43], v[140:143], v[236:239], v[40:43]
	v_mfma_f32_16x16x32_bf16 v[84:87], v[136:139], v[198:201], v[84:87]
	v_mfma_f32_16x16x32_bf16 v[20:23], v[144:147], v[198:201], v[20:23]
	v_mfma_f32_16x16x32_bf16 v[76:79], v[136:139], v[224:227], v[76:79]
	v_mfma_f32_16x16x32_bf16 v[12:15], v[144:147], v[224:227], v[12:15]
	v_mfma_f32_16x16x32_bf16 v[68:71], v[136:139], v[232:235], v[68:71]
	v_mfma_f32_16x16x32_bf16 v[4:7], v[144:147], v[232:235], v[4:7]
	v_mfma_f32_16x16x32_bf16 v[106:109], v[136:139], v[240:243], v[106:109]
	v_mfma_f32_16x16x32_bf16 v[40:43], v[144:147], v[240:243], v[40:43]
	v_mfma_f32_16x16x32_bf16 v[80:83], v[148:151], v[194:197], v[80:83]
	v_mfma_f32_16x16x32_bf16 v[16:19], v[156:159], v[194:197], v[16:19]
	v_mfma_f32_16x16x32_bf16 v[72:75], v[148:151], v[212:215], v[72:75]
	v_mfma_f32_16x16x32_bf16 v[8:11], v[156:159], v[212:215], v[8:11]
	v_mfma_f32_16x16x32_bf16 v[64:67], v[148:151], v[228:231], v[64:67]
	v_mfma_f32_16x16x32_bf16 v[0:3], v[156:159], v[228:231], v[0:3]
	v_mfma_f32_16x16x32_bf16 v[98:101], v[148:151], v[236:239], v[98:101]
	v_mfma_f32_16x16x32_bf16 v[32:35], v[156:159], v[236:239], v[32:35]
	v_mfma_f32_16x16x32_bf16 v[80:83], v[152:155], v[198:201], v[80:83]
	v_mfma_f32_16x16x32_bf16 v[16:19], v[174:177], v[198:201], v[16:19]
	v_mfma_f32_16x16x32_bf16 v[72:75], v[152:155], v[224:227], v[72:75]
	v_mfma_f32_16x16x32_bf16 v[8:11], v[174:177], v[224:227], v[8:11]
	v_mfma_f32_16x16x32_bf16 v[64:67], v[152:155], v[232:235], v[64:67]
	v_mfma_f32_16x16x32_bf16 v[0:3], v[174:177], v[232:235], v[0:3]
	v_mfma_f32_16x16x32_bf16 v[98:101], v[152:155], v[240:243], v[98:101]
	v_mfma_f32_16x16x32_bf16 v[32:35], v[174:177], v[240:243], v[32:35]
	s_barrier
	s_setprio 0
	s_add_i32 s50, s50, 2
	s_add_u32 s0, s0, 0x100
	s_addc_u32 s1, s1, 0
	s_cmp_gt_u32 s50, 13
.LBB0_565:
	ds_read_b128 v[132:135], v207
	ds_read_b128 v[136:139], v207 offset:1024
	ds_read_b128 v[140:143], v207 offset:2048
	ds_read_b128 v[144:147], v207 offset:3072
	ds_read_b128 v[148:151], v208
	ds_read_b128 v[152:155], v208 offset:1024
	ds_read_b128 v[156:159], v208 offset:2048
	ds_read_b128 v[174:177], v208 offset:3072
	s_add_u32 s51, s84, s0
	s_addc_u32 s68, s85, s1
	s_add_u32 s51, s51, 0x100
	s_addc_u32 s68, s68, 0
	s_add_u32 s69, vcc_lo, s0
	s_addc_u32 s70, vcc_hi, s1
	s_cmpk_eq_i32 s0, 0x700
	s_cselect_b32 s91, s79, s68
	s_cselect_b32 s90, s78, s51
	s_cselect_b32 s51, s81, s87
	s_cselect_b32 s71, s80, s86
	s_cselect_b32 s89, s13, s70
	s_cselect_b32 s88, s77, s69
	v_lshl_add_u64 v[160:161], v[92:93], 0, s[0:1]
	s_add_i32 m0, s59, 0xc000
	ds_read_b128 v[194:197], v209
	ds_read_b128 v[198:201], v209 offset:1024
	ds_read_b128 v[212:215], v209 offset:2048
	ds_read_b128 v[224:227], v209 offset:3072
	ds_read_b128 v[228:231], v209 offset:4096
	ds_read_b128 v[232:235], v209 offset:5120
	ds_read_b128 v[236:239], v209 offset:6144
	ds_read_b128 v[240:243], v209 offset:7168
	global_load_lds_dwordx4 v[160:161], off
	s_add_i32 m0, s59, 0xe000
	v_lshl_add_u64 v[160:161], v[130:131], 0, s[0:1]
	global_load_lds_dwordx4 v[160:161], off
	s_setprio 1
	s_waitcnt vmcnt(8) lgkmcnt(0)
	s_barrier
	v_mfma_f32_16x16x32_bf16 v[126:129], v[132:135], v[194:197], v[126:129]
	v_mfma_f32_16x16x32_bf16 v[60:63], v[140:143], v[194:197], v[60:63]
	v_mfma_f32_16x16x32_bf16 v[118:121], v[132:135], v[212:215], v[118:121]
	v_mfma_f32_16x16x32_bf16 v[52:55], v[140:143], v[212:215], v[52:55]
	v_mfma_f32_16x16x32_bf16 v[110:113], v[132:135], v[228:231], v[110:113]
	v_mfma_f32_16x16x32_bf16 v[44:47], v[140:143], v[228:231], v[44:47]
	v_mfma_f32_16x16x32_bf16 v[94:97], v[132:135], v[236:239], v[94:97]
	v_mfma_f32_16x16x32_bf16 v[28:31], v[140:143], v[236:239], v[28:31]
	v_mfma_f32_16x16x32_bf16 v[126:129], v[136:139], v[198:201], v[126:129]
	v_mfma_f32_16x16x32_bf16 v[60:63], v[144:147], v[198:201], v[60:63]
	v_mfma_f32_16x16x32_bf16 v[118:121], v[136:139], v[224:227], v[118:121]
	v_mfma_f32_16x16x32_bf16 v[52:55], v[144:147], v[224:227], v[52:55]
	v_mfma_f32_16x16x32_bf16 v[110:113], v[136:139], v[232:235], v[110:113]
	v_mfma_f32_16x16x32_bf16 v[44:47], v[144:147], v[232:235], v[44:47]
	v_mfma_f32_16x16x32_bf16 v[94:97], v[136:139], v[240:243], v[94:97]
	v_mfma_f32_16x16x32_bf16 v[28:31], v[144:147], v[240:243], v[28:31]
	v_mfma_f32_16x16x32_bf16 v[122:125], v[148:151], v[194:197], v[122:125]
	v_mfma_f32_16x16x32_bf16 v[56:59], v[156:159], v[194:197], v[56:59]
	v_mfma_f32_16x16x32_bf16 v[114:117], v[148:151], v[212:215], v[114:117]
	v_mfma_f32_16x16x32_bf16 v[48:51], v[156:159], v[212:215], v[48:51]
	v_mfma_f32_16x16x32_bf16 v[102:105], v[148:151], v[228:231], v[102:105]
	v_mfma_f32_16x16x32_bf16 v[36:39], v[156:159], v[228:231], v[36:39]
	v_mfma_f32_16x16x32_bf16 v[88:91], v[148:151], v[236:239], v[88:91]
	v_mfma_f32_16x16x32_bf16 v[24:27], v[156:159], v[236:239], v[24:27]
	v_mfma_f32_16x16x32_bf16 v[122:125], v[152:155], v[198:201], v[122:125]
	v_mfma_f32_16x16x32_bf16 v[56:59], v[174:177], v[198:201], v[56:59]
	v_mfma_f32_16x16x32_bf16 v[114:117], v[152:155], v[224:227], v[114:117]
	v_mfma_f32_16x16x32_bf16 v[48:51], v[174:177], v[224:227], v[48:51]
	v_mfma_f32_16x16x32_bf16 v[102:105], v[152:155], v[232:235], v[102:105]
	v_mfma_f32_16x16x32_bf16 v[36:39], v[174:177], v[232:235], v[36:39]
	v_mfma_f32_16x16x32_bf16 v[88:91], v[152:155], v[240:243], v[88:91]
	v_mfma_f32_16x16x32_bf16 v[24:27], v[174:177], v[240:243], v[24:27]
	s_barrier
	ds_read_b128 v[194:197], v209 offset:16384
	ds_read_b128 v[198:201], v209 offset:17408
	ds_read_b128 v[212:215], v209 offset:18432
	ds_read_b128 v[224:227], v209 offset:19456
	ds_read_b128 v[228:231], v209 offset:20480
	ds_read_b128 v[232:235], v209 offset:21504
	ds_read_b128 v[236:239], v209 offset:22528
	ds_read_b128 v[240:243], v209 offset:23552
	s_setprio 0
	s_add_i32 s68, s95, s57
	s_mov_b32 m0, s68
	v_lshl_add_u64 v[160:161], s[88:89], 0, v[164:165]
	global_load_lds_dwordx4 v[160:161], off
	s_add_i32 m0, s68, 0x2000
	s_add_u32 s68, s88, 0x40000
	v_lshl_add_u64 v[216:217], s[88:89], 0, v[166:167]
	s_addc_u32 s69, s89, 0
	s_add_i32 s70, s96, s57
	global_load_lds_dwordx4 v[216:217], off
	s_mov_b32 m0, s70
	v_lshl_add_u64 v[220:221], s[68:69], 0, v[164:165]
	global_load_lds_dwordx4 v[220:221], off
	s_add_i32 m0, s70, 0x2000
	v_lshl_add_u64 v[220:221], s[68:69], 0, v[166:167]
	s_add_u32 s68, s90, s71
	global_load_lds_dwordx4 v[220:221], off
	v_lshl_add_u64 v[220:221], s[90:91], 0, v[162:163]
	s_mov_b32 m0, s59
	s_addc_u32 s69, s91, s51
	global_load_lds_dwordx4 v[220:221], off
	s_mov_b32 m0, s61
	v_lshl_add_u64 v[244:245], s[68:69], 0, v[162:163]
	global_load_lds_dwordx4 v[244:245], off
	s_setprio 1
	s_waitcnt vmcnt(8) lgkmcnt(0)
	s_barrier
	v_mfma_f32_16x16x32_bf16 v[84:87], v[132:135], v[194:197], v[84:87]
	v_mfma_f32_16x16x32_bf16 v[20:23], v[140:143], v[194:197], v[20:23]
	v_mfma_f32_16x16x32_bf16 v[76:79], v[132:135], v[212:215], v[76:79]
	v_mfma_f32_16x16x32_bf16 v[12:15], v[140:143], v[212:215], v[12:15]
	v_mfma_f32_16x16x32_bf16 v[68:71], v[132:135], v[228:231], v[68:71]
	v_mfma_f32_16x16x32_bf16 v[4:7], v[140:143], v[228:231], v[4:7]
	v_mfma_f32_16x16x32_bf16 v[106:109], v[132:135], v[236:239], v[106:109]
	v_mfma_f32_16x16x32_bf16 v[40:43], v[140:143], v[236:239], v[40:43]
	v_mfma_f32_16x16x32_bf16 v[84:87], v[136:139], v[198:201], v[84:87]
	v_mfma_f32_16x16x32_bf16 v[20:23], v[144:147], v[198:201], v[20:23]
	v_mfma_f32_16x16x32_bf16 v[76:79], v[136:139], v[224:227], v[76:79]
	v_mfma_f32_16x16x32_bf16 v[12:15], v[144:147], v[224:227], v[12:15]
	v_mfma_f32_16x16x32_bf16 v[68:71], v[136:139], v[232:235], v[68:71]
	v_mfma_f32_16x16x32_bf16 v[4:7], v[144:147], v[232:235], v[4:7]
	v_mfma_f32_16x16x32_bf16 v[106:109], v[136:139], v[240:243], v[106:109]
	v_mfma_f32_16x16x32_bf16 v[40:43], v[144:147], v[240:243], v[40:43]
	v_mfma_f32_16x16x32_bf16 v[80:83], v[148:151], v[194:197], v[80:83]
	v_mfma_f32_16x16x32_bf16 v[16:19], v[156:159], v[194:197], v[16:19]
	v_mfma_f32_16x16x32_bf16 v[72:75], v[148:151], v[212:215], v[72:75]
	v_mfma_f32_16x16x32_bf16 v[8:11], v[156:159], v[212:215], v[8:11]
	v_mfma_f32_16x16x32_bf16 v[64:67], v[148:151], v[228:231], v[64:67]
	v_mfma_f32_16x16x32_bf16 v[0:3], v[156:159], v[228:231], v[0:3]
	v_mfma_f32_16x16x32_bf16 v[98:101], v[148:151], v[236:239], v[98:101]
	v_mfma_f32_16x16x32_bf16 v[32:35], v[156:159], v[236:239], v[32:35]
	v_mfma_f32_16x16x32_bf16 v[80:83], v[152:155], v[198:201], v[80:83]
	v_mfma_f32_16x16x32_bf16 v[16:19], v[174:177], v[198:201], v[16:19]
	v_mfma_f32_16x16x32_bf16 v[72:75], v[152:155], v[224:227], v[72:75]
	v_mfma_f32_16x16x32_bf16 v[8:11], v[174:177], v[224:227], v[8:11]
	v_mfma_f32_16x16x32_bf16 v[64:67], v[152:155], v[232:235], v[64:67]
	v_mfma_f32_16x16x32_bf16 v[0:3], v[174:177], v[232:235], v[0:3]
	v_mfma_f32_16x16x32_bf16 v[98:101], v[152:155], v[240:243], v[98:101]
	v_mfma_f32_16x16x32_bf16 v[32:35], v[174:177], v[240:243], v[32:35]
	s_barrier
	s_setprio 0
	s_add_i32 s70, 0, 0x18000
	s_add_i32 s14, 0, 0x1c000
	v_add_u32_e32 v144, s70, v203
	v_add_u32_e32 v174, s14, v203
	ds_read_b128 v[132:135], v144
	ds_read_b128 v[136:139], v144 offset:1024
	ds_read_b128 v[140:143], v144 offset:2048
	ds_read_b128 v[144:147], v144 offset:3072
	ds_read_b128 v[148:151], v174
	ds_read_b128 v[152:155], v174 offset:1024
	ds_read_b128 v[156:159], v174 offset:2048
	ds_read_b128 v[174:177], v174 offset:3072
	s_add_u32 s68, s90, 0x2000
	s_addc_u32 s69, s91, 0
	v_lshl_add_u64 v[246:247], s[68:69], 0, v[162:163]
	s_add_u32 s68, s68, s71
	s_mov_b32 m0, s63
	s_addc_u32 s69, s69, s51
	ds_read_b128 v[194:197], v209 offset:32768
	ds_read_b128 v[198:201], v209 offset:33792
	ds_read_b128 v[212:215], v209 offset:34816
	ds_read_b128 v[224:227], v209 offset:35840
	ds_read_b128 v[228:231], v209 offset:36864
	ds_read_b128 v[232:235], v209 offset:37888
	ds_read_b128 v[236:239], v209 offset:38912
	ds_read_b128 v[240:243], v209 offset:39936
	global_load_lds_dwordx4 v[246:247], off
	s_mov_b32 m0, s67
	v_lshl_add_u64 v[246:247], s[68:69], 0, v[162:163]
	global_load_lds_dwordx4 v[246:247], off
	s_setprio 1
	s_waitcnt vmcnt(8) lgkmcnt(0)
	s_barrier
	v_mfma_f32_16x16x32_bf16 v[126:129], v[132:135], v[194:197], v[126:129]
	v_mfma_f32_16x16x32_bf16 v[60:63], v[140:143], v[194:197], v[60:63]
	v_mfma_f32_16x16x32_bf16 v[118:121], v[132:135], v[212:215], v[118:121]
	v_mfma_f32_16x16x32_bf16 v[52:55], v[140:143], v[212:215], v[52:55]
	v_mfma_f32_16x16x32_bf16 v[110:113], v[132:135], v[228:231], v[110:113]
	v_mfma_f32_16x16x32_bf16 v[44:47], v[140:143], v[228:231], v[44:47]
	v_mfma_f32_16x16x32_bf16 v[94:97], v[132:135], v[236:239], v[94:97]
	v_mfma_f32_16x16x32_bf16 v[28:31], v[140:143], v[236:239], v[28:31]
	v_mfma_f32_16x16x32_bf16 v[126:129], v[136:139], v[198:201], v[126:129]
	v_mfma_f32_16x16x32_bf16 v[60:63], v[144:147], v[198:201], v[60:63]
	v_mfma_f32_16x16x32_bf16 v[118:121], v[136:139], v[224:227], v[118:121]
	v_mfma_f32_16x16x32_bf16 v[52:55], v[144:147], v[224:227], v[52:55]
	v_mfma_f32_16x16x32_bf16 v[110:113], v[136:139], v[232:235], v[110:113]
	v_mfma_f32_16x16x32_bf16 v[44:47], v[144:147], v[232:235], v[44:47]
	v_mfma_f32_16x16x32_bf16 v[94:97], v[136:139], v[240:243], v[94:97]
	v_mfma_f32_16x16x32_bf16 v[28:31], v[144:147], v[240:243], v[28:31]
	v_mfma_f32_16x16x32_bf16 v[122:125], v[148:151], v[194:197], v[122:125]
	v_mfma_f32_16x16x32_bf16 v[56:59], v[156:159], v[194:197], v[56:59]
	v_mfma_f32_16x16x32_bf16 v[114:117], v[148:151], v[212:215], v[114:117]
	v_mfma_f32_16x16x32_bf16 v[48:51], v[156:159], v[212:215], v[48:51]
	v_mfma_f32_16x16x32_bf16 v[102:105], v[148:151], v[228:231], v[102:105]
	v_mfma_f32_16x16x32_bf16 v[36:39], v[156:159], v[228:231], v[36:39]
	v_mfma_f32_16x16x32_bf16 v[88:91], v[148:151], v[236:239], v[88:91]
	v_mfma_f32_16x16x32_bf16 v[24:27], v[156:159], v[236:239], v[24:27]
	v_mfma_f32_16x16x32_bf16 v[122:125], v[152:155], v[198:201], v[122:125]
	v_mfma_f32_16x16x32_bf16 v[56:59], v[174:177], v[198:201], v[56:59]
	v_mfma_f32_16x16x32_bf16 v[114:117], v[152:155], v[224:227], v[114:117]
	v_mfma_f32_16x16x32_bf16 v[48:51], v[174:177], v[224:227], v[48:51]
	v_mfma_f32_16x16x32_bf16 v[102:105], v[152:155], v[232:235], v[102:105]
	v_mfma_f32_16x16x32_bf16 v[36:39], v[174:177], v[232:235], v[36:39]
	v_mfma_f32_16x16x32_bf16 v[88:91], v[152:155], v[240:243], v[88:91]
	v_mfma_f32_16x16x32_bf16 v[24:27], v[174:177], v[240:243], v[24:27]
	s_barrier
	ds_read_b128 v[194:197], v209 offset:49152
	ds_read_b128 v[198:201], v209 offset:50176
	ds_read_b128 v[212:215], v209 offset:51200
	ds_read_b128 v[224:227], v209 offset:52224
	ds_read_b128 v[228:231], v209 offset:53248
	ds_read_b128 v[232:235], v209 offset:54272
	ds_read_b128 v[236:239], v209 offset:55296
	ds_read_b128 v[240:243], v209 offset:56320
	s_setprio 0
	s_add_i32 s15, s70, s57
	s_mov_b32 m0, s15
	v_lshl_add_u64 v[160:161], v[160:161], 0, s[22:23]
	global_load_lds_dwordx4 v[160:161], off
	s_add_i32 m0, s15, 0x2000
	s_add_u32 s68, s88, 0x40080
	v_lshl_add_u64 v[160:161], v[216:217], 0, s[22:23]
	s_addc_u32 s69, s89, 0
	s_add_i32 s14, s14, s57
	global_load_lds_dwordx4 v[160:161], off
	s_mov_b32 m0, s14
	v_lshl_add_u64 v[160:161], s[68:69], 0, v[164:165]
	global_load_lds_dwordx4 v[160:161], off
	s_add_i32 m0, s14, 0x2000
	v_lshl_add_u64 v[160:161], s[68:69], 0, v[166:167]
	global_load_lds_dwordx4 v[160:161], off
	s_mov_b32 m0, s75
	v_lshl_add_u64 v[160:161], v[220:221], 0, s[22:23]
	global_load_lds_dwordx4 v[160:161], off
	s_mov_b32 m0, s92
	v_lshl_add_u64 v[160:161], v[244:245], 0, s[22:23]
	global_load_lds_dwordx4 v[160:161], off
	s_setprio 1
	s_waitcnt vmcnt(8) lgkmcnt(0)
	s_barrier
	v_mfma_f32_16x16x32_bf16 v[84:87], v[132:135], v[194:197], v[84:87]
	v_mfma_f32_16x16x32_bf16 v[20:23], v[140:143], v[194:197], v[20:23]
	v_mfma_f32_16x16x32_bf16 v[76:79], v[132:135], v[212:215], v[76:79]
	v_mfma_f32_16x16x32_bf16 v[12:15], v[140:143], v[212:215], v[12:15]
	v_mfma_f32_16x16x32_bf16 v[68:71], v[132:135], v[228:231], v[68:71]
	v_mfma_f32_16x16x32_bf16 v[4:7], v[140:143], v[228:231], v[4:7]
	v_mfma_f32_16x16x32_bf16 v[106:109], v[132:135], v[236:239], v[106:109]
	v_mfma_f32_16x16x32_bf16 v[40:43], v[140:143], v[236:239], v[40:43]
	v_mfma_f32_16x16x32_bf16 v[84:87], v[136:139], v[198:201], v[84:87]
	v_mfma_f32_16x16x32_bf16 v[20:23], v[144:147], v[198:201], v[20:23]
	v_mfma_f32_16x16x32_bf16 v[76:79], v[136:139], v[224:227], v[76:79]
	v_mfma_f32_16x16x32_bf16 v[12:15], v[144:147], v[224:227], v[12:15]
	v_mfma_f32_16x16x32_bf16 v[68:71], v[136:139], v[232:235], v[68:71]
	v_mfma_f32_16x16x32_bf16 v[4:7], v[144:147], v[232:235], v[4:7]
	v_mfma_f32_16x16x32_bf16 v[106:109], v[136:139], v[240:243], v[106:109]
	v_mfma_f32_16x16x32_bf16 v[40:43], v[144:147], v[240:243], v[40:43]
	v_mfma_f32_16x16x32_bf16 v[80:83], v[148:151], v[194:197], v[80:83]
	v_mfma_f32_16x16x32_bf16 v[16:19], v[156:159], v[194:197], v[16:19]
	v_mfma_f32_16x16x32_bf16 v[72:75], v[148:151], v[212:215], v[72:75]
	v_mfma_f32_16x16x32_bf16 v[8:11], v[156:159], v[212:215], v[8:11]
	v_mfma_f32_16x16x32_bf16 v[64:67], v[148:151], v[228:231], v[64:67]
	v_mfma_f32_16x16x32_bf16 v[0:3], v[156:159], v[228:231], v[0:3]
	v_mfma_f32_16x16x32_bf16 v[98:101], v[148:151], v[236:239], v[98:101]
	v_mfma_f32_16x16x32_bf16 v[32:35], v[156:159], v[236:239], v[32:35]
	v_mfma_f32_16x16x32_bf16 v[80:83], v[152:155], v[198:201], v[80:83]
	v_mfma_f32_16x16x32_bf16 v[16:19], v[174:177], v[198:201], v[16:19]
	v_mfma_f32_16x16x32_bf16 v[72:75], v[152:155], v[224:227], v[72:75]
	v_mfma_f32_16x16x32_bf16 v[8:11], v[174:177], v[224:227], v[8:11]
	v_mfma_f32_16x16x32_bf16 v[64:67], v[152:155], v[232:235], v[64:67]
	v_mfma_f32_16x16x32_bf16 v[0:3], v[174:177], v[232:235], v[0:3]
	v_mfma_f32_16x16x32_bf16 v[98:101], v[152:155], v[240:243], v[98:101]
	v_mfma_f32_16x16x32_bf16 v[32:35], v[174:177], v[240:243], v[32:35]
	s_barrier
	s_setprio 0
	s_add_i32 s50, s50, 2
	s_add_u32 s0, s0, 0x100
	s_addc_u32 s1, s1, 0
	s_cmp_gt_u32 s50, 13
	s_cbranch_scc0 .LBB0_565

.LBB0_585:
	s_add_u32 s58, s46, s52
	s_addc_u32 s59, s47, s53
	s_add_u32 s56, s58, 0x100
	s_addc_u32 s57, s59, 0
	s_and_b64 s[54:55], s[50:51], exec
	s_cselect_b32 s54, s81, s56
	s_cselect_b32 s55, s13, s57
	s_add_u32 s52, s44, s52
	s_addc_u32 s53, s45, s53
	s_add_u32 s52, s52, 0x100
	ds_read_b128 v[148:151], v145
	ds_read_b128 v[152:155], v145 offset:1024
	ds_read_b128 v[156:159], v145 offset:2048
	ds_read_b128 v[160:163], v145 offset:3072
	ds_read_b128 v[164:167], v146
	ds_read_b128 v[168:171], v146 offset:1024
	ds_read_b128 v[172:175], v146 offset:2048
	ds_read_b128 v[176:179], v146 offset:3072
	s_addc_u32 s53, s53, 0
	s_and_b64 s[50:51], s[50:51], exec
	s_cselect_b32 s53, s39, s53
	s_cselect_b32 s52, s82, s52
	s_add_i32 s92, s75, s35
	s_add_i32 m0, s62, 0xc000
	s_add_i32 s93, s62, 0xe000
	s_add_i32 s89, s92, 0x2000
	s_add_u32 s56, s52, 0x10000
	s_addc_u32 s57, s53, 0
	s_add_i32 s88, 0, 0x18000
	s_add_i32 s91, s76, s35
	s_add_i32 s86, s88, s35
	s_add_i32 s90, s91, 0x2000
	s_add_i32 s87, 0, 0x1c000
	s_add_i32 s84, s86, 0x2000
	s_add_u32 s50, s52, 0x10080
	s_addc_u32 s51, s53, 0
	s_add_i32 s85, s87, s35
	s_add_i32 s83, s85, 0x2000
	v_lshl_add_u64 v[140:141], s[58:59], 0, v[134:135]
	v_lshl_add_u64 v[140:141], v[140:141], 0, s[68:69]
	ds_read_b128 v[180:183], v147
	ds_read_b128 v[184:187], v147 offset:1024
	ds_read_b128 v[188:191], v147 offset:2048
	ds_read_b128 v[192:195], v147 offset:3072
	ds_read_b128 v[196:199], v147 offset:4096
	ds_read_b128 v[200:203], v147 offset:5120
	ds_read_b128 v[204:207], v147 offset:6144
	ds_read_b128 v[208:211], v147 offset:7168
	global_load_lds_dwordx4 v[140:141], off
	v_lshl_add_u64 v[140:141], s[58:59], 0, v[130:131]
	s_mov_b64 s[58:59], 0x18080
	s_mov_b32 m0, s93
	v_lshl_add_u64 v[140:141], v[140:141], 0, s[58:59]
	global_load_lds_dwordx4 v[140:141], off
	s_setprio 1
	s_waitcnt vmcnt(8) lgkmcnt(0)
	s_barrier
	v_mfma_f32_16x16x32_bf16 v[124:127], v[148:151], v[180:183], v[124:127]
	v_mfma_f32_16x16x32_bf16 v[120:123], v[156:159], v[180:183], v[120:123]
	v_mfma_f32_16x16x32_bf16 v[112:115], v[148:151], v[188:191], v[112:115]
	v_mfma_f32_16x16x32_bf16 v[104:107], v[156:159], v[188:191], v[104:107]
	v_mfma_f32_16x16x32_bf16 v[96:99], v[148:151], v[196:199], v[96:99]
	v_mfma_f32_16x16x32_bf16 v[88:91], v[156:159], v[196:199], v[88:91]
	v_mfma_f32_16x16x32_bf16 v[80:83], v[148:151], v[204:207], v[80:83]
	v_mfma_f32_16x16x32_bf16 v[72:75], v[156:159], v[204:207], v[72:75]
	v_mfma_f32_16x16x32_bf16 v[124:127], v[152:155], v[184:187], v[124:127]
	v_mfma_f32_16x16x32_bf16 v[120:123], v[160:163], v[184:187], v[120:123]
	v_mfma_f32_16x16x32_bf16 v[112:115], v[152:155], v[192:195], v[112:115]
	v_mfma_f32_16x16x32_bf16 v[104:107], v[160:163], v[192:195], v[104:107]
	v_mfma_f32_16x16x32_bf16 v[96:99], v[152:155], v[200:203], v[96:99]
	v_mfma_f32_16x16x32_bf16 v[88:91], v[160:163], v[200:203], v[88:91]
	v_mfma_f32_16x16x32_bf16 v[80:83], v[152:155], v[208:211], v[80:83]
	v_mfma_f32_16x16x32_bf16 v[72:75], v[160:163], v[208:211], v[72:75]
	v_mfma_f32_16x16x32_bf16 v[116:119], v[164:167], v[180:183], v[116:119]
	v_mfma_f32_16x16x32_bf16 v[108:111], v[172:175], v[180:183], v[108:111]
	v_mfma_f32_16x16x32_bf16 v[100:103], v[164:167], v[188:191], v[100:103]
	v_mfma_f32_16x16x32_bf16 v[92:95], v[172:175], v[188:191], v[92:95]
	v_mfma_f32_16x16x32_bf16 v[84:87], v[164:167], v[196:199], v[84:87]
	v_mfma_f32_16x16x32_bf16 v[76:79], v[172:175], v[196:199], v[76:79]
	v_mfma_f32_16x16x32_bf16 v[68:71], v[164:167], v[204:207], v[68:71]
	v_mfma_f32_16x16x32_bf16 v[64:67], v[172:175], v[204:207], v[64:67]
	v_mfma_f32_16x16x32_bf16 v[116:119], v[168:171], v[184:187], v[116:119]
	v_mfma_f32_16x16x32_bf16 v[108:111], v[176:179], v[184:187], v[108:111]
	v_mfma_f32_16x16x32_bf16 v[100:103], v[168:171], v[192:195], v[100:103]
	v_mfma_f32_16x16x32_bf16 v[92:95], v[176:179], v[192:195], v[92:95]
	v_mfma_f32_16x16x32_bf16 v[84:87], v[168:171], v[200:203], v[84:87]
	v_mfma_f32_16x16x32_bf16 v[76:79], v[176:179], v[200:203], v[76:79]
	v_mfma_f32_16x16x32_bf16 v[68:71], v[168:171], v[208:211], v[68:71]
	v_mfma_f32_16x16x32_bf16 v[64:67], v[176:179], v[208:211], v[64:67]
	s_barrier
	ds_read_b128 v[180:183], v147 offset:16384
	ds_read_b128 v[184:187], v147 offset:17408
	ds_read_b128 v[188:191], v147 offset:18432
	ds_read_b128 v[192:195], v147 offset:19456
	ds_read_b128 v[196:199], v147 offset:20480
	ds_read_b128 v[200:203], v147 offset:21504
	ds_read_b128 v[204:207], v147 offset:22528
	ds_read_b128 v[208:211], v147 offset:23552
	s_setprio 0
	s_mov_b32 m0, s92
	v_lshl_add_u64 v[140:141], s[52:53], 0, v[132:133]
	global_load_lds_dwordx4 v[140:141], off
	v_lshl_add_u64 v[212:213], s[52:53], 0, v[128:129]
	s_mov_b32 m0, s89
	v_lshl_add_u64 v[214:215], s[56:57], 0, v[132:133]
	global_load_lds_dwordx4 v[212:213], off
	s_mov_b32 m0, s91
	v_lshl_add_u64 v[216:217], s[54:55], 0, v[130:131]
	global_load_lds_dwordx4 v[214:215], off
	v_lshl_add_u64 v[214:215], s[56:57], 0, v[128:129]
	s_mov_b32 m0, s90
	v_lshl_add_u64 v[220:221], v[216:217], 0, s[6:7]
	global_load_lds_dwordx4 v[214:215], off
	s_mov_b32 m0, s62
	v_lshl_add_u64 v[214:215], s[54:55], 0, v[134:135]
	global_load_lds_dwordx4 v[214:215], off
	s_mov_b32 m0, s63
	s_nop 0
	global_load_lds_dwordx4 v[220:221], off
	s_setprio 1
	s_waitcnt vmcnt(8) lgkmcnt(0)
	s_barrier
	v_mfma_f32_16x16x32_bf16 v[60:63], v[148:151], v[180:183], v[60:63]
	v_mfma_f32_16x16x32_bf16 v[56:59], v[156:159], v[180:183], v[56:59]
	v_mfma_f32_16x16x32_bf16 v[52:55], v[148:151], v[188:191], v[52:55]
	v_mfma_f32_16x16x32_bf16 v[44:47], v[156:159], v[188:191], v[44:47]
	v_mfma_f32_16x16x32_bf16 v[36:39], v[148:151], v[196:199], v[36:39]
	v_mfma_f32_16x16x32_bf16 v[28:31], v[156:159], v[196:199], v[28:31]
	v_mfma_f32_16x16x32_bf16 v[20:23], v[148:151], v[204:207], v[20:23]
	v_mfma_f32_16x16x32_bf16 v[12:15], v[156:159], v[204:207], v[12:15]
	v_mfma_f32_16x16x32_bf16 v[60:63], v[152:155], v[184:187], v[60:63]
	v_mfma_f32_16x16x32_bf16 v[56:59], v[160:163], v[184:187], v[56:59]
	v_mfma_f32_16x16x32_bf16 v[52:55], v[152:155], v[192:195], v[52:55]
	v_mfma_f32_16x16x32_bf16 v[44:47], v[160:163], v[192:195], v[44:47]
	v_mfma_f32_16x16x32_bf16 v[36:39], v[152:155], v[200:203], v[36:39]
	v_mfma_f32_16x16x32_bf16 v[28:31], v[160:163], v[200:203], v[28:31]
	v_mfma_f32_16x16x32_bf16 v[20:23], v[152:155], v[208:211], v[20:23]
	v_mfma_f32_16x16x32_bf16 v[12:15], v[160:163], v[208:211], v[12:15]
	v_mfma_f32_16x16x32_bf16 v[48:51], v[164:167], v[180:183], v[48:51]
	v_mfma_f32_16x16x32_bf16 v[40:43], v[172:175], v[180:183], v[40:43]
	v_mfma_f32_16x16x32_bf16 v[32:35], v[164:167], v[188:191], v[32:35]
	v_mfma_f32_16x16x32_bf16 v[24:27], v[172:175], v[188:191], v[24:27]
	v_mfma_f32_16x16x32_bf16 v[16:19], v[164:167], v[196:199], v[16:19]
	v_mfma_f32_16x16x32_bf16 v[8:11], v[172:175], v[196:199], v[8:11]
	v_mfma_f32_16x16x32_bf16 v[4:7], v[164:167], v[204:207], v[4:7]
	v_mfma_f32_16x16x32_bf16 v[0:3], v[172:175], v[204:207], v[0:3]
	v_mfma_f32_16x16x32_bf16 v[48:51], v[168:171], v[184:187], v[48:51]
	v_mfma_f32_16x16x32_bf16 v[40:43], v[176:179], v[184:187], v[40:43]
	v_mfma_f32_16x16x32_bf16 v[32:35], v[168:171], v[192:195], v[32:35]
	v_mfma_f32_16x16x32_bf16 v[24:27], v[176:179], v[192:195], v[24:27]
	v_mfma_f32_16x16x32_bf16 v[16:19], v[168:171], v[200:203], v[16:19]
	v_mfma_f32_16x16x32_bf16 v[8:11], v[176:179], v[200:203], v[8:11]
	v_mfma_f32_16x16x32_bf16 v[4:7], v[168:171], v[208:211], v[4:7]
	v_mfma_f32_16x16x32_bf16 v[0:3], v[176:179], v[208:211], v[0:3]
	s_barrier
	s_setprio 0
	v_add_u32_e32 v160, s88, v143
	v_add_u32_e32 v176, s87, v143
	ds_read_b128 v[148:151], v160
	ds_read_b128 v[152:155], v160 offset:1024
	ds_read_b128 v[156:159], v160 offset:2048
	ds_read_b128 v[160:163], v160 offset:3072
	ds_read_b128 v[164:167], v176
	ds_read_b128 v[168:171], v176 offset:1024
	ds_read_b128 v[172:175], v176 offset:2048
	ds_read_b128 v[176:179], v176 offset:3072
	s_mov_b32 m0, s64
	v_lshl_add_u64 v[220:221], v[214:215], 0, s[4:5]
	ds_read_b128 v[180:183], v147 offset:32768
	ds_read_b128 v[184:187], v147 offset:33792
	ds_read_b128 v[188:191], v147 offset:34816
	ds_read_b128 v[192:195], v147 offset:35840
	ds_read_b128 v[196:199], v147 offset:36864
	ds_read_b128 v[200:203], v147 offset:37888
	ds_read_b128 v[204:207], v147 offset:38912
	ds_read_b128 v[208:211], v147 offset:39936
	global_load_lds_dwordx4 v[220:221], off
	s_mov_b32 m0, s65
	v_lshl_add_u64 v[220:221], v[216:217], 0, s[8:9]
	global_load_lds_dwordx4 v[220:221], off
	s_setprio 1
	s_waitcnt vmcnt(8) lgkmcnt(0)
	s_barrier
	v_mfma_f32_16x16x32_bf16 v[124:127], v[148:151], v[180:183], v[124:127]
	v_mfma_f32_16x16x32_bf16 v[120:123], v[156:159], v[180:183], v[120:123]
	v_mfma_f32_16x16x32_bf16 v[112:115], v[148:151], v[188:191], v[112:115]
	v_mfma_f32_16x16x32_bf16 v[104:107], v[156:159], v[188:191], v[104:107]
	v_mfma_f32_16x16x32_bf16 v[96:99], v[148:151], v[196:199], v[96:99]
	v_mfma_f32_16x16x32_bf16 v[88:91], v[156:159], v[196:199], v[88:91]
	v_mfma_f32_16x16x32_bf16 v[80:83], v[148:151], v[204:207], v[80:83]
	v_mfma_f32_16x16x32_bf16 v[72:75], v[156:159], v[204:207], v[72:75]
	v_mfma_f32_16x16x32_bf16 v[124:127], v[152:155], v[184:187], v[124:127]
	v_mfma_f32_16x16x32_bf16 v[120:123], v[160:163], v[184:187], v[120:123]
	v_mfma_f32_16x16x32_bf16 v[112:115], v[152:155], v[192:195], v[112:115]
	v_mfma_f32_16x16x32_bf16 v[104:107], v[160:163], v[192:195], v[104:107]
	v_mfma_f32_16x16x32_bf16 v[96:99], v[152:155], v[200:203], v[96:99]
	v_mfma_f32_16x16x32_bf16 v[88:91], v[160:163], v[200:203], v[88:91]
	v_mfma_f32_16x16x32_bf16 v[80:83], v[152:155], v[208:211], v[80:83]
	v_mfma_f32_16x16x32_bf16 v[72:75], v[160:163], v[208:211], v[72:75]
	v_mfma_f32_16x16x32_bf16 v[116:119], v[164:167], v[180:183], v[116:119]
	v_mfma_f32_16x16x32_bf16 v[108:111], v[172:175], v[180:183], v[108:111]
	v_mfma_f32_16x16x32_bf16 v[100:103], v[164:167], v[188:191], v[100:103]
	v_mfma_f32_16x16x32_bf16 v[92:95], v[172:175], v[188:191], v[92:95]
	v_mfma_f32_16x16x32_bf16 v[84:87], v[164:167], v[196:199], v[84:87]
	v_mfma_f32_16x16x32_bf16 v[76:79], v[172:175], v[196:199], v[76:79]
	v_mfma_f32_16x16x32_bf16 v[68:71], v[164:167], v[204:207], v[68:71]
	v_mfma_f32_16x16x32_bf16 v[64:67], v[172:175], v[204:207], v[64:67]
	v_mfma_f32_16x16x32_bf16 v[116:119], v[168:171], v[184:187], v[116:119]
	v_mfma_f32_16x16x32_bf16 v[108:111], v[176:179], v[184:187], v[108:111]
	v_mfma_f32_16x16x32_bf16 v[100:103], v[168:171], v[192:195], v[100:103]
	v_mfma_f32_16x16x32_bf16 v[92:95], v[176:179], v[192:195], v[92:95]
	v_mfma_f32_16x16x32_bf16 v[84:87], v[168:171], v[200:203], v[84:87]
	v_mfma_f32_16x16x32_bf16 v[76:79], v[176:179], v[200:203], v[76:79]
	v_mfma_f32_16x16x32_bf16 v[68:71], v[168:171], v[208:211], v[68:71]
	v_mfma_f32_16x16x32_bf16 v[64:67], v[176:179], v[208:211], v[64:67]
	s_barrier
	ds_read_b128 v[180:183], v147 offset:49152
	ds_read_b128 v[184:187], v147 offset:50176
	ds_read_b128 v[188:191], v147 offset:51200
	ds_read_b128 v[192:195], v147 offset:52224
	ds_read_b128 v[196:199], v147 offset:53248
	ds_read_b128 v[200:203], v147 offset:54272
	ds_read_b128 v[204:207], v147 offset:55296
	ds_read_b128 v[208:211], v147 offset:56320
	s_setprio 0
	s_mov_b32 m0, s86
	v_lshl_add_u64 v[140:141], v[140:141], 0, s[18:19]
	global_load_lds_dwordx4 v[140:141], off
	s_mov_b32 m0, s84
	v_lshl_add_u64 v[140:141], v[212:213], 0, s[18:19]
	global_load_lds_dwordx4 v[140:141], off
	s_mov_b32 m0, s85
	v_lshl_add_u64 v[140:141], s[50:51], 0, v[132:133]
	global_load_lds_dwordx4 v[140:141], off
	s_mov_b32 m0, s83
	v_lshl_add_u64 v[140:141], s[50:51], 0, v[128:129]
	global_load_lds_dwordx4 v[140:141], off
	s_mov_b32 m0, s67
	v_lshl_add_u64 v[140:141], v[214:215], 0, s[18:19]
	global_load_lds_dwordx4 v[140:141], off
	s_mov_b32 m0, s72
	v_lshl_add_u64 v[140:141], v[216:217], 0, s[20:21]
	global_load_lds_dwordx4 v[140:141], off
	s_setprio 1
	s_waitcnt vmcnt(8) lgkmcnt(0)
	s_barrier
	v_mfma_f32_16x16x32_bf16 v[60:63], v[148:151], v[180:183], v[60:63]
	v_mfma_f32_16x16x32_bf16 v[56:59], v[156:159], v[180:183], v[56:59]
	v_mfma_f32_16x16x32_bf16 v[52:55], v[148:151], v[188:191], v[52:55]
	v_mfma_f32_16x16x32_bf16 v[44:47], v[156:159], v[188:191], v[44:47]
	v_mfma_f32_16x16x32_bf16 v[36:39], v[148:151], v[196:199], v[36:39]
	v_mfma_f32_16x16x32_bf16 v[28:31], v[156:159], v[196:199], v[28:31]
	v_mfma_f32_16x16x32_bf16 v[20:23], v[148:151], v[204:207], v[20:23]
	v_mfma_f32_16x16x32_bf16 v[12:15], v[156:159], v[204:207], v[12:15]
	v_mfma_f32_16x16x32_bf16 v[60:63], v[152:155], v[184:187], v[60:63]
	v_mfma_f32_16x16x32_bf16 v[56:59], v[160:163], v[184:187], v[56:59]
	v_mfma_f32_16x16x32_bf16 v[52:55], v[152:155], v[192:195], v[52:55]
	v_mfma_f32_16x16x32_bf16 v[44:47], v[160:163], v[192:195], v[44:47]
	v_mfma_f32_16x16x32_bf16 v[36:39], v[152:155], v[200:203], v[36:39]
	v_mfma_f32_16x16x32_bf16 v[28:31], v[160:163], v[200:203], v[28:31]
	v_mfma_f32_16x16x32_bf16 v[20:23], v[152:155], v[208:211], v[20:23]
	v_mfma_f32_16x16x32_bf16 v[12:15], v[160:163], v[208:211], v[12:15]
	v_mfma_f32_16x16x32_bf16 v[48:51], v[164:167], v[180:183], v[48:51]
	v_mfma_f32_16x16x32_bf16 v[40:43], v[172:175], v[180:183], v[40:43]
	v_mfma_f32_16x16x32_bf16 v[32:35], v[164:167], v[188:191], v[32:35]
	v_mfma_f32_16x16x32_bf16 v[24:27], v[172:175], v[188:191], v[24:27]
	v_mfma_f32_16x16x32_bf16 v[16:19], v[164:167], v[196:199], v[16:19]
	v_mfma_f32_16x16x32_bf16 v[8:11], v[172:175], v[196:199], v[8:11]
	v_mfma_f32_16x16x32_bf16 v[4:7], v[164:167], v[204:207], v[4:7]
	v_mfma_f32_16x16x32_bf16 v[0:3], v[172:175], v[204:207], v[0:3]
	v_mfma_f32_16x16x32_bf16 v[48:51], v[168:171], v[184:187], v[48:51]
	v_mfma_f32_16x16x32_bf16 v[40:43], v[176:179], v[184:187], v[40:43]
	v_mfma_f32_16x16x32_bf16 v[32:35], v[168:171], v[192:195], v[32:35]
	v_mfma_f32_16x16x32_bf16 v[24:27], v[176:179], v[192:195], v[24:27]
	v_mfma_f32_16x16x32_bf16 v[16:19], v[168:171], v[200:203], v[16:19]
	v_mfma_f32_16x16x32_bf16 v[8:11], v[176:179], v[200:203], v[8:11]
	v_mfma_f32_16x16x32_bf16 v[4:7], v[168:171], v[208:211], v[4:7]
	v_mfma_f32_16x16x32_bf16 v[0:3], v[176:179], v[208:211], v[0:3]
	s_barrier
	s_setprio 0
	s_andn2_b64 vcc, exec, s[48:49]
	s_mov_b64 s[50:51], -1
	s_mov_b64 s[48:49], 0
	s_mov_b64 s[52:53], 0x100
	s_cbranch_vccz .LBB0_585
	s_and_b64 vcc, exec, s[22:23]
	s_cbranch_vccz .LBB0_588
	s_barrier

.LBB0_661:
	s_add_u32 s64, s44, 0x100
	s_addc_u32 s65, s45, 0
	s_mov_b32 s66, -2
	s_waitcnt lgkmcnt(0)
	s_waitcnt vmcnt(0)
	ds_read_b128 v[144:147], v151
	ds_read_b128 v[156:159], v151 offset:1024
	ds_read_b128 v[160:163], v151 offset:2048
	ds_read_b128 v[164:167], v151 offset:3072
	ds_read_b128 v[168:171], v152
	ds_read_b128 v[172:175], v152 offset:1024
	ds_read_b128 v[176:179], v152 offset:2048
	ds_read_b128 v[180:183], v152 offset:3072
	s_add_u32 s44, s42, 0x100
	s_addc_u32 s45, s43, 0
	s_cmp_eq_u32 s66, 40
	s_cselect_b32 s69, s1, s45
	s_cselect_b32 s68, s0, s44
	s_cselect_b32 s47, s41, s65
	s_cselect_b32 s46, s40, s64
	v_lshl_add_u64 v[216:217], s[42:43], 0, v[136:137]
	s_add_i32 m0, s48, 0xc000
	ds_read_b128 v[184:187], v153
	ds_read_b128 v[188:191], v153 offset:1024
	ds_read_b128 v[192:195], v153 offset:2048
	ds_read_b128 v[196:199], v153 offset:3072
	ds_read_b128 v[200:203], v153 offset:4096
	ds_read_b128 v[204:207], v153 offset:5120
	ds_read_b128 v[208:211], v153 offset:6144
	ds_read_b128 v[212:215], v153 offset:7168
	global_load_lds_dwordx4 v[216:217], off
	s_add_i32 m0, s48, 0xe000
	v_lshl_add_u64 v[216:217], s[42:43], 0, v[138:139]
	global_load_lds_dwordx4 v[216:217], off
	s_setprio 1
	s_waitcnt vmcnt(8) lgkmcnt(0)
	s_barrier
	v_mfma_f32_16x16x32_bf16 v[124:127], v[144:147], v[184:187], 0
	v_mfma_f32_16x16x32_bf16 v[120:123], v[160:163], v[184:187], 0
	v_mfma_f32_16x16x32_bf16 v[108:111], v[144:147], v[192:195], 0
	v_mfma_f32_16x16x32_bf16 v[104:107], v[160:163], v[192:195], 0
	v_mfma_f32_16x16x32_bf16 v[92:95], v[144:147], v[200:203], 0
	v_mfma_f32_16x16x32_bf16 v[88:91], v[160:163], v[200:203], 0
	v_mfma_f32_16x16x32_bf16 v[76:79], v[144:147], v[208:211], 0
	v_mfma_f32_16x16x32_bf16 v[72:75], v[160:163], v[208:211], 0
	v_mfma_f32_16x16x32_bf16 v[124:127], v[156:159], v[188:191], v[124:127]
	v_mfma_f32_16x16x32_bf16 v[120:123], v[164:167], v[188:191], v[120:123]
	v_mfma_f32_16x16x32_bf16 v[108:111], v[156:159], v[196:199], v[108:111]
	v_mfma_f32_16x16x32_bf16 v[104:107], v[164:167], v[196:199], v[104:107]
	v_mfma_f32_16x16x32_bf16 v[92:95], v[156:159], v[204:207], v[92:95]
	v_mfma_f32_16x16x32_bf16 v[88:91], v[164:167], v[204:207], v[88:91]
	v_mfma_f32_16x16x32_bf16 v[76:79], v[156:159], v[212:215], v[76:79]
	v_mfma_f32_16x16x32_bf16 v[72:75], v[164:167], v[212:215], v[72:75]
	v_mfma_f32_16x16x32_bf16 v[116:119], v[168:171], v[184:187], 0
	v_mfma_f32_16x16x32_bf16 v[112:115], v[176:179], v[184:187], 0
	v_mfma_f32_16x16x32_bf16 v[100:103], v[168:171], v[192:195], 0
	v_mfma_f32_16x16x32_bf16 v[96:99], v[176:179], v[192:195], 0
	v_mfma_f32_16x16x32_bf16 v[84:87], v[168:171], v[200:203], 0
	v_mfma_f32_16x16x32_bf16 v[80:83], v[176:179], v[200:203], 0
	v_mfma_f32_16x16x32_bf16 v[68:71], v[168:171], v[208:211], 0
	v_mfma_f32_16x16x32_bf16 v[64:67], v[176:179], v[208:211], 0
	v_mfma_f32_16x16x32_bf16 v[116:119], v[172:175], v[188:191], v[116:119]
	v_mfma_f32_16x16x32_bf16 v[112:115], v[180:183], v[188:191], v[112:115]
	v_mfma_f32_16x16x32_bf16 v[100:103], v[172:175], v[196:199], v[100:103]
	v_mfma_f32_16x16x32_bf16 v[96:99], v[180:183], v[196:199], v[96:99]
	v_mfma_f32_16x16x32_bf16 v[84:87], v[172:175], v[204:207], v[84:87]
	v_mfma_f32_16x16x32_bf16 v[80:83], v[180:183], v[204:207], v[80:83]
	v_mfma_f32_16x16x32_bf16 v[68:71], v[172:175], v[212:215], v[68:71]
	v_mfma_f32_16x16x32_bf16 v[64:67], v[180:183], v[212:215], v[64:67]
	s_barrier
	ds_read_b128 v[184:187], v153 offset:16384
	ds_read_b128 v[188:191], v153 offset:17408
	ds_read_b128 v[192:195], v153 offset:18432
	ds_read_b128 v[196:199], v153 offset:19456
	ds_read_b128 v[200:203], v153 offset:20480
	ds_read_b128 v[204:207], v153 offset:21504
	ds_read_b128 v[208:211], v153 offset:22528
	ds_read_b128 v[212:215], v153 offset:23552
	s_setprio 0
	s_add_i32 s42, s59, s35
	s_mov_b32 m0, s42
	v_lshl_add_u64 v[216:217], s[46:47], 0, v[130:131]
	global_load_lds_dwordx4 v[216:217], off
	s_add_i32 m0, s42, 0x2000
	s_add_u32 s42, s46, 0xb0000
	v_lshl_add_u64 v[220:221], s[46:47], 0, v[134:135]
	s_addc_u32 s43, s47, 0
	s_add_i32 s67, s60, s35
	global_load_lds_dwordx4 v[220:221], off
	v_lshl_add_u64 v[224:225], s[42:43], 0, v[130:131]
	s_mov_b32 m0, s67
	v_lshl_add_u64 v[226:227], s[68:69], 0, v[132:133]
	global_load_lds_dwordx4 v[224:225], off
	v_lshl_add_u64 v[224:225], s[42:43], 0, v[134:135]
	s_add_i32 m0, s67, 0x2000
	v_lshl_add_u64 v[228:229], v[226:227], 0, s[14:15]
	global_load_lds_dwordx4 v[224:225], off
	s_mov_b32 m0, s48
	v_lshl_add_u64 v[224:225], s[68:69], 0, v[128:129]
	global_load_lds_dwordx4 v[224:225], off
	s_mov_b32 m0, s49
	s_nop 0
	global_load_lds_dwordx4 v[228:229], off
	s_setprio 1
	s_waitcnt vmcnt(8) lgkmcnt(0)
	s_barrier
	v_mfma_f32_16x16x32_bf16 v[60:63], v[144:147], v[184:187], 0
	v_mfma_f32_16x16x32_bf16 v[56:59], v[160:163], v[184:187], 0
	v_mfma_f32_16x16x32_bf16 v[44:47], v[144:147], v[192:195], 0
	v_mfma_f32_16x16x32_bf16 v[40:43], v[160:163], v[192:195], 0
	v_mfma_f32_16x16x32_bf16 v[28:31], v[144:147], v[200:203], 0
	v_mfma_f32_16x16x32_bf16 v[24:27], v[160:163], v[200:203], 0
	v_mfma_f32_16x16x32_bf16 v[12:15], v[144:147], v[208:211], 0
	v_mfma_f32_16x16x32_bf16 v[8:11], v[160:163], v[208:211], 0
	v_mfma_f32_16x16x32_bf16 v[60:63], v[156:159], v[188:191], v[60:63]
	v_mfma_f32_16x16x32_bf16 v[56:59], v[164:167], v[188:191], v[56:59]
	v_mfma_f32_16x16x32_bf16 v[44:47], v[156:159], v[196:199], v[44:47]
	v_mfma_f32_16x16x32_bf16 v[40:43], v[164:167], v[196:199], v[40:43]
	v_mfma_f32_16x16x32_bf16 v[28:31], v[156:159], v[204:207], v[28:31]
	v_mfma_f32_16x16x32_bf16 v[24:27], v[164:167], v[204:207], v[24:27]
	v_mfma_f32_16x16x32_bf16 v[12:15], v[156:159], v[212:215], v[12:15]
	v_mfma_f32_16x16x32_bf16 v[8:11], v[164:167], v[212:215], v[8:11]
	v_mfma_f32_16x16x32_bf16 v[52:55], v[168:171], v[184:187], 0
	v_mfma_f32_16x16x32_bf16 v[48:51], v[176:179], v[184:187], 0
	v_mfma_f32_16x16x32_bf16 v[36:39], v[168:171], v[192:195], 0
	v_mfma_f32_16x16x32_bf16 v[32:35], v[176:179], v[192:195], 0
	v_mfma_f32_16x16x32_bf16 v[20:23], v[168:171], v[200:203], 0
	v_mfma_f32_16x16x32_bf16 v[16:19], v[176:179], v[200:203], 0
	v_mfma_f32_16x16x32_bf16 v[4:7], v[168:171], v[208:211], 0
	v_mfma_f32_16x16x32_bf16 v[0:3], v[176:179], v[208:211], 0
	v_mfma_f32_16x16x32_bf16 v[52:55], v[172:175], v[188:191], v[52:55]
	v_mfma_f32_16x16x32_bf16 v[48:51], v[180:183], v[188:191], v[48:51]
	v_mfma_f32_16x16x32_bf16 v[36:39], v[172:175], v[196:199], v[36:39]
	v_mfma_f32_16x16x32_bf16 v[32:35], v[180:183], v[196:199], v[32:35]
	v_mfma_f32_16x16x32_bf16 v[20:23], v[172:175], v[204:207], v[20:23]
	v_mfma_f32_16x16x32_bf16 v[16:19], v[180:183], v[204:207], v[16:19]
	v_mfma_f32_16x16x32_bf16 v[4:7], v[172:175], v[212:215], v[4:7]
	v_mfma_f32_16x16x32_bf16 v[0:3], v[180:183], v[212:215], v[0:3]
	s_barrier
	s_setprio 0
	s_add_i32 s42, 0, 0x18000
	v_add_u32_e32 v155, s42, v149
	s_add_i32 s67, 0, 0x1c000
	ds_read_b128 v[144:147], v155
	ds_read_b128 v[156:159], v155 offset:1024
	ds_read_b128 v[160:163], v155 offset:2048
	ds_read_b128 v[164:167], v155 offset:3072
	v_add_u32_e32 v155, s67, v149
	ds_read_b128 v[168:171], v155
	ds_read_b128 v[172:175], v155 offset:1024
	ds_read_b128 v[176:179], v155 offset:2048
	ds_read_b128 v[180:183], v155 offset:3072
	s_mov_b32 m0, s50
	v_lshl_add_u64 v[228:229], v[224:225], 0, s[12:13]
	ds_read_b128 v[184:187], v153 offset:32768
	ds_read_b128 v[188:191], v153 offset:33792
	ds_read_b128 v[192:195], v153 offset:34816
	ds_read_b128 v[196:199], v153 offset:35840
	ds_read_b128 v[200:203], v153 offset:36864
	ds_read_b128 v[204:207], v153 offset:37888
	ds_read_b128 v[208:211], v153 offset:38912
	ds_read_b128 v[212:215], v153 offset:39936
	global_load_lds_dwordx4 v[228:229], off
	s_mov_b32 m0, s51
	v_lshl_add_u64 v[228:229], v[226:227], 0, s[16:17]
	global_load_lds_dwordx4 v[228:229], off
	s_setprio 1
	s_waitcnt vmcnt(8) lgkmcnt(0)
	s_barrier
	v_mfma_f32_16x16x32_bf16 v[124:127], v[144:147], v[184:187], v[124:127]
	v_mfma_f32_16x16x32_bf16 v[120:123], v[160:163], v[184:187], v[120:123]
	v_mfma_f32_16x16x32_bf16 v[108:111], v[144:147], v[192:195], v[108:111]
	v_mfma_f32_16x16x32_bf16 v[104:107], v[160:163], v[192:195], v[104:107]
	v_mfma_f32_16x16x32_bf16 v[92:95], v[144:147], v[200:203], v[92:95]
	v_mfma_f32_16x16x32_bf16 v[88:91], v[160:163], v[200:203], v[88:91]
	v_mfma_f32_16x16x32_bf16 v[76:79], v[144:147], v[208:211], v[76:79]
	v_mfma_f32_16x16x32_bf16 v[72:75], v[160:163], v[208:211], v[72:75]
	v_mfma_f32_16x16x32_bf16 v[124:127], v[156:159], v[188:191], v[124:127]
	v_mfma_f32_16x16x32_bf16 v[120:123], v[164:167], v[188:191], v[120:123]
	v_mfma_f32_16x16x32_bf16 v[108:111], v[156:159], v[196:199], v[108:111]
	v_mfma_f32_16x16x32_bf16 v[104:107], v[164:167], v[196:199], v[104:107]
	v_mfma_f32_16x16x32_bf16 v[92:95], v[156:159], v[204:207], v[92:95]
	v_mfma_f32_16x16x32_bf16 v[88:91], v[164:167], v[204:207], v[88:91]
	v_mfma_f32_16x16x32_bf16 v[76:79], v[156:159], v[212:215], v[76:79]
	v_mfma_f32_16x16x32_bf16 v[72:75], v[164:167], v[212:215], v[72:75]
	v_mfma_f32_16x16x32_bf16 v[116:119], v[168:171], v[184:187], v[116:119]
	v_mfma_f32_16x16x32_bf16 v[112:115], v[176:179], v[184:187], v[112:115]
	v_mfma_f32_16x16x32_bf16 v[100:103], v[168:171], v[192:195], v[100:103]
	v_mfma_f32_16x16x32_bf16 v[96:99], v[176:179], v[192:195], v[96:99]
	v_mfma_f32_16x16x32_bf16 v[84:87], v[168:171], v[200:203], v[84:87]
	v_mfma_f32_16x16x32_bf16 v[80:83], v[176:179], v[200:203], v[80:83]
	v_mfma_f32_16x16x32_bf16 v[68:71], v[168:171], v[208:211], v[68:71]
	v_mfma_f32_16x16x32_bf16 v[64:67], v[176:179], v[208:211], v[64:67]
	v_mfma_f32_16x16x32_bf16 v[116:119], v[172:175], v[188:191], v[116:119]
	v_mfma_f32_16x16x32_bf16 v[112:115], v[180:183], v[188:191], v[112:115]
	v_mfma_f32_16x16x32_bf16 v[100:103], v[172:175], v[196:199], v[100:103]
	v_mfma_f32_16x16x32_bf16 v[96:99], v[180:183], v[196:199], v[96:99]
	v_mfma_f32_16x16x32_bf16 v[84:87], v[172:175], v[204:207], v[84:87]
	v_mfma_f32_16x16x32_bf16 v[80:83], v[180:183], v[204:207], v[80:83]
	v_mfma_f32_16x16x32_bf16 v[68:71], v[172:175], v[212:215], v[68:71]
	v_mfma_f32_16x16x32_bf16 v[64:67], v[180:183], v[212:215], v[64:67]
	s_barrier
	ds_read_b128 v[184:187], v153 offset:49152
	ds_read_b128 v[188:191], v153 offset:50176
	ds_read_b128 v[192:195], v153 offset:51200
	ds_read_b128 v[196:199], v153 offset:52224
	ds_read_b128 v[200:203], v153 offset:53248
	ds_read_b128 v[204:207], v153 offset:54272
	ds_read_b128 v[208:211], v153 offset:55296
	ds_read_b128 v[212:215], v153 offset:56320
	s_setprio 0
	s_add_i32 s42, s42, s35
	s_mov_b32 m0, s42
	v_lshl_add_u64 v[216:217], v[216:217], 0, s[24:25]
	global_load_lds_dwordx4 v[216:217], off
	s_add_i32 m0, s42, 0x2000
	s_add_u32 s42, s46, 0xb0080
	v_lshl_add_u64 v[216:217], v[220:221], 0, s[24:25]
	s_addc_u32 s43, s47, 0
	s_add_i32 s46, s67, s35
	global_load_lds_dwordx4 v[216:217], off
	s_mov_b32 m0, s46
	v_lshl_add_u64 v[216:217], s[42:43], 0, v[130:131]
	global_load_lds_dwordx4 v[216:217], off
	s_add_i32 m0, s46, 0x2000
	v_lshl_add_u64 v[216:217], s[42:43], 0, v[134:135]
	global_load_lds_dwordx4 v[216:217], off
	s_mov_b32 m0, s53
	v_lshl_add_u64 v[216:217], v[224:225], 0, s[24:25]
	global_load_lds_dwordx4 v[216:217], off
	s_mov_b32 m0, s54
	v_lshl_add_u64 v[216:217], v[226:227], 0, s[36:37]
	global_load_lds_dwordx4 v[216:217], off
	s_setprio 1
	s_waitcnt vmcnt(8) lgkmcnt(0)
	s_barrier
	v_mfma_f32_16x16x32_bf16 v[60:63], v[144:147], v[184:187], v[60:63]
	v_mfma_f32_16x16x32_bf16 v[56:59], v[160:163], v[184:187], v[56:59]
	v_mfma_f32_16x16x32_bf16 v[44:47], v[144:147], v[192:195], v[44:47]
	v_mfma_f32_16x16x32_bf16 v[40:43], v[160:163], v[192:195], v[40:43]
	v_mfma_f32_16x16x32_bf16 v[28:31], v[144:147], v[200:203], v[28:31]
	v_mfma_f32_16x16x32_bf16 v[24:27], v[160:163], v[200:203], v[24:27]
	v_mfma_f32_16x16x32_bf16 v[12:15], v[144:147], v[208:211], v[12:15]
	v_mfma_f32_16x16x32_bf16 v[8:11], v[160:163], v[208:211], v[8:11]
	v_mfma_f32_16x16x32_bf16 v[60:63], v[156:159], v[188:191], v[60:63]
	v_mfma_f32_16x16x32_bf16 v[56:59], v[164:167], v[188:191], v[56:59]
	v_mfma_f32_16x16x32_bf16 v[44:47], v[156:159], v[196:199], v[44:47]
	v_mfma_f32_16x16x32_bf16 v[40:43], v[164:167], v[196:199], v[40:43]
	v_mfma_f32_16x16x32_bf16 v[28:31], v[156:159], v[204:207], v[28:31]
	v_mfma_f32_16x16x32_bf16 v[24:27], v[164:167], v[204:207], v[24:27]
	v_mfma_f32_16x16x32_bf16 v[12:15], v[156:159], v[212:215], v[12:15]
	v_mfma_f32_16x16x32_bf16 v[8:11], v[164:167], v[212:215], v[8:11]
	v_mfma_f32_16x16x32_bf16 v[52:55], v[168:171], v[184:187], v[52:55]
	v_mfma_f32_16x16x32_bf16 v[48:51], v[176:179], v[184:187], v[48:51]
	v_mfma_f32_16x16x32_bf16 v[36:39], v[168:171], v[192:195], v[36:39]
	v_mfma_f32_16x16x32_bf16 v[32:35], v[176:179], v[192:195], v[32:35]
	v_mfma_f32_16x16x32_bf16 v[20:23], v[168:171], v[200:203], v[20:23]
	v_mfma_f32_16x16x32_bf16 v[16:19], v[176:179], v[200:203], v[16:19]
	v_mfma_f32_16x16x32_bf16 v[4:7], v[168:171], v[208:211], v[4:7]
	v_mfma_f32_16x16x32_bf16 v[0:3], v[176:179], v[208:211], v[0:3]
	v_mfma_f32_16x16x32_bf16 v[52:55], v[172:175], v[188:191], v[52:55]
	v_mfma_f32_16x16x32_bf16 v[48:51], v[180:183], v[188:191], v[48:51]
	v_mfma_f32_16x16x32_bf16 v[36:39], v[172:175], v[196:199], v[36:39]
	v_mfma_f32_16x16x32_bf16 v[32:35], v[180:183], v[196:199], v[32:35]
	v_mfma_f32_16x16x32_bf16 v[20:23], v[172:175], v[204:207], v[20:23]
	v_mfma_f32_16x16x32_bf16 v[16:19], v[180:183], v[204:207], v[16:19]
	v_mfma_f32_16x16x32_bf16 v[4:7], v[172:175], v[212:215], v[4:7]
	v_mfma_f32_16x16x32_bf16 v[0:3], v[180:183], v[212:215], v[0:3]
	s_barrier
	s_setprio 0
	s_add_i32 s66, s66, 2
	s_add_u32 s64, s64, 0x100
	s_addc_u32 s65, s65, 0
	s_cmp_gt_u32 s66, 41
	s_mov_b64 s[42:43], s[44:45]
.LBB0_662:
	ds_read_b128 v[144:147], v151
	ds_read_b128 v[156:159], v151 offset:1024
	ds_read_b128 v[160:163], v151 offset:2048
	ds_read_b128 v[164:167], v151 offset:3072
	ds_read_b128 v[168:171], v152
	ds_read_b128 v[172:175], v152 offset:1024
	ds_read_b128 v[176:179], v152 offset:2048
	ds_read_b128 v[180:183], v152 offset:3072
	s_add_u32 s44, s42, 0x100
	s_addc_u32 s45, s43, 0
	s_cmp_eq_u32 s66, 40
	s_cselect_b32 s69, s1, s45
	s_cselect_b32 s68, s0, s44
	s_cselect_b32 s47, s41, s65
	s_cselect_b32 s46, s40, s64
	v_lshl_add_u64 v[216:217], s[42:43], 0, v[136:137]
	s_add_i32 m0, s48, 0xc000
	ds_read_b128 v[184:187], v153
	ds_read_b128 v[188:191], v153 offset:1024
	ds_read_b128 v[192:195], v153 offset:2048
	ds_read_b128 v[196:199], v153 offset:3072
	ds_read_b128 v[200:203], v153 offset:4096
	ds_read_b128 v[204:207], v153 offset:5120
	ds_read_b128 v[208:211], v153 offset:6144
	ds_read_b128 v[212:215], v153 offset:7168
	global_load_lds_dwordx4 v[216:217], off
	s_add_i32 m0, s48, 0xe000
	v_lshl_add_u64 v[216:217], s[42:43], 0, v[138:139]
	global_load_lds_dwordx4 v[216:217], off
	s_setprio 1
	s_waitcnt vmcnt(8) lgkmcnt(0)
	s_barrier
	v_mfma_f32_16x16x32_bf16 v[124:127], v[144:147], v[184:187], v[124:127]
	v_mfma_f32_16x16x32_bf16 v[120:123], v[160:163], v[184:187], v[120:123]
	v_mfma_f32_16x16x32_bf16 v[108:111], v[144:147], v[192:195], v[108:111]
	v_mfma_f32_16x16x32_bf16 v[104:107], v[160:163], v[192:195], v[104:107]
	v_mfma_f32_16x16x32_bf16 v[92:95], v[144:147], v[200:203], v[92:95]
	v_mfma_f32_16x16x32_bf16 v[88:91], v[160:163], v[200:203], v[88:91]
	v_mfma_f32_16x16x32_bf16 v[76:79], v[144:147], v[208:211], v[76:79]
	v_mfma_f32_16x16x32_bf16 v[72:75], v[160:163], v[208:211], v[72:75]
	v_mfma_f32_16x16x32_bf16 v[124:127], v[156:159], v[188:191], v[124:127]
	v_mfma_f32_16x16x32_bf16 v[120:123], v[164:167], v[188:191], v[120:123]
	v_mfma_f32_16x16x32_bf16 v[108:111], v[156:159], v[196:199], v[108:111]
	v_mfma_f32_16x16x32_bf16 v[104:107], v[164:167], v[196:199], v[104:107]
	v_mfma_f32_16x16x32_bf16 v[92:95], v[156:159], v[204:207], v[92:95]
	v_mfma_f32_16x16x32_bf16 v[88:91], v[164:167], v[204:207], v[88:91]
	v_mfma_f32_16x16x32_bf16 v[76:79], v[156:159], v[212:215], v[76:79]
	v_mfma_f32_16x16x32_bf16 v[72:75], v[164:167], v[212:215], v[72:75]
	v_mfma_f32_16x16x32_bf16 v[116:119], v[168:171], v[184:187], v[116:119]
	v_mfma_f32_16x16x32_bf16 v[112:115], v[176:179], v[184:187], v[112:115]
	v_mfma_f32_16x16x32_bf16 v[100:103], v[168:171], v[192:195], v[100:103]
	v_mfma_f32_16x16x32_bf16 v[96:99], v[176:179], v[192:195], v[96:99]
	v_mfma_f32_16x16x32_bf16 v[84:87], v[168:171], v[200:203], v[84:87]
	v_mfma_f32_16x16x32_bf16 v[80:83], v[176:179], v[200:203], v[80:83]
	v_mfma_f32_16x16x32_bf16 v[68:71], v[168:171], v[208:211], v[68:71]
	v_mfma_f32_16x16x32_bf16 v[64:67], v[176:179], v[208:211], v[64:67]
	v_mfma_f32_16x16x32_bf16 v[116:119], v[172:175], v[188:191], v[116:119]
	v_mfma_f32_16x16x32_bf16 v[112:115], v[180:183], v[188:191], v[112:115]
	v_mfma_f32_16x16x32_bf16 v[100:103], v[172:175], v[196:199], v[100:103]
	v_mfma_f32_16x16x32_bf16 v[96:99], v[180:183], v[196:199], v[96:99]
	v_mfma_f32_16x16x32_bf16 v[84:87], v[172:175], v[204:207], v[84:87]
	v_mfma_f32_16x16x32_bf16 v[80:83], v[180:183], v[204:207], v[80:83]
	v_mfma_f32_16x16x32_bf16 v[68:71], v[172:175], v[212:215], v[68:71]
	v_mfma_f32_16x16x32_bf16 v[64:67], v[180:183], v[212:215], v[64:67]
	s_barrier
	ds_read_b128 v[184:187], v153 offset:16384
	ds_read_b128 v[188:191], v153 offset:17408
	ds_read_b128 v[192:195], v153 offset:18432
	ds_read_b128 v[196:199], v153 offset:19456
	ds_read_b128 v[200:203], v153 offset:20480
	ds_read_b128 v[204:207], v153 offset:21504
	ds_read_b128 v[208:211], v153 offset:22528
	ds_read_b128 v[212:215], v153 offset:23552
	s_setprio 0
	s_add_i32 s42, s59, s35
	s_mov_b32 m0, s42
	v_lshl_add_u64 v[216:217], s[46:47], 0, v[130:131]
	global_load_lds_dwordx4 v[216:217], off
	s_add_i32 m0, s42, 0x2000
	s_add_u32 s42, s46, 0xb0000
	v_lshl_add_u64 v[220:221], s[46:47], 0, v[134:135]
	s_addc_u32 s43, s47, 0
	s_add_i32 s67, s60, s35
	global_load_lds_dwordx4 v[220:221], off
	v_lshl_add_u64 v[224:225], s[42:43], 0, v[130:131]
	s_mov_b32 m0, s67
	v_lshl_add_u64 v[226:227], s[68:69], 0, v[132:133]
	global_load_lds_dwordx4 v[224:225], off
	v_lshl_add_u64 v[224:225], s[42:43], 0, v[134:135]
	s_add_i32 m0, s67, 0x2000
	v_lshl_add_u64 v[228:229], v[226:227], 0, s[14:15]
	global_load_lds_dwordx4 v[224:225], off
	s_mov_b32 m0, s48
	v_lshl_add_u64 v[224:225], s[68:69], 0, v[128:129]
	global_load_lds_dwordx4 v[224:225], off
	s_mov_b32 m0, s49
	s_nop 0
	global_load_lds_dwordx4 v[228:229], off
	s_setprio 1
	s_waitcnt vmcnt(8) lgkmcnt(0)
	s_barrier
	v_mfma_f32_16x16x32_bf16 v[60:63], v[144:147], v[184:187], v[60:63]
	v_mfma_f32_16x16x32_bf16 v[56:59], v[160:163], v[184:187], v[56:59]
	v_mfma_f32_16x16x32_bf16 v[44:47], v[144:147], v[192:195], v[44:47]
	v_mfma_f32_16x16x32_bf16 v[40:43], v[160:163], v[192:195], v[40:43]
	v_mfma_f32_16x16x32_bf16 v[28:31], v[144:147], v[200:203], v[28:31]
	v_mfma_f32_16x16x32_bf16 v[24:27], v[160:163], v[200:203], v[24:27]
	v_mfma_f32_16x16x32_bf16 v[12:15], v[144:147], v[208:211], v[12:15]
	v_mfma_f32_16x16x32_bf16 v[8:11], v[160:163], v[208:211], v[8:11]
	v_mfma_f32_16x16x32_bf16 v[60:63], v[156:159], v[188:191], v[60:63]
	v_mfma_f32_16x16x32_bf16 v[56:59], v[164:167], v[188:191], v[56:59]
	v_mfma_f32_16x16x32_bf16 v[44:47], v[156:159], v[196:199], v[44:47]
	v_mfma_f32_16x16x32_bf16 v[40:43], v[164:167], v[196:199], v[40:43]
	v_mfma_f32_16x16x32_bf16 v[28:31], v[156:159], v[204:207], v[28:31]
	v_mfma_f32_16x16x32_bf16 v[24:27], v[164:167], v[204:207], v[24:27]
	v_mfma_f32_16x16x32_bf16 v[12:15], v[156:159], v[212:215], v[12:15]
	v_mfma_f32_16x16x32_bf16 v[8:11], v[164:167], v[212:215], v[8:11]
	v_mfma_f32_16x16x32_bf16 v[52:55], v[168:171], v[184:187], v[52:55]
	v_mfma_f32_16x16x32_bf16 v[48:51], v[176:179], v[184:187], v[48:51]
	v_mfma_f32_16x16x32_bf16 v[36:39], v[168:171], v[192:195], v[36:39]
	v_mfma_f32_16x16x32_bf16 v[32:35], v[176:179], v[192:195], v[32:35]
	v_mfma_f32_16x16x32_bf16 v[20:23], v[168:171], v[200:203], v[20:23]
	v_mfma_f32_16x16x32_bf16 v[16:19], v[176:179], v[200:203], v[16:19]
	v_mfma_f32_16x16x32_bf16 v[4:7], v[168:171], v[208:211], v[4:7]
	v_mfma_f32_16x16x32_bf16 v[0:3], v[176:179], v[208:211], v[0:3]
	v_mfma_f32_16x16x32_bf16 v[52:55], v[172:175], v[188:191], v[52:55]
	v_mfma_f32_16x16x32_bf16 v[48:51], v[180:183], v[188:191], v[48:51]
	v_mfma_f32_16x16x32_bf16 v[36:39], v[172:175], v[196:199], v[36:39]
	v_mfma_f32_16x16x32_bf16 v[32:35], v[180:183], v[196:199], v[32:35]
	v_mfma_f32_16x16x32_bf16 v[20:23], v[172:175], v[204:207], v[20:23]
	v_mfma_f32_16x16x32_bf16 v[16:19], v[180:183], v[204:207], v[16:19]
	v_mfma_f32_16x16x32_bf16 v[4:7], v[172:175], v[212:215], v[4:7]
	v_mfma_f32_16x16x32_bf16 v[0:3], v[180:183], v[212:215], v[0:3]
	s_barrier
	s_setprio 0
	s_add_i32 s42, 0, 0x18000
	v_add_u32_e32 v155, s42, v149
	s_add_i32 s67, 0, 0x1c000
	ds_read_b128 v[144:147], v155
	ds_read_b128 v[156:159], v155 offset:1024
	ds_read_b128 v[160:163], v155 offset:2048
	ds_read_b128 v[164:167], v155 offset:3072
	v_add_u32_e32 v155, s67, v149
	ds_read_b128 v[168:171], v155
	ds_read_b128 v[172:175], v155 offset:1024
	ds_read_b128 v[176:179], v155 offset:2048
	ds_read_b128 v[180:183], v155 offset:3072
	s_mov_b32 m0, s50
	v_lshl_add_u64 v[228:229], v[224:225], 0, s[12:13]
	ds_read_b128 v[184:187], v153 offset:32768
	ds_read_b128 v[188:191], v153 offset:33792
	ds_read_b128 v[192:195], v153 offset:34816
	ds_read_b128 v[196:199], v153 offset:35840
	ds_read_b128 v[200:203], v153 offset:36864
	ds_read_b128 v[204:207], v153 offset:37888
	ds_read_b128 v[208:211], v153 offset:38912
	ds_read_b128 v[212:215], v153 offset:39936
	global_load_lds_dwordx4 v[228:229], off
	s_mov_b32 m0, s51
	v_lshl_add_u64 v[228:229], v[226:227], 0, s[16:17]
	global_load_lds_dwordx4 v[228:229], off
	s_setprio 1
	s_waitcnt vmcnt(8) lgkmcnt(0)
	s_barrier
	v_mfma_f32_16x16x32_bf16 v[124:127], v[144:147], v[184:187], v[124:127]
	v_mfma_f32_16x16x32_bf16 v[120:123], v[160:163], v[184:187], v[120:123]
	v_mfma_f32_16x16x32_bf16 v[108:111], v[144:147], v[192:195], v[108:111]
	v_mfma_f32_16x16x32_bf16 v[104:107], v[160:163], v[192:195], v[104:107]
	v_mfma_f32_16x16x32_bf16 v[92:95], v[144:147], v[200:203], v[92:95]
	v_mfma_f32_16x16x32_bf16 v[88:91], v[160:163], v[200:203], v[88:91]
	v_mfma_f32_16x16x32_bf16 v[76:79], v[144:147], v[208:211], v[76:79]
	v_mfma_f32_16x16x32_bf16 v[72:75], v[160:163], v[208:211], v[72:75]
	v_mfma_f32_16x16x32_bf16 v[124:127], v[156:159], v[188:191], v[124:127]
	v_mfma_f32_16x16x32_bf16 v[120:123], v[164:167], v[188:191], v[120:123]
	v_mfma_f32_16x16x32_bf16 v[108:111], v[156:159], v[196:199], v[108:111]
	v_mfma_f32_16x16x32_bf16 v[104:107], v[164:167], v[196:199], v[104:107]
	v_mfma_f32_16x16x32_bf16 v[92:95], v[156:159], v[204:207], v[92:95]
	v_mfma_f32_16x16x32_bf16 v[88:91], v[164:167], v[204:207], v[88:91]
	v_mfma_f32_16x16x32_bf16 v[76:79], v[156:159], v[212:215], v[76:79]
	v_mfma_f32_16x16x32_bf16 v[72:75], v[164:167], v[212:215], v[72:75]
	v_mfma_f32_16x16x32_bf16 v[116:119], v[168:171], v[184:187], v[116:119]
	v_mfma_f32_16x16x32_bf16 v[112:115], v[176:179], v[184:187], v[112:115]
	v_mfma_f32_16x16x32_bf16 v[100:103], v[168:171], v[192:195], v[100:103]
	v_mfma_f32_16x16x32_bf16 v[96:99], v[176:179], v[192:195], v[96:99]
	v_mfma_f32_16x16x32_bf16 v[84:87], v[168:171], v[200:203], v[84:87]
	v_mfma_f32_16x16x32_bf16 v[80:83], v[176:179], v[200:203], v[80:83]
	v_mfma_f32_16x16x32_bf16 v[68:71], v[168:171], v[208:211], v[68:71]
	v_mfma_f32_16x16x32_bf16 v[64:67], v[176:179], v[208:211], v[64:67]
	v_mfma_f32_16x16x32_bf16 v[116:119], v[172:175], v[188:191], v[116:119]
	v_mfma_f32_16x16x32_bf16 v[112:115], v[180:183], v[188:191], v[112:115]
	v_mfma_f32_16x16x32_bf16 v[100:103], v[172:175], v[196:199], v[100:103]
	v_mfma_f32_16x16x32_bf16 v[96:99], v[180:183], v[196:199], v[96:99]
	v_mfma_f32_16x16x32_bf16 v[84:87], v[172:175], v[204:207], v[84:87]
	v_mfma_f32_16x16x32_bf16 v[80:83], v[180:183], v[204:207], v[80:83]
	v_mfma_f32_16x16x32_bf16 v[68:71], v[172:175], v[212:215], v[68:71]
	v_mfma_f32_16x16x32_bf16 v[64:67], v[180:183], v[212:215], v[64:67]
	s_barrier
	ds_read_b128 v[184:187], v153 offset:49152
	ds_read_b128 v[188:191], v153 offset:50176
	ds_read_b128 v[192:195], v153 offset:51200
	ds_read_b128 v[196:199], v153 offset:52224
	ds_read_b128 v[200:203], v153 offset:53248
	ds_read_b128 v[204:207], v153 offset:54272
	ds_read_b128 v[208:211], v153 offset:55296
	ds_read_b128 v[212:215], v153 offset:56320
	s_setprio 0
	s_add_i32 s42, s42, s35
	s_mov_b32 m0, s42
	v_lshl_add_u64 v[216:217], v[216:217], 0, s[24:25]
	global_load_lds_dwordx4 v[216:217], off
	s_add_i32 m0, s42, 0x2000
	s_add_u32 s42, s46, 0xb0080
	v_lshl_add_u64 v[216:217], v[220:221], 0, s[24:25]
	s_addc_u32 s43, s47, 0
	s_add_i32 s46, s67, s35
	global_load_lds_dwordx4 v[216:217], off
	s_mov_b32 m0, s46
	v_lshl_add_u64 v[216:217], s[42:43], 0, v[130:131]
	global_load_lds_dwordx4 v[216:217], off
	s_add_i32 m0, s46, 0x2000
	v_lshl_add_u64 v[216:217], s[42:43], 0, v[134:135]
	global_load_lds_dwordx4 v[216:217], off
	s_mov_b32 m0, s53
	v_lshl_add_u64 v[216:217], v[224:225], 0, s[24:25]
	global_load_lds_dwordx4 v[216:217], off
	s_mov_b32 m0, s54
	v_lshl_add_u64 v[216:217], v[226:227], 0, s[36:37]
	global_load_lds_dwordx4 v[216:217], off
	s_setprio 1
	s_waitcnt vmcnt(8) lgkmcnt(0)
	s_barrier
	v_mfma_f32_16x16x32_bf16 v[60:63], v[144:147], v[184:187], v[60:63]
	v_mfma_f32_16x16x32_bf16 v[56:59], v[160:163], v[184:187], v[56:59]
	v_mfma_f32_16x16x32_bf16 v[44:47], v[144:147], v[192:195], v[44:47]
	v_mfma_f32_16x16x32_bf16 v[40:43], v[160:163], v[192:195], v[40:43]
	v_mfma_f32_16x16x32_bf16 v[28:31], v[144:147], v[200:203], v[28:31]
	v_mfma_f32_16x16x32_bf16 v[24:27], v[160:163], v[200:203], v[24:27]
	v_mfma_f32_16x16x32_bf16 v[12:15], v[144:147], v[208:211], v[12:15]
	v_mfma_f32_16x16x32_bf16 v[8:11], v[160:163], v[208:211], v[8:11]
	v_mfma_f32_16x16x32_bf16 v[60:63], v[156:159], v[188:191], v[60:63]
	v_mfma_f32_16x16x32_bf16 v[56:59], v[164:167], v[188:191], v[56:59]
	v_mfma_f32_16x16x32_bf16 v[44:47], v[156:159], v[196:199], v[44:47]
	v_mfma_f32_16x16x32_bf16 v[40:43], v[164:167], v[196:199], v[40:43]
	v_mfma_f32_16x16x32_bf16 v[28:31], v[156:159], v[204:207], v[28:31]
	v_mfma_f32_16x16x32_bf16 v[24:27], v[164:167], v[204:207], v[24:27]
	v_mfma_f32_16x16x32_bf16 v[12:15], v[156:159], v[212:215], v[12:15]
	v_mfma_f32_16x16x32_bf16 v[8:11], v[164:167], v[212:215], v[8:11]
	v_mfma_f32_16x16x32_bf16 v[52:55], v[168:171], v[184:187], v[52:55]
	v_mfma_f32_16x16x32_bf16 v[48:51], v[176:179], v[184:187], v[48:51]
	v_mfma_f32_16x16x32_bf16 v[36:39], v[168:171], v[192:195], v[36:39]
	v_mfma_f32_16x16x32_bf16 v[32:35], v[176:179], v[192:195], v[32:35]
	v_mfma_f32_16x16x32_bf16 v[20:23], v[168:171], v[200:203], v[20:23]
	v_mfma_f32_16x16x32_bf16 v[16:19], v[176:179], v[200:203], v[16:19]
	v_mfma_f32_16x16x32_bf16 v[4:7], v[168:171], v[208:211], v[4:7]
	v_mfma_f32_16x16x32_bf16 v[0:3], v[176:179], v[208:211], v[0:3]
	v_mfma_f32_16x16x32_bf16 v[52:55], v[172:175], v[188:191], v[52:55]
	v_mfma_f32_16x16x32_bf16 v[48:51], v[180:183], v[188:191], v[48:51]
	v_mfma_f32_16x16x32_bf16 v[36:39], v[172:175], v[196:199], v[36:39]
	v_mfma_f32_16x16x32_bf16 v[32:35], v[180:183], v[196:199], v[32:35]
	v_mfma_f32_16x16x32_bf16 v[20:23], v[172:175], v[204:207], v[20:23]
	v_mfma_f32_16x16x32_bf16 v[16:19], v[180:183], v[204:207], v[16:19]
	v_mfma_f32_16x16x32_bf16 v[4:7], v[172:175], v[212:215], v[4:7]
	v_mfma_f32_16x16x32_bf16 v[0:3], v[180:183], v[212:215], v[0:3]
	s_barrier
	s_setprio 0
	s_add_i32 s66, s66, 2
	s_add_u32 s64, s64, 0x100
	s_addc_u32 s65, s65, 0
	s_cmp_gt_u32 s66, 41
	s_mov_b64 s[42:43], s[44:45]
	s_cbranch_scc0 .LBB0_662

.LBB0_750:
	s_lshl_b32 s38, s65, 8
	s_ashr_i32 s39, s38, 31
	s_lshl_b64 s[38:39], s[38:39], 11
	s_add_u32 s38, s8, s38
	s_addc_u32 s39, s9, s39
	s_and_b64 s[40:41], s[4:5], exec
	s_cselect_b32 s43, s39, s45
	s_cselect_b32 s67, s38, s44
	s_ashr_i32 s37, s36, 31
	s_lshl_b64 s[40:41], s[36:37], 19
	s_add_u32 s40, s3, s40
	s_addc_u32 s41, s33, s41
	s_and_b64 s[48:49], s[4:5], exec
	s_cselect_b32 s37, s41, s47
	s_cselect_b32 s68, s40, s46
	s_add_u32 s69, s46, 0x100
	s_addc_u32 s71, s47, 0
	s_mov_b32 s72, -2
	s_waitcnt vmcnt(0)
	ds_read_b128 v[144:147], v189
	ds_read_b128 v[148:151], v189 offset:1024
	ds_read_b128 v[152:155], v189 offset:2048
	ds_read_b128 v[156:159], v189 offset:3072
	ds_read_b128 v[160:163], v190
	ds_read_b128 v[164:167], v190 offset:1024
	ds_read_b128 v[168:171], v190 offset:2048
	ds_read_b128 v[172:175], v190 offset:3072
	s_add_u32 s46, s44, 0x100
	s_addc_u32 s47, s45, 0
	s_cmp_eq_u32 s72, 12
	s_cselect_b32 s75, s43, s47
	s_cselect_b32 s74, s67, s46
	s_cselect_b32 s49, s37, s71
	s_cselect_b32 s48, s68, s69
	v_lshl_add_u64 v[184:185], s[44:45], 0, v[136:137]
	s_add_i32 m0, s51, 0xc000
	ds_read_b128 v[176:179], v191
	ds_read_b128 v[180:183], v191 offset:1024
	ds_read_b128 v[194:197], v191 offset:2048
	ds_read_b128 v[198:201], v191 offset:3072
	ds_read_b128 v[202:205], v191 offset:4096
	ds_read_b128 v[206:209], v191 offset:5120
	ds_read_b128 v[210:213], v191 offset:6144
	ds_read_b128 v[214:217], v191 offset:7168
	global_load_lds_dwordx4 v[184:185], off
	s_add_i32 m0, s51, 0xe000
	v_lshl_add_u64 v[184:185], s[44:45], 0, v[138:139]
	global_load_lds_dwordx4 v[184:185], off
	s_setprio 1
	s_waitcnt vmcnt(8) lgkmcnt(0)
	s_barrier
	v_mfma_f32_16x16x32_bf16 v[124:127], v[144:147], v[176:179], 0
	v_mfma_f32_16x16x32_bf16 v[120:123], v[152:155], v[176:179], 0
	v_mfma_f32_16x16x32_bf16 v[108:111], v[144:147], v[194:197], 0
	v_mfma_f32_16x16x32_bf16 v[104:107], v[152:155], v[194:197], 0
	v_mfma_f32_16x16x32_bf16 v[92:95], v[144:147], v[202:205], 0
	v_mfma_f32_16x16x32_bf16 v[88:91], v[152:155], v[202:205], 0
	v_mfma_f32_16x16x32_bf16 v[76:79], v[144:147], v[210:213], 0
	v_mfma_f32_16x16x32_bf16 v[72:75], v[152:155], v[210:213], 0
	v_mfma_f32_16x16x32_bf16 v[124:127], v[148:151], v[180:183], v[124:127]
	v_mfma_f32_16x16x32_bf16 v[120:123], v[156:159], v[180:183], v[120:123]
	v_mfma_f32_16x16x32_bf16 v[108:111], v[148:151], v[198:201], v[108:111]
	v_mfma_f32_16x16x32_bf16 v[104:107], v[156:159], v[198:201], v[104:107]
	v_mfma_f32_16x16x32_bf16 v[92:95], v[148:151], v[206:209], v[92:95]
	v_mfma_f32_16x16x32_bf16 v[88:91], v[156:159], v[206:209], v[88:91]
	v_mfma_f32_16x16x32_bf16 v[76:79], v[148:151], v[214:217], v[76:79]
	v_mfma_f32_16x16x32_bf16 v[72:75], v[156:159], v[214:217], v[72:75]
	v_mfma_f32_16x16x32_bf16 v[116:119], v[160:163], v[176:179], 0
	v_mfma_f32_16x16x32_bf16 v[112:115], v[168:171], v[176:179], 0
	v_mfma_f32_16x16x32_bf16 v[100:103], v[160:163], v[194:197], 0
	v_mfma_f32_16x16x32_bf16 v[96:99], v[168:171], v[194:197], 0
	v_mfma_f32_16x16x32_bf16 v[84:87], v[160:163], v[202:205], 0
	v_mfma_f32_16x16x32_bf16 v[80:83], v[168:171], v[202:205], 0
	v_mfma_f32_16x16x32_bf16 v[68:71], v[160:163], v[210:213], 0
	v_mfma_f32_16x16x32_bf16 v[64:67], v[168:171], v[210:213], 0
	v_mfma_f32_16x16x32_bf16 v[116:119], v[164:167], v[180:183], v[116:119]
	v_mfma_f32_16x16x32_bf16 v[112:115], v[172:175], v[180:183], v[112:115]
	v_mfma_f32_16x16x32_bf16 v[100:103], v[164:167], v[198:201], v[100:103]
	v_mfma_f32_16x16x32_bf16 v[96:99], v[172:175], v[198:201], v[96:99]
	v_mfma_f32_16x16x32_bf16 v[84:87], v[164:167], v[206:209], v[84:87]
	v_mfma_f32_16x16x32_bf16 v[80:83], v[172:175], v[206:209], v[80:83]
	v_mfma_f32_16x16x32_bf16 v[68:71], v[164:167], v[214:217], v[68:71]
	v_mfma_f32_16x16x32_bf16 v[64:67], v[172:175], v[214:217], v[64:67]
	s_barrier
	ds_read_b128 v[176:179], v191 offset:16384
	ds_read_b128 v[180:183], v191 offset:17408
	ds_read_b128 v[194:197], v191 offset:18432
	ds_read_b128 v[198:201], v191 offset:19456
	ds_read_b128 v[202:205], v191 offset:20480
	ds_read_b128 v[206:209], v191 offset:21504
	ds_read_b128 v[210:213], v191 offset:22528
	ds_read_b128 v[214:217], v191 offset:23552
	s_setprio 0
	s_add_i32 s44, s63, s50
	s_mov_b32 m0, s44
	v_lshl_add_u64 v[184:185], s[48:49], 0, v[130:131]
	global_load_lds_dwordx4 v[184:185], off
	s_add_i32 m0, s44, 0x2000
	s_add_u32 s44, s48, 0x40000
	v_lshl_add_u64 v[218:219], s[48:49], 0, v[134:135]
	s_addc_u32 s45, s49, 0
	s_add_i32 s70, s64, s50
	global_load_lds_dwordx4 v[218:219], off
	v_lshl_add_u64 v[220:221], s[44:45], 0, v[130:131]
	s_mov_b32 m0, s70
	v_lshl_add_u64 v[222:223], s[74:75], 0, v[132:133]
	global_load_lds_dwordx4 v[220:221], off
	v_lshl_add_u64 v[220:221], s[44:45], 0, v[134:135]
	s_add_i32 m0, s70, 0x2000
	v_lshl_add_u64 v[224:225], v[222:223], 0, s[12:13]
	global_load_lds_dwordx4 v[220:221], off
	s_mov_b32 m0, s51
	v_lshl_add_u64 v[220:221], s[74:75], 0, v[128:129]
	global_load_lds_dwordx4 v[220:221], off
	s_mov_b32 m0, s52
	s_nop 0
	global_load_lds_dwordx4 v[224:225], off
	s_setprio 1
	s_waitcnt vmcnt(8) lgkmcnt(0)
	s_barrier
	v_mfma_f32_16x16x32_bf16 v[60:63], v[144:147], v[176:179], 0
	v_mfma_f32_16x16x32_bf16 v[56:59], v[152:155], v[176:179], 0
	v_mfma_f32_16x16x32_bf16 v[44:47], v[144:147], v[194:197], 0
	v_mfma_f32_16x16x32_bf16 v[40:43], v[152:155], v[194:197], 0
	v_mfma_f32_16x16x32_bf16 v[28:31], v[144:147], v[202:205], 0
	v_mfma_f32_16x16x32_bf16 v[24:27], v[152:155], v[202:205], 0
	v_mfma_f32_16x16x32_bf16 v[12:15], v[144:147], v[210:213], 0
	v_mfma_f32_16x16x32_bf16 v[8:11], v[152:155], v[210:213], 0
	v_mfma_f32_16x16x32_bf16 v[60:63], v[148:151], v[180:183], v[60:63]
	v_mfma_f32_16x16x32_bf16 v[56:59], v[156:159], v[180:183], v[56:59]
	v_mfma_f32_16x16x32_bf16 v[44:47], v[148:151], v[198:201], v[44:47]
	v_mfma_f32_16x16x32_bf16 v[40:43], v[156:159], v[198:201], v[40:43]
	v_mfma_f32_16x16x32_bf16 v[28:31], v[148:151], v[206:209], v[28:31]
	v_mfma_f32_16x16x32_bf16 v[24:27], v[156:159], v[206:209], v[24:27]
	v_mfma_f32_16x16x32_bf16 v[12:15], v[148:151], v[214:217], v[12:15]
	v_mfma_f32_16x16x32_bf16 v[8:11], v[156:159], v[214:217], v[8:11]
	v_mfma_f32_16x16x32_bf16 v[52:55], v[160:163], v[176:179], 0
	v_mfma_f32_16x16x32_bf16 v[48:51], v[168:171], v[176:179], 0
	v_mfma_f32_16x16x32_bf16 v[36:39], v[160:163], v[194:197], 0
	v_mfma_f32_16x16x32_bf16 v[32:35], v[168:171], v[194:197], 0
	v_mfma_f32_16x16x32_bf16 v[20:23], v[160:163], v[202:205], 0
	v_mfma_f32_16x16x32_bf16 v[16:19], v[168:171], v[202:205], 0
	v_mfma_f32_16x16x32_bf16 v[4:7], v[160:163], v[210:213], 0
	v_mfma_f32_16x16x32_bf16 v[0:3], v[168:171], v[210:213], 0
	v_mfma_f32_16x16x32_bf16 v[52:55], v[164:167], v[180:183], v[52:55]
	v_mfma_f32_16x16x32_bf16 v[48:51], v[172:175], v[180:183], v[48:51]
	v_mfma_f32_16x16x32_bf16 v[36:39], v[164:167], v[198:201], v[36:39]
	v_mfma_f32_16x16x32_bf16 v[32:35], v[172:175], v[198:201], v[32:35]
	v_mfma_f32_16x16x32_bf16 v[20:23], v[164:167], v[206:209], v[20:23]
	v_mfma_f32_16x16x32_bf16 v[16:19], v[172:175], v[206:209], v[16:19]
	v_mfma_f32_16x16x32_bf16 v[4:7], v[164:167], v[214:217], v[4:7]
	v_mfma_f32_16x16x32_bf16 v[0:3], v[172:175], v[214:217], v[0:3]
	s_barrier
	s_setprio 0
	s_add_i32 s44, 0, 0x18000
	s_add_i32 s70, 0, 0x1c000
	v_add_u32_e32 v156, s44, v187
	v_add_u32_e32 v172, s70, v187
	ds_read_b128 v[144:147], v156
	ds_read_b128 v[148:151], v156 offset:1024
	ds_read_b128 v[152:155], v156 offset:2048
	ds_read_b128 v[156:159], v156 offset:3072
	ds_read_b128 v[160:163], v172
	ds_read_b128 v[164:167], v172 offset:1024
	ds_read_b128 v[168:171], v172 offset:2048
	ds_read_b128 v[172:175], v172 offset:3072
	s_mov_b32 m0, s53
	v_lshl_add_u64 v[224:225], v[220:221], 0, s[10:11]
	ds_read_b128 v[176:179], v191 offset:32768
	ds_read_b128 v[180:183], v191 offset:33792
	ds_read_b128 v[194:197], v191 offset:34816
	ds_read_b128 v[198:201], v191 offset:35840
	ds_read_b128 v[202:205], v191 offset:36864
	ds_read_b128 v[206:209], v191 offset:37888
	ds_read_b128 v[210:213], v191 offset:38912
	ds_read_b128 v[214:217], v191 offset:39936
	global_load_lds_dwordx4 v[224:225], off
	s_mov_b32 m0, s54
	v_lshl_add_u64 v[224:225], v[222:223], 0, s[14:15]
	global_load_lds_dwordx4 v[224:225], off
	s_setprio 1
	s_waitcnt vmcnt(8) lgkmcnt(0)
	s_barrier
	v_mfma_f32_16x16x32_bf16 v[124:127], v[144:147], v[176:179], v[124:127]
	v_mfma_f32_16x16x32_bf16 v[120:123], v[152:155], v[176:179], v[120:123]
	v_mfma_f32_16x16x32_bf16 v[108:111], v[144:147], v[194:197], v[108:111]
	v_mfma_f32_16x16x32_bf16 v[104:107], v[152:155], v[194:197], v[104:107]
	v_mfma_f32_16x16x32_bf16 v[92:95], v[144:147], v[202:205], v[92:95]
	v_mfma_f32_16x16x32_bf16 v[88:91], v[152:155], v[202:205], v[88:91]
	v_mfma_f32_16x16x32_bf16 v[76:79], v[144:147], v[210:213], v[76:79]
	v_mfma_f32_16x16x32_bf16 v[72:75], v[152:155], v[210:213], v[72:75]
	v_mfma_f32_16x16x32_bf16 v[124:127], v[148:151], v[180:183], v[124:127]
	v_mfma_f32_16x16x32_bf16 v[120:123], v[156:159], v[180:183], v[120:123]
	v_mfma_f32_16x16x32_bf16 v[108:111], v[148:151], v[198:201], v[108:111]
	v_mfma_f32_16x16x32_bf16 v[104:107], v[156:159], v[198:201], v[104:107]
	v_mfma_f32_16x16x32_bf16 v[92:95], v[148:151], v[206:209], v[92:95]
	v_mfma_f32_16x16x32_bf16 v[88:91], v[156:159], v[206:209], v[88:91]
	v_mfma_f32_16x16x32_bf16 v[76:79], v[148:151], v[214:217], v[76:79]
	v_mfma_f32_16x16x32_bf16 v[72:75], v[156:159], v[214:217], v[72:75]
	v_mfma_f32_16x16x32_bf16 v[116:119], v[160:163], v[176:179], v[116:119]
	v_mfma_f32_16x16x32_bf16 v[112:115], v[168:171], v[176:179], v[112:115]
	v_mfma_f32_16x16x32_bf16 v[100:103], v[160:163], v[194:197], v[100:103]
	v_mfma_f32_16x16x32_bf16 v[96:99], v[168:171], v[194:197], v[96:99]
	v_mfma_f32_16x16x32_bf16 v[84:87], v[160:163], v[202:205], v[84:87]
	v_mfma_f32_16x16x32_bf16 v[80:83], v[168:171], v[202:205], v[80:83]
	v_mfma_f32_16x16x32_bf16 v[68:71], v[160:163], v[210:213], v[68:71]
	v_mfma_f32_16x16x32_bf16 v[64:67], v[168:171], v[210:213], v[64:67]
	v_mfma_f32_16x16x32_bf16 v[116:119], v[164:167], v[180:183], v[116:119]
	v_mfma_f32_16x16x32_bf16 v[112:115], v[172:175], v[180:183], v[112:115]
	v_mfma_f32_16x16x32_bf16 v[100:103], v[164:167], v[198:201], v[100:103]
	v_mfma_f32_16x16x32_bf16 v[96:99], v[172:175], v[198:201], v[96:99]
	v_mfma_f32_16x16x32_bf16 v[84:87], v[164:167], v[206:209], v[84:87]
	v_mfma_f32_16x16x32_bf16 v[80:83], v[172:175], v[206:209], v[80:83]
	v_mfma_f32_16x16x32_bf16 v[68:71], v[164:167], v[214:217], v[68:71]
	v_mfma_f32_16x16x32_bf16 v[64:67], v[172:175], v[214:217], v[64:67]
	s_barrier
	ds_read_b128 v[176:179], v191 offset:49152
	ds_read_b128 v[180:183], v191 offset:50176
	ds_read_b128 v[194:197], v191 offset:51200
	ds_read_b128 v[198:201], v191 offset:52224
	ds_read_b128 v[202:205], v191 offset:53248
	ds_read_b128 v[206:209], v191 offset:54272
	ds_read_b128 v[210:213], v191 offset:55296
	ds_read_b128 v[214:217], v191 offset:56320
	s_setprio 0
	s_add_i32 s44, s44, s50
	s_mov_b32 m0, s44
	v_lshl_add_u64 v[184:185], v[184:185], 0, s[24:25]
	global_load_lds_dwordx4 v[184:185], off
	s_add_i32 m0, s44, 0x2000
	s_add_u32 s44, s48, 0x40080
	v_lshl_add_u64 v[184:185], v[218:219], 0, s[24:25]
	s_addc_u32 s45, s49, 0
	s_add_i32 s48, s70, s50
	global_load_lds_dwordx4 v[184:185], off
	s_mov_b32 m0, s48
	v_lshl_add_u64 v[184:185], s[44:45], 0, v[130:131]
	global_load_lds_dwordx4 v[184:185], off
	s_add_i32 m0, s48, 0x2000
	v_lshl_add_u64 v[184:185], s[44:45], 0, v[134:135]
	global_load_lds_dwordx4 v[184:185], off
	s_mov_b32 m0, s58
	v_lshl_add_u64 v[184:185], v[220:221], 0, s[24:25]
	global_load_lds_dwordx4 v[184:185], off
	s_mov_b32 m0, s59
	v_lshl_add_u64 v[184:185], v[222:223], 0, s[30:31]
	global_load_lds_dwordx4 v[184:185], off
	s_setprio 1
	s_waitcnt vmcnt(8) lgkmcnt(0)
	s_barrier
	v_mfma_f32_16x16x32_bf16 v[60:63], v[144:147], v[176:179], v[60:63]
	v_mfma_f32_16x16x32_bf16 v[56:59], v[152:155], v[176:179], v[56:59]
	v_mfma_f32_16x16x32_bf16 v[44:47], v[144:147], v[194:197], v[44:47]
	v_mfma_f32_16x16x32_bf16 v[40:43], v[152:155], v[194:197], v[40:43]
	v_mfma_f32_16x16x32_bf16 v[28:31], v[144:147], v[202:205], v[28:31]
	v_mfma_f32_16x16x32_bf16 v[24:27], v[152:155], v[202:205], v[24:27]
	v_mfma_f32_16x16x32_bf16 v[12:15], v[144:147], v[210:213], v[12:15]
	v_mfma_f32_16x16x32_bf16 v[8:11], v[152:155], v[210:213], v[8:11]
	v_mfma_f32_16x16x32_bf16 v[60:63], v[148:151], v[180:183], v[60:63]
	v_mfma_f32_16x16x32_bf16 v[56:59], v[156:159], v[180:183], v[56:59]
	v_mfma_f32_16x16x32_bf16 v[44:47], v[148:151], v[198:201], v[44:47]
	v_mfma_f32_16x16x32_bf16 v[40:43], v[156:159], v[198:201], v[40:43]
	v_mfma_f32_16x16x32_bf16 v[28:31], v[148:151], v[206:209], v[28:31]
	v_mfma_f32_16x16x32_bf16 v[24:27], v[156:159], v[206:209], v[24:27]
	v_mfma_f32_16x16x32_bf16 v[12:15], v[148:151], v[214:217], v[12:15]
	v_mfma_f32_16x16x32_bf16 v[8:11], v[156:159], v[214:217], v[8:11]
	v_mfma_f32_16x16x32_bf16 v[52:55], v[160:163], v[176:179], v[52:55]
	v_mfma_f32_16x16x32_bf16 v[48:51], v[168:171], v[176:179], v[48:51]
	v_mfma_f32_16x16x32_bf16 v[36:39], v[160:163], v[194:197], v[36:39]
	v_mfma_f32_16x16x32_bf16 v[32:35], v[168:171], v[194:197], v[32:35]
	v_mfma_f32_16x16x32_bf16 v[20:23], v[160:163], v[202:205], v[20:23]
	v_mfma_f32_16x16x32_bf16 v[16:19], v[168:171], v[202:205], v[16:19]
	v_mfma_f32_16x16x32_bf16 v[4:7], v[160:163], v[210:213], v[4:7]
	v_mfma_f32_16x16x32_bf16 v[0:3], v[168:171], v[210:213], v[0:3]
	v_mfma_f32_16x16x32_bf16 v[52:55], v[164:167], v[180:183], v[52:55]
	v_mfma_f32_16x16x32_bf16 v[48:51], v[172:175], v[180:183], v[48:51]
	v_mfma_f32_16x16x32_bf16 v[36:39], v[164:167], v[198:201], v[36:39]
	v_mfma_f32_16x16x32_bf16 v[32:35], v[172:175], v[198:201], v[32:35]
	v_mfma_f32_16x16x32_bf16 v[20:23], v[164:167], v[206:209], v[20:23]
	v_mfma_f32_16x16x32_bf16 v[16:19], v[172:175], v[206:209], v[16:19]
	v_mfma_f32_16x16x32_bf16 v[4:7], v[164:167], v[214:217], v[4:7]
	v_mfma_f32_16x16x32_bf16 v[0:3], v[172:175], v[214:217], v[0:3]
	s_barrier
	s_setprio 0
	s_add_i32 s72, s72, 2
	s_add_u32 s69, s69, 0x100
	s_addc_u32 s71, s71, 0
	s_cmp_gt_u32 s72, 13
	s_mov_b64 s[44:45], s[46:47]
.LBB0_751:
	ds_read_b128 v[144:147], v189
	ds_read_b128 v[148:151], v189 offset:1024
	ds_read_b128 v[152:155], v189 offset:2048
	ds_read_b128 v[156:159], v189 offset:3072
	ds_read_b128 v[160:163], v190
	ds_read_b128 v[164:167], v190 offset:1024
	ds_read_b128 v[168:171], v190 offset:2048
	ds_read_b128 v[172:175], v190 offset:3072
	s_add_u32 s46, s44, 0x100
	s_addc_u32 s47, s45, 0
	s_cmp_eq_u32 s72, 12
	s_cselect_b32 s75, s43, s47
	s_cselect_b32 s74, s67, s46
	s_cselect_b32 s49, s37, s71
	s_cselect_b32 s48, s68, s69
	v_lshl_add_u64 v[184:185], s[44:45], 0, v[136:137]
	s_add_i32 m0, s51, 0xc000
	ds_read_b128 v[176:179], v191
	ds_read_b128 v[180:183], v191 offset:1024
	ds_read_b128 v[194:197], v191 offset:2048
	ds_read_b128 v[198:201], v191 offset:3072
	ds_read_b128 v[202:205], v191 offset:4096
	ds_read_b128 v[206:209], v191 offset:5120
	ds_read_b128 v[210:213], v191 offset:6144
	ds_read_b128 v[214:217], v191 offset:7168
	global_load_lds_dwordx4 v[184:185], off
	s_add_i32 m0, s51, 0xe000
	v_lshl_add_u64 v[184:185], s[44:45], 0, v[138:139]
	global_load_lds_dwordx4 v[184:185], off
	s_setprio 1
	s_waitcnt vmcnt(8) lgkmcnt(0)
	s_barrier
	v_mfma_f32_16x16x32_bf16 v[124:127], v[144:147], v[176:179], v[124:127]
	v_mfma_f32_16x16x32_bf16 v[120:123], v[152:155], v[176:179], v[120:123]
	v_mfma_f32_16x16x32_bf16 v[108:111], v[144:147], v[194:197], v[108:111]
	v_mfma_f32_16x16x32_bf16 v[104:107], v[152:155], v[194:197], v[104:107]
	v_mfma_f32_16x16x32_bf16 v[92:95], v[144:147], v[202:205], v[92:95]
	v_mfma_f32_16x16x32_bf16 v[88:91], v[152:155], v[202:205], v[88:91]
	v_mfma_f32_16x16x32_bf16 v[76:79], v[144:147], v[210:213], v[76:79]
	v_mfma_f32_16x16x32_bf16 v[72:75], v[152:155], v[210:213], v[72:75]
	v_mfma_f32_16x16x32_bf16 v[124:127], v[148:151], v[180:183], v[124:127]
	v_mfma_f32_16x16x32_bf16 v[120:123], v[156:159], v[180:183], v[120:123]
	v_mfma_f32_16x16x32_bf16 v[108:111], v[148:151], v[198:201], v[108:111]
	v_mfma_f32_16x16x32_bf16 v[104:107], v[156:159], v[198:201], v[104:107]
	v_mfma_f32_16x16x32_bf16 v[92:95], v[148:151], v[206:209], v[92:95]
	v_mfma_f32_16x16x32_bf16 v[88:91], v[156:159], v[206:209], v[88:91]
	v_mfma_f32_16x16x32_bf16 v[76:79], v[148:151], v[214:217], v[76:79]
	v_mfma_f32_16x16x32_bf16 v[72:75], v[156:159], v[214:217], v[72:75]
	v_mfma_f32_16x16x32_bf16 v[116:119], v[160:163], v[176:179], v[116:119]
	v_mfma_f32_16x16x32_bf16 v[112:115], v[168:171], v[176:179], v[112:115]
	v_mfma_f32_16x16x32_bf16 v[100:103], v[160:163], v[194:197], v[100:103]
	v_mfma_f32_16x16x32_bf16 v[96:99], v[168:171], v[194:197], v[96:99]
	v_mfma_f32_16x16x32_bf16 v[84:87], v[160:163], v[202:205], v[84:87]
	v_mfma_f32_16x16x32_bf16 v[80:83], v[168:171], v[202:205], v[80:83]
	v_mfma_f32_16x16x32_bf16 v[68:71], v[160:163], v[210:213], v[68:71]
	v_mfma_f32_16x16x32_bf16 v[64:67], v[168:171], v[210:213], v[64:67]
	v_mfma_f32_16x16x32_bf16 v[116:119], v[164:167], v[180:183], v[116:119]
	v_mfma_f32_16x16x32_bf16 v[112:115], v[172:175], v[180:183], v[112:115]
	v_mfma_f32_16x16x32_bf16 v[100:103], v[164:167], v[198:201], v[100:103]
	v_mfma_f32_16x16x32_bf16 v[96:99], v[172:175], v[198:201], v[96:99]
	v_mfma_f32_16x16x32_bf16 v[84:87], v[164:167], v[206:209], v[84:87]
	v_mfma_f32_16x16x32_bf16 v[80:83], v[172:175], v[206:209], v[80:83]
	v_mfma_f32_16x16x32_bf16 v[68:71], v[164:167], v[214:217], v[68:71]
	v_mfma_f32_16x16x32_bf16 v[64:67], v[172:175], v[214:217], v[64:67]
	s_barrier
	ds_read_b128 v[176:179], v191 offset:16384
	ds_read_b128 v[180:183], v191 offset:17408
	ds_read_b128 v[194:197], v191 offset:18432
	ds_read_b128 v[198:201], v191 offset:19456
	ds_read_b128 v[202:205], v191 offset:20480
	ds_read_b128 v[206:209], v191 offset:21504
	ds_read_b128 v[210:213], v191 offset:22528
	ds_read_b128 v[214:217], v191 offset:23552
	s_setprio 0
	s_add_i32 s44, s63, s50
	s_mov_b32 m0, s44
	v_lshl_add_u64 v[184:185], s[48:49], 0, v[130:131]
	global_load_lds_dwordx4 v[184:185], off
	s_add_i32 m0, s44, 0x2000
	s_add_u32 s44, s48, 0x40000
	v_lshl_add_u64 v[218:219], s[48:49], 0, v[134:135]
	s_addc_u32 s45, s49, 0
	s_add_i32 s70, s64, s50
	global_load_lds_dwordx4 v[218:219], off
	v_lshl_add_u64 v[220:221], s[44:45], 0, v[130:131]
	s_mov_b32 m0, s70
	v_lshl_add_u64 v[222:223], s[74:75], 0, v[132:133]
	global_load_lds_dwordx4 v[220:221], off
	v_lshl_add_u64 v[220:221], s[44:45], 0, v[134:135]
	s_add_i32 m0, s70, 0x2000
	v_lshl_add_u64 v[224:225], v[222:223], 0, s[12:13]
	global_load_lds_dwordx4 v[220:221], off
	s_mov_b32 m0, s51
	v_lshl_add_u64 v[220:221], s[74:75], 0, v[128:129]
	global_load_lds_dwordx4 v[220:221], off
	s_mov_b32 m0, s52
	s_nop 0
	global_load_lds_dwordx4 v[224:225], off
	s_setprio 1
	s_waitcnt vmcnt(8) lgkmcnt(0)
	s_barrier
	v_mfma_f32_16x16x32_bf16 v[60:63], v[144:147], v[176:179], v[60:63]
	v_mfma_f32_16x16x32_bf16 v[56:59], v[152:155], v[176:179], v[56:59]
	v_mfma_f32_16x16x32_bf16 v[44:47], v[144:147], v[194:197], v[44:47]
	v_mfma_f32_16x16x32_bf16 v[40:43], v[152:155], v[194:197], v[40:43]
	v_mfma_f32_16x16x32_bf16 v[28:31], v[144:147], v[202:205], v[28:31]
	v_mfma_f32_16x16x32_bf16 v[24:27], v[152:155], v[202:205], v[24:27]
	v_mfma_f32_16x16x32_bf16 v[12:15], v[144:147], v[210:213], v[12:15]
	v_mfma_f32_16x16x32_bf16 v[8:11], v[152:155], v[210:213], v[8:11]
	v_mfma_f32_16x16x32_bf16 v[60:63], v[148:151], v[180:183], v[60:63]
	v_mfma_f32_16x16x32_bf16 v[56:59], v[156:159], v[180:183], v[56:59]
	v_mfma_f32_16x16x32_bf16 v[44:47], v[148:151], v[198:201], v[44:47]
	v_mfma_f32_16x16x32_bf16 v[40:43], v[156:159], v[198:201], v[40:43]
	v_mfma_f32_16x16x32_bf16 v[28:31], v[148:151], v[206:209], v[28:31]
	v_mfma_f32_16x16x32_bf16 v[24:27], v[156:159], v[206:209], v[24:27]
	v_mfma_f32_16x16x32_bf16 v[12:15], v[148:151], v[214:217], v[12:15]
	v_mfma_f32_16x16x32_bf16 v[8:11], v[156:159], v[214:217], v[8:11]
	v_mfma_f32_16x16x32_bf16 v[52:55], v[160:163], v[176:179], v[52:55]
	v_mfma_f32_16x16x32_bf16 v[48:51], v[168:171], v[176:179], v[48:51]
	v_mfma_f32_16x16x32_bf16 v[36:39], v[160:163], v[194:197], v[36:39]
	v_mfma_f32_16x16x32_bf16 v[32:35], v[168:171], v[194:197], v[32:35]
	v_mfma_f32_16x16x32_bf16 v[20:23], v[160:163], v[202:205], v[20:23]
	v_mfma_f32_16x16x32_bf16 v[16:19], v[168:171], v[202:205], v[16:19]
	v_mfma_f32_16x16x32_bf16 v[4:7], v[160:163], v[210:213], v[4:7]
	v_mfma_f32_16x16x32_bf16 v[0:3], v[168:171], v[210:213], v[0:3]
	v_mfma_f32_16x16x32_bf16 v[52:55], v[164:167], v[180:183], v[52:55]
	v_mfma_f32_16x16x32_bf16 v[48:51], v[172:175], v[180:183], v[48:51]
	v_mfma_f32_16x16x32_bf16 v[36:39], v[164:167], v[198:201], v[36:39]
	v_mfma_f32_16x16x32_bf16 v[32:35], v[172:175], v[198:201], v[32:35]
	v_mfma_f32_16x16x32_bf16 v[20:23], v[164:167], v[206:209], v[20:23]
	v_mfma_f32_16x16x32_bf16 v[16:19], v[172:175], v[206:209], v[16:19]
	v_mfma_f32_16x16x32_bf16 v[4:7], v[164:167], v[214:217], v[4:7]
	v_mfma_f32_16x16x32_bf16 v[0:3], v[172:175], v[214:217], v[0:3]
	s_barrier
	s_setprio 0
	s_add_i32 s44, 0, 0x18000
	s_add_i32 s70, 0, 0x1c000
	v_add_u32_e32 v156, s44, v187
	v_add_u32_e32 v172, s70, v187
	ds_read_b128 v[144:147], v156
	ds_read_b128 v[148:151], v156 offset:1024
	ds_read_b128 v[152:155], v156 offset:2048
	ds_read_b128 v[156:159], v156 offset:3072
	ds_read_b128 v[160:163], v172
	ds_read_b128 v[164:167], v172 offset:1024
	ds_read_b128 v[168:171], v172 offset:2048
	ds_read_b128 v[172:175], v172 offset:3072
	s_mov_b32 m0, s53
	v_lshl_add_u64 v[224:225], v[220:221], 0, s[10:11]
	ds_read_b128 v[176:179], v191 offset:32768
	ds_read_b128 v[180:183], v191 offset:33792
	ds_read_b128 v[194:197], v191 offset:34816
	ds_read_b128 v[198:201], v191 offset:35840
	ds_read_b128 v[202:205], v191 offset:36864
	ds_read_b128 v[206:209], v191 offset:37888
	ds_read_b128 v[210:213], v191 offset:38912
	ds_read_b128 v[214:217], v191 offset:39936
	global_load_lds_dwordx4 v[224:225], off
	s_mov_b32 m0, s54
	v_lshl_add_u64 v[224:225], v[222:223], 0, s[14:15]
	global_load_lds_dwordx4 v[224:225], off
	s_setprio 1
	s_waitcnt vmcnt(8) lgkmcnt(0)
	s_barrier
	v_mfma_f32_16x16x32_bf16 v[124:127], v[144:147], v[176:179], v[124:127]
	v_mfma_f32_16x16x32_bf16 v[120:123], v[152:155], v[176:179], v[120:123]
	v_mfma_f32_16x16x32_bf16 v[108:111], v[144:147], v[194:197], v[108:111]
	v_mfma_f32_16x16x32_bf16 v[104:107], v[152:155], v[194:197], v[104:107]
	v_mfma_f32_16x16x32_bf16 v[92:95], v[144:147], v[202:205], v[92:95]
	v_mfma_f32_16x16x32_bf16 v[88:91], v[152:155], v[202:205], v[88:91]
	v_mfma_f32_16x16x32_bf16 v[76:79], v[144:147], v[210:213], v[76:79]
	v_mfma_f32_16x16x32_bf16 v[72:75], v[152:155], v[210:213], v[72:75]
	v_mfma_f32_16x16x32_bf16 v[124:127], v[148:151], v[180:183], v[124:127]
	v_mfma_f32_16x16x32_bf16 v[120:123], v[156:159], v[180:183], v[120:123]
	v_mfma_f32_16x16x32_bf16 v[108:111], v[148:151], v[198:201], v[108:111]
	v_mfma_f32_16x16x32_bf16 v[104:107], v[156:159], v[198:201], v[104:107]
	v_mfma_f32_16x16x32_bf16 v[92:95], v[148:151], v[206:209], v[92:95]
	v_mfma_f32_16x16x32_bf16 v[88:91], v[156:159], v[206:209], v[88:91]
	v_mfma_f32_16x16x32_bf16 v[76:79], v[148:151], v[214:217], v[76:79]
	v_mfma_f32_16x16x32_bf16 v[72:75], v[156:159], v[214:217], v[72:75]
	v_mfma_f32_16x16x32_bf16 v[116:119], v[160:163], v[176:179], v[116:119]
	v_mfma_f32_16x16x32_bf16 v[112:115], v[168:171], v[176:179], v[112:115]
	v_mfma_f32_16x16x32_bf16 v[100:103], v[160:163], v[194:197], v[100:103]
	v_mfma_f32_16x16x32_bf16 v[96:99], v[168:171], v[194:197], v[96:99]
	v_mfma_f32_16x16x32_bf16 v[84:87], v[160:163], v[202:205], v[84:87]
	v_mfma_f32_16x16x32_bf16 v[80:83], v[168:171], v[202:205], v[80:83]
	v_mfma_f32_16x16x32_bf16 v[68:71], v[160:163], v[210:213], v[68:71]
	v_mfma_f32_16x16x32_bf16 v[64:67], v[168:171], v[210:213], v[64:67]
	v_mfma_f32_16x16x32_bf16 v[116:119], v[164:167], v[180:183], v[116:119]
	v_mfma_f32_16x16x32_bf16 v[112:115], v[172:175], v[180:183], v[112:115]
	v_mfma_f32_16x16x32_bf16 v[100:103], v[164:167], v[198:201], v[100:103]
	v_mfma_f32_16x16x32_bf16 v[96:99], v[172:175], v[198:201], v[96:99]
	v_mfma_f32_16x16x32_bf16 v[84:87], v[164:167], v[206:209], v[84:87]
	v_mfma_f32_16x16x32_bf16 v[80:83], v[172:175], v[206:209], v[80:83]
	v_mfma_f32_16x16x32_bf16 v[68:71], v[164:167], v[214:217], v[68:71]
	v_mfma_f32_16x16x32_bf16 v[64:67], v[172:175], v[214:217], v[64:67]
	s_barrier
	ds_read_b128 v[176:179], v191 offset:49152
	ds_read_b128 v[180:183], v191 offset:50176
	ds_read_b128 v[194:197], v191 offset:51200
	ds_read_b128 v[198:201], v191 offset:52224
	ds_read_b128 v[202:205], v191 offset:53248
	ds_read_b128 v[206:209], v191 offset:54272
	ds_read_b128 v[210:213], v191 offset:55296
	ds_read_b128 v[214:217], v191 offset:56320
	s_setprio 0
	s_add_i32 s44, s44, s50
	s_mov_b32 m0, s44
	v_lshl_add_u64 v[184:185], v[184:185], 0, s[24:25]
	global_load_lds_dwordx4 v[184:185], off
	s_add_i32 m0, s44, 0x2000
	s_add_u32 s44, s48, 0x40080
	v_lshl_add_u64 v[184:185], v[218:219], 0, s[24:25]
	s_addc_u32 s45, s49, 0
	s_add_i32 s48, s70, s50
	global_load_lds_dwordx4 v[184:185], off
	s_mov_b32 m0, s48
	v_lshl_add_u64 v[184:185], s[44:45], 0, v[130:131]
	global_load_lds_dwordx4 v[184:185], off
	s_add_i32 m0, s48, 0x2000
	v_lshl_add_u64 v[184:185], s[44:45], 0, v[134:135]
	global_load_lds_dwordx4 v[184:185], off
	s_mov_b32 m0, s58
	v_lshl_add_u64 v[184:185], v[220:221], 0, s[24:25]
	global_load_lds_dwordx4 v[184:185], off
	s_mov_b32 m0, s59
	v_lshl_add_u64 v[184:185], v[222:223], 0, s[30:31]
	global_load_lds_dwordx4 v[184:185], off
	s_setprio 1
	s_waitcnt vmcnt(8) lgkmcnt(0)
	s_barrier
	v_mfma_f32_16x16x32_bf16 v[60:63], v[144:147], v[176:179], v[60:63]
	v_mfma_f32_16x16x32_bf16 v[56:59], v[152:155], v[176:179], v[56:59]
	v_mfma_f32_16x16x32_bf16 v[44:47], v[144:147], v[194:197], v[44:47]
	v_mfma_f32_16x16x32_bf16 v[40:43], v[152:155], v[194:197], v[40:43]
	v_mfma_f32_16x16x32_bf16 v[28:31], v[144:147], v[202:205], v[28:31]
	v_mfma_f32_16x16x32_bf16 v[24:27], v[152:155], v[202:205], v[24:27]
	v_mfma_f32_16x16x32_bf16 v[12:15], v[144:147], v[210:213], v[12:15]
	v_mfma_f32_16x16x32_bf16 v[8:11], v[152:155], v[210:213], v[8:11]
	v_mfma_f32_16x16x32_bf16 v[60:63], v[148:151], v[180:183], v[60:63]
	v_mfma_f32_16x16x32_bf16 v[56:59], v[156:159], v[180:183], v[56:59]
	v_mfma_f32_16x16x32_bf16 v[44:47], v[148:151], v[198:201], v[44:47]
	v_mfma_f32_16x16x32_bf16 v[40:43], v[156:159], v[198:201], v[40:43]
	v_mfma_f32_16x16x32_bf16 v[28:31], v[148:151], v[206:209], v[28:31]
	v_mfma_f32_16x16x32_bf16 v[24:27], v[156:159], v[206:209], v[24:27]
	v_mfma_f32_16x16x32_bf16 v[12:15], v[148:151], v[214:217], v[12:15]
	v_mfma_f32_16x16x32_bf16 v[8:11], v[156:159], v[214:217], v[8:11]
	v_mfma_f32_16x16x32_bf16 v[52:55], v[160:163], v[176:179], v[52:55]
	v_mfma_f32_16x16x32_bf16 v[48:51], v[168:171], v[176:179], v[48:51]
	v_mfma_f32_16x16x32_bf16 v[36:39], v[160:163], v[194:197], v[36:39]
	v_mfma_f32_16x16x32_bf16 v[32:35], v[168:171], v[194:197], v[32:35]
	v_mfma_f32_16x16x32_bf16 v[20:23], v[160:163], v[202:205], v[20:23]
	v_mfma_f32_16x16x32_bf16 v[16:19], v[168:171], v[202:205], v[16:19]
	v_mfma_f32_16x16x32_bf16 v[4:7], v[160:163], v[210:213], v[4:7]
	v_mfma_f32_16x16x32_bf16 v[0:3], v[168:171], v[210:213], v[0:3]
	v_mfma_f32_16x16x32_bf16 v[52:55], v[164:167], v[180:183], v[52:55]
	v_mfma_f32_16x16x32_bf16 v[48:51], v[172:175], v[180:183], v[48:51]
	v_mfma_f32_16x16x32_bf16 v[36:39], v[164:167], v[198:201], v[36:39]
	v_mfma_f32_16x16x32_bf16 v[32:35], v[172:175], v[198:201], v[32:35]
	v_mfma_f32_16x16x32_bf16 v[20:23], v[164:167], v[206:209], v[20:23]
	v_mfma_f32_16x16x32_bf16 v[16:19], v[172:175], v[206:209], v[16:19]
	v_mfma_f32_16x16x32_bf16 v[4:7], v[164:167], v[214:217], v[4:7]
	v_mfma_f32_16x16x32_bf16 v[0:3], v[172:175], v[214:217], v[0:3]
	s_barrier
	s_setprio 0
	s_add_i32 s72, s72, 2
	s_add_u32 s69, s69, 0x100
	s_addc_u32 s71, s71, 0
	s_cmp_gt_u32 s72, 13
	s_mov_b64 s[44:45], s[46:47]
	s_cbranch_scc0 .LBB0_751
	s_and_b64 vcc, exec, s[34:35]
	s_cbranch_vccz .LBB0_754
	s_barrier
